# RWKV scan: specialised unit-2 path (v = 0: no kd*v term, no kd / v LDS reads)
# speedup vs baseline: 1.0406x; 1.0133x over previous
.Lrw0_noout:
	ds_read_b128 v[30:33], v93 offset:46080
	ds_read_b128 v[34:37], v93 offset:46096
	ds_read_b128 v[38:41], v93 offset:46112
	ds_read_b128 v[42:45], v93 offset:46128
	ds_read_b64 v[70:71], v1 offset:27008
	ds_read_b64 v[72:73], v1 offset:26624
	ds_read_b64 v[74:75], v1 offset:27392
	ds_read_b64 v[76:77], v1 offset:27136
	ds_read_b64 v[78:79], v1 offset:26752
	ds_read_b64 v[80:81], v1 offset:27520
	ds_read_b64 v[82:83], v1 offset:27264
	ds_read_b64 v[84:85], v1 offset:26880
	ds_read_b64 v[96:97], v1 offset:27648
	ds_read_b64 v[128:129], v2 offset:33536
	ds_read_b64 v[130:131], v2 offset:33664
	v_add_u32_e32 v87, s28, v127
	v_cmp_ne_u32_e32 vcc, 0, v87
	s_nop 1
	v_cndmask_b32_e64 v98, 0, 0.5, vcc
	v_cmp_ne_u32_e32 vcc, s29, v87
	s_nop 1
	v_cndmask_b32_e64 v100, 0, 0.5, vcc
	s_waitcnt lgkmcnt(8)
	v_lshlrev_b32_e32 v132, 16, v70
	v_and_b32_e32 v133, 0xffff0000, v70
	v_lshlrev_b32_e32 v134, 16, v71
	v_and_b32_e32 v135, 0xffff0000, v71
	v_lshlrev_b32_e32 v136, 16, v72
	v_and_b32_e32 v137, 0xffff0000, v72
	v_lshlrev_b32_e32 v138, 16, v73
	v_and_b32_e32 v139, 0xffff0000, v73
	v_lshlrev_b32_e32 v140, 16, v74
	v_and_b32_e32 v141, 0xffff0000, v74
	v_lshlrev_b32_e32 v142, 16, v75
	v_and_b32_e32 v143, 0xffff0000, v75
	v_pk_mul_f32 v[136:137], v[136:137], v[98:99] op_sel_hi:[1,0]
	v_pk_fma_f32 v[136:137], v[140:141], v[100:101], v[136:137] op_sel_hi:[1,0,1]
	v_pk_add_f32 v[136:137], v[136:137], v[132:133] neg_lo:[0,1] neg_hi:[0,1]
	v_pk_fma_f32 v[144:145], v[30:31], v[136:137], v[132:133]
	v_pk_mul_f32 v[138:139], v[138:139], v[98:99] op_sel_hi:[1,0]
	v_pk_fma_f32 v[138:139], v[142:143], v[100:101], v[138:139] op_sel_hi:[1,0,1]
	v_pk_add_f32 v[138:139], v[138:139], v[134:135] neg_lo:[0,1] neg_hi:[0,1]
	v_pk_fma_f32 v[146:147], v[32:33], v[138:139], v[134:135]
	ds_read_b128 v[30:33], v93 offset:46144
	s_waitcnt lgkmcnt(6)
	v_lshlrev_b32_e32 v132, 16, v76
	v_and_b32_e32 v133, 0xffff0000, v76
	v_lshlrev_b32_e32 v134, 16, v77
	v_and_b32_e32 v135, 0xffff0000, v77
	v_lshlrev_b32_e32 v136, 16, v78
	v_and_b32_e32 v137, 0xffff0000, v78
	v_lshlrev_b32_e32 v138, 16, v79
	v_and_b32_e32 v139, 0xffff0000, v79
	v_lshlrev_b32_e32 v140, 16, v80
	v_and_b32_e32 v141, 0xffff0000, v80
	v_lshlrev_b32_e32 v142, 16, v81
	v_and_b32_e32 v143, 0xffff0000, v81
	v_pk_mul_f32 v[136:137], v[136:137], v[98:99] op_sel_hi:[1,0]
	v_pk_fma_f32 v[136:137], v[140:141], v[100:101], v[136:137] op_sel_hi:[1,0,1]
	v_pk_add_f32 v[136:137], v[136:137], v[132:133] neg_lo:[0,1] neg_hi:[0,1]
	v_pk_fma_f32 v[102:103], v[34:35], v[136:137], v[132:133]
	v_pk_mul_f32 v[138:139], v[138:139], v[98:99] op_sel_hi:[1,0]
	v_pk_fma_f32 v[138:139], v[142:143], v[100:101], v[138:139] op_sel_hi:[1,0,1]
	v_pk_add_f32 v[138:139], v[138:139], v[134:135] neg_lo:[0,1] neg_hi:[0,1]
	v_pk_fma_f32 v[104:105], v[36:37], v[138:139], v[134:135]
	s_waitcnt lgkmcnt(3)
	v_lshlrev_b32_e32 v132, 16, v82
	v_and_b32_e32 v133, 0xffff0000, v82
	v_lshlrev_b32_e32 v134, 16, v83
	v_and_b32_e32 v135, 0xffff0000, v83
	v_lshlrev_b32_e32 v136, 16, v84
	v_and_b32_e32 v137, 0xffff0000, v84
	v_lshlrev_b32_e32 v138, 16, v85
	v_and_b32_e32 v139, 0xffff0000, v85
	v_lshlrev_b32_e32 v140, 16, v96
	v_and_b32_e32 v141, 0xffff0000, v96
	v_lshlrev_b32_e32 v142, 16, v97
	v_and_b32_e32 v143, 0xffff0000, v97
	v_pk_mul_f32 v[136:137], v[136:137], v[98:99] op_sel_hi:[1,0]
	v_pk_fma_f32 v[136:137], v[140:141], v[100:101], v[136:137] op_sel_hi:[1,0,1]
	v_pk_add_f32 v[136:137], v[136:137], v[132:133] neg_lo:[0,1] neg_hi:[0,1]
	v_pk_fma_f32 v[148:149], v[38:39], v[136:137], v[132:133]
	v_pk_mul_f32 v[138:139], v[138:139], v[98:99] op_sel_hi:[1,0]
	v_pk_fma_f32 v[138:139], v[142:143], v[100:101], v[138:139] op_sel_hi:[1,0,1]
	v_pk_add_f32 v[138:139], v[138:139], v[134:135] neg_lo:[0,1] neg_hi:[0,1]
	v_pk_fma_f32 v[150:151], v[40:41], v[138:139], v[134:135]
	s_waitcnt lgkmcnt(0)
	v_lshlrev_b32_e32 v132, 16, v128
	v_and_b32_e32 v133, 0xffff0000, v128
	v_lshlrev_b32_e32 v134, 16, v129
	v_and_b32_e32 v135, 0xffff0000, v129
	v_lshlrev_b32_e32 v136, 16, v130
	v_and_b32_e32 v137, 0xffff0000, v130
	v_lshlrev_b32_e32 v138, 16, v131
	v_and_b32_e32 v139, 0xffff0000, v131
	s_mov_b32 s98, 0xbf60028b
	v_mul_f32_e32 v132, s98, v132
	v_mul_f32_e32 v133, s98, v133
	v_mul_f32_e32 v134, s98, v134
	v_mul_f32_e32 v135, s98, v135
	v_exp_f32_e32 v132, v132
	v_exp_f32_e32 v133, v133
	v_exp_f32_e32 v134, v134
	v_exp_f32_e32 v135, v135
	v_pk_mul_f32 v[140:141], v[102:103], v[42:43]
	v_pk_mul_f32 v[142:143], v[104:105], v[44:45]
	v_pk_mul_f32 v[106:107], v[140:141], v[140:141]
	v_pk_fma_f32 v[106:107], v[142:143], v[142:143], v[106:107]
	v_add_f32_e32 v106, v106, v107
	s_nop 1
	v_add_f32_dpp v106, v106, v106 row_ror:8 row_mask:0xf bank_mask:0xf bound_ctrl:1
	s_nop 1
	v_add_f32_dpp v106, v106, v106 row_ror:4 row_mask:0xf bank_mask:0xf bound_ctrl:1
	s_nop 1
	v_add_f32_dpp v106, v106, v106 row_ror:2 row_mask:0xf bank_mask:0xf bound_ctrl:1
	s_nop 1
	v_add_f32_dpp v106, v106, v106 row_ror:1 row_mask:0xf bank_mask:0xf bound_ctrl:1
	v_add_f32_e32 v106, 0x2b8cbccc, v106
	v_rsq_f32_e32 v106, v106
	v_pk_mul_f32 v[148:149], v[148:149], s[40:41] op_sel_hi:[1,0]
	v_pk_mul_f32 v[150:151], v[150:151], s[40:41] op_sel_hi:[1,0]
	v_pk_mul_f32 v[140:141], v[140:141], v[106:107] op_sel_hi:[1,0]
	v_pk_mul_f32 v[142:143], v[142:143], v[106:107] op_sel_hi:[1,0]
	v_pk_add_f32 v[70:71], v[136:137], -1.0 op_sel_hi:[1,0]
	v_pk_add_f32 v[72:73], v[138:139], -1.0 op_sel_hi:[1,0]
	v_pk_fma_f32 v[70:71], v[30:31], v[70:71], 1.0 op_sel_hi:[1,1,0]
	v_pk_fma_f32 v[72:73], v[32:33], v[72:73], 1.0 op_sel_hi:[1,1,0]
	v_pk_mul_f32 v[70:71], v[102:103], v[70:71]
	v_pk_mul_f32 v[72:73], v[104:105], v[72:73]
	v_pk_mul_f32 v[74:75], v[140:141], v[136:137]
	v_pk_mul_f32 v[76:77], v[142:143], v[138:139]
	ds_write_b128 v3, v[140:143] offset:0
	ds_write_b128 v3, v[132:135] offset:4096
	ds_write_b128 v3, v[74:77] offset:8192
	ds_write_b128 v3, v[70:73] offset:12288
	ds_write_b128 v3, v[144:147] offset:16384
	ds_write_b128 v4, v[148:151]
	s_waitcnt lgkmcnt(0)
	s_barrier
	s_cmp_eq_u32 s18, 2
	s_cbranch_scc1 .Lrw0_u2s0
	ds_read_b128 v[30:33], v112 offset:0
	ds_read_b128 v[34:37], v112 offset:16
	ds_read_b128 v[78:81], v112 offset:12288
	ds_read_b128 v[82:85], v112 offset:12304
	ds_read_b32 v104, v108 offset:20480
	ds_read_b128 v[38:41], v112 offset:4096
	ds_read_b128 v[42:45], v112 offset:4112
	ds_read_b128 v[70:73], v112 offset:8192
	ds_read_b128 v[74:77], v112 offset:8208
	s_waitcnt lgkmcnt(7)
	v_pk_mul_f32 v[136:137], v[22:23], v[30:31]
	v_pk_fma_f32 v[136:137], v[24:25], v[32:33], v[136:137]
	v_pk_fma_f32 v[136:137], v[26:27], v[34:35], v[136:137]
	v_pk_fma_f32 v[136:137], v[28:29], v[36:37], v[136:137]
	ds_read_b128 v[30:33], v112 offset:256
	ds_read_b128 v[34:37], v112 offset:272
	ds_read_b128 v[96:99], v112 offset:16384
	ds_read_b128 v[100:103], v112 offset:16400
	v_add_f32_e32 v140, v136, v137
	s_waitcnt lgkmcnt(8)
	v_pk_mul_f32 v[128:129], v[78:79], v[104:105] op_sel_hi:[1,0]
	v_add_f32_dpp v140, v140, v140 row_half_mirror row_mask:0xf bank_mask:0xf
	v_pk_mul_f32 v[130:131], v[80:81], v[104:105] op_sel_hi:[1,0]
	v_pk_mul_f32 v[132:133], v[82:83], v[104:105] op_sel_hi:[1,0]
	v_pk_mul_f32 v[134:135], v[84:85], v[104:105] op_sel_hi:[1,0]
	ds_read_b128 v[78:81], v112 offset:12544
	ds_read_b128 v[82:85], v112 offset:12560
	ds_read_b32 v104, v108 offset:20608
	v_add_f32_dpp v140, v140, v140 quad_perm:[1,0,3,2] row_mask:0xf bank_mask:0xf
	s_waitcnt lgkmcnt(9)
	v_pk_fma_f32 v[128:129], v[22:23], v[38:39], v[128:129]
	v_pk_fma_f32 v[130:131], v[24:25], v[40:41], v[130:131]
	v_pk_fma_f32 v[132:133], v[26:27], v[42:43], v[132:133]
	v_add_f32_dpp v140, v140, v140 quad_perm:[2,3,0,1] row_mask:0xf bank_mask:0xf
	v_pk_fma_f32 v[134:135], v[28:29], v[44:45], v[134:135]
	ds_read_b128 v[38:41], v112 offset:4352
	ds_read_b128 v[42:45], v112 offset:4368
	s_waitcnt lgkmcnt(9)
	v_pk_fma_f32 v[22:23], v[140:141], v[70:71], v[128:129] op_sel_hi:[0,1,1] neg_lo:[1,0,0] neg_hi:[1,0,0]
	v_pk_fma_f32 v[24:25], v[140:141], v[72:73], v[130:131] op_sel_hi:[0,1,1] neg_lo:[1,0,0] neg_hi:[1,0,0]
	v_pk_fma_f32 v[26:27], v[140:141], v[74:75], v[132:133] op_sel_hi:[0,1,1] neg_lo:[1,0,0] neg_hi:[1,0,0]
	v_pk_fma_f32 v[28:29], v[140:141], v[76:77], v[134:135] op_sel_hi:[0,1,1] neg_lo:[1,0,0] neg_hi:[1,0,0]
	ds_read_b128 v[70:73], v112 offset:8448
	ds_read_b128 v[74:77], v112 offset:8464
	s_waitcnt lgkmcnt(7)
	v_pk_mul_f32 v[136:137], v[22:23], v[30:31]
	v_pk_mul_f32 v[138:139], v[22:23], v[96:97]
	v_pk_fma_f32 v[136:137], v[24:25], v[32:33], v[136:137]
	v_pk_fma_f32 v[138:139], v[24:25], v[98:99], v[138:139]
	v_pk_fma_f32 v[136:137], v[26:27], v[34:35], v[136:137]
	v_pk_fma_f32 v[138:139], v[26:27], v[100:101], v[138:139]
	v_pk_fma_f32 v[136:137], v[28:29], v[36:37], v[136:137]
	v_pk_fma_f32 v[138:139], v[28:29], v[102:103], v[138:139]
	ds_read_b128 v[30:33], v112 offset:512
	ds_read_b128 v[34:37], v112 offset:528
	ds_read_b128 v[96:99], v112 offset:16640
	ds_read_b128 v[100:103], v112 offset:16656
	v_add_f32_e32 v140, v136, v137
	v_add_f32_e32 v142, v138, v139
	s_waitcnt lgkmcnt(8)
	v_pk_mul_f32 v[128:129], v[78:79], v[104:105] op_sel_hi:[1,0]
	v_add_f32_dpp v140, v140, v140 row_half_mirror row_mask:0xf bank_mask:0xf
	v_add_f32_dpp v142, v142, v142 row_half_mirror row_mask:0xf bank_mask:0xf
	v_pk_mul_f32 v[130:131], v[80:81], v[104:105] op_sel_hi:[1,0]
	v_pk_mul_f32 v[132:133], v[82:83], v[104:105] op_sel_hi:[1,0]
	v_add_f32_dpp v140, v140, v140 quad_perm:[1,0,3,2] row_mask:0xf bank_mask:0xf
	v_add_f32_dpp v142, v142, v142 quad_perm:[1,0,3,2] row_mask:0xf bank_mask:0xf
	v_pk_mul_f32 v[134:135], v[84:85], v[104:105] op_sel_hi:[1,0]
	ds_read_b128 v[78:81], v112 offset:12800
	ds_read_b128 v[82:85], v112 offset:12816
	ds_read_b32 v104, v108 offset:20736
	s_waitcnt lgkmcnt(9)
	v_pk_fma_f32 v[128:129], v[22:23], v[38:39], v[128:129]
	v_add_f32_dpp v140, v140, v140 quad_perm:[2,3,0,1] row_mask:0xf bank_mask:0xf
	v_add_f32_dpp v142, v142, v142 quad_perm:[2,3,0,1] row_mask:0xf bank_mask:0xf
	v_pk_fma_f32 v[130:131], v[24:25], v[40:41], v[130:131]
	v_pk_fma_f32 v[132:133], v[26:27], v[42:43], v[132:133]
	v_pk_fma_f32 v[134:135], v[28:29], v[44:45], v[134:135]
	ds_read_b128 v[38:41], v112 offset:4608
	ds_read_b128 v[42:45], v112 offset:4624
	s_waitcnt lgkmcnt(9)
	v_pk_fma_f32 v[22:23], v[140:141], v[70:71], v[128:129] op_sel_hi:[0,1,1] neg_lo:[1,0,0] neg_hi:[1,0,0]
	v_pk_fma_f32 v[24:25], v[140:141], v[72:73], v[130:131] op_sel_hi:[0,1,1] neg_lo:[1,0,0] neg_hi:[1,0,0]
	v_pk_fma_f32 v[26:27], v[140:141], v[74:75], v[132:133] op_sel_hi:[0,1,1] neg_lo:[1,0,0] neg_hi:[1,0,0]
	v_pk_fma_f32 v[28:29], v[140:141], v[76:77], v[134:135] op_sel_hi:[0,1,1] neg_lo:[1,0,0] neg_hi:[1,0,0]
	ds_read_b128 v[70:73], v112 offset:8704
	ds_read_b128 v[74:77], v112 offset:8720
	ds_write_b32 v108, v142 offset:22528
	s_waitcnt lgkmcnt(8)
	v_pk_mul_f32 v[136:137], v[22:23], v[30:31]
	v_pk_mul_f32 v[138:139], v[22:23], v[96:97]
	v_pk_fma_f32 v[136:137], v[24:25], v[32:33], v[136:137]
	v_pk_fma_f32 v[138:139], v[24:25], v[98:99], v[138:139]
	v_pk_fma_f32 v[136:137], v[26:27], v[34:35], v[136:137]
	v_pk_fma_f32 v[138:139], v[26:27], v[100:101], v[138:139]
	v_pk_fma_f32 v[136:137], v[28:29], v[36:37], v[136:137]
	v_pk_fma_f32 v[138:139], v[28:29], v[102:103], v[138:139]
	ds_read_b128 v[30:33], v112 offset:768
	ds_read_b128 v[34:37], v112 offset:784
	ds_read_b128 v[96:99], v112 offset:16896
	ds_read_b128 v[100:103], v112 offset:16912
	v_add_f32_e32 v140, v136, v137
	v_add_f32_e32 v142, v138, v139
	s_waitcnt lgkmcnt(9)
	v_pk_mul_f32 v[128:129], v[78:79], v[104:105] op_sel_hi:[1,0]
	v_add_f32_dpp v140, v140, v140 row_half_mirror row_mask:0xf bank_mask:0xf
	v_add_f32_dpp v142, v142, v142 row_half_mirror row_mask:0xf bank_mask:0xf
	v_pk_mul_f32 v[130:131], v[80:81], v[104:105] op_sel_hi:[1,0]
	v_pk_mul_f32 v[132:133], v[82:83], v[104:105] op_sel_hi:[1,0]
	v_add_f32_dpp v140, v140, v140 quad_perm:[1,0,3,2] row_mask:0xf bank_mask:0xf
	v_add_f32_dpp v142, v142, v142 quad_perm:[1,0,3,2] row_mask:0xf bank_mask:0xf
	v_pk_mul_f32 v[134:135], v[84:85], v[104:105] op_sel_hi:[1,0]
	ds_read_b128 v[78:81], v112 offset:13056
	ds_read_b128 v[82:85], v112 offset:13072
	ds_read_b32 v104, v108 offset:20864
	s_waitcnt lgkmcnt(10)
	v_pk_fma_f32 v[128:129], v[22:23], v[38:39], v[128:129]
	v_add_f32_dpp v140, v140, v140 quad_perm:[2,3,0,1] row_mask:0xf bank_mask:0xf
	v_add_f32_dpp v142, v142, v142 quad_perm:[2,3,0,1] row_mask:0xf bank_mask:0xf
	v_pk_fma_f32 v[130:131], v[24:25], v[40:41], v[130:131]
	v_pk_fma_f32 v[132:133], v[26:27], v[42:43], v[132:133]
	v_pk_fma_f32 v[134:135], v[28:29], v[44:45], v[134:135]
	ds_read_b128 v[38:41], v112 offset:4864
	ds_read_b128 v[42:45], v112 offset:4880
	s_waitcnt lgkmcnt(10)
	v_pk_fma_f32 v[22:23], v[140:141], v[70:71], v[128:129] op_sel_hi:[0,1,1] neg_lo:[1,0,0] neg_hi:[1,0,0]
	v_pk_fma_f32 v[24:25], v[140:141], v[72:73], v[130:131] op_sel_hi:[0,1,1] neg_lo:[1,0,0] neg_hi:[1,0,0]
	v_pk_fma_f32 v[26:27], v[140:141], v[74:75], v[132:133] op_sel_hi:[0,1,1] neg_lo:[1,0,0] neg_hi:[1,0,0]
	v_pk_fma_f32 v[28:29], v[140:141], v[76:77], v[134:135] op_sel_hi:[0,1,1] neg_lo:[1,0,0] neg_hi:[1,0,0]
	ds_read_b128 v[70:73], v112 offset:8960
	ds_read_b128 v[74:77], v112 offset:8976
	ds_write_b32 v108, v142 offset:22656
	s_waitcnt lgkmcnt(8)
	v_pk_mul_f32 v[136:137], v[22:23], v[30:31]
	v_pk_mul_f32 v[138:139], v[22:23], v[96:97]
	v_pk_fma_f32 v[136:137], v[24:25], v[32:33], v[136:137]
	v_pk_fma_f32 v[138:139], v[24:25], v[98:99], v[138:139]
	v_pk_fma_f32 v[136:137], v[26:27], v[34:35], v[136:137]
	v_pk_fma_f32 v[138:139], v[26:27], v[100:101], v[138:139]
	v_pk_fma_f32 v[136:137], v[28:29], v[36:37], v[136:137]
	v_pk_fma_f32 v[138:139], v[28:29], v[102:103], v[138:139]
	ds_read_b128 v[30:33], v112 offset:1024
	ds_read_b128 v[34:37], v112 offset:1040
	ds_read_b128 v[96:99], v112 offset:17152
	ds_read_b128 v[100:103], v112 offset:17168
	v_add_f32_e32 v140, v136, v137
	v_add_f32_e32 v142, v138, v139
	s_waitcnt lgkmcnt(9)
	v_pk_mul_f32 v[128:129], v[78:79], v[104:105] op_sel_hi:[1,0]
	v_add_f32_dpp v140, v140, v140 row_half_mirror row_mask:0xf bank_mask:0xf
	v_add_f32_dpp v142, v142, v142 row_half_mirror row_mask:0xf bank_mask:0xf
	v_pk_mul_f32 v[130:131], v[80:81], v[104:105] op_sel_hi:[1,0]
	v_pk_mul_f32 v[132:133], v[82:83], v[104:105] op_sel_hi:[1,0]
	v_add_f32_dpp v140, v140, v140 quad_perm:[1,0,3,2] row_mask:0xf bank_mask:0xf
	v_add_f32_dpp v142, v142, v142 quad_perm:[1,0,3,2] row_mask:0xf bank_mask:0xf
	v_pk_mul_f32 v[134:135], v[84:85], v[104:105] op_sel_hi:[1,0]
	ds_read_b128 v[78:81], v112 offset:13312
	ds_read_b128 v[82:85], v112 offset:13328
	ds_read_b32 v104, v108 offset:20992
	s_waitcnt lgkmcnt(10)
	v_pk_fma_f32 v[128:129], v[22:23], v[38:39], v[128:129]
	v_add_f32_dpp v140, v140, v140 quad_perm:[2,3,0,1] row_mask:0xf bank_mask:0xf
	v_add_f32_dpp v142, v142, v142 quad_perm:[2,3,0,1] row_mask:0xf bank_mask:0xf
	v_pk_fma_f32 v[130:131], v[24:25], v[40:41], v[130:131]
	v_pk_fma_f32 v[132:133], v[26:27], v[42:43], v[132:133]
	v_pk_fma_f32 v[134:135], v[28:29], v[44:45], v[134:135]
	ds_read_b128 v[38:41], v112 offset:5120
	ds_read_b128 v[42:45], v112 offset:5136
	s_waitcnt lgkmcnt(10)
	v_pk_fma_f32 v[22:23], v[140:141], v[70:71], v[128:129] op_sel_hi:[0,1,1] neg_lo:[1,0,0] neg_hi:[1,0,0]
	v_pk_fma_f32 v[24:25], v[140:141], v[72:73], v[130:131] op_sel_hi:[0,1,1] neg_lo:[1,0,0] neg_hi:[1,0,0]
	v_pk_fma_f32 v[26:27], v[140:141], v[74:75], v[132:133] op_sel_hi:[0,1,1] neg_lo:[1,0,0] neg_hi:[1,0,0]
	v_pk_fma_f32 v[28:29], v[140:141], v[76:77], v[134:135] op_sel_hi:[0,1,1] neg_lo:[1,0,0] neg_hi:[1,0,0]
	ds_read_b128 v[70:73], v112 offset:9216
	ds_read_b128 v[74:77], v112 offset:9232
	ds_write_b32 v108, v142 offset:22784
	s_waitcnt lgkmcnt(8)
	v_pk_mul_f32 v[136:137], v[22:23], v[30:31]
	v_pk_mul_f32 v[138:139], v[22:23], v[96:97]
	v_pk_fma_f32 v[136:137], v[24:25], v[32:33], v[136:137]
	v_pk_fma_f32 v[138:139], v[24:25], v[98:99], v[138:139]
	v_pk_fma_f32 v[136:137], v[26:27], v[34:35], v[136:137]
	v_pk_fma_f32 v[138:139], v[26:27], v[100:101], v[138:139]
	v_pk_fma_f32 v[136:137], v[28:29], v[36:37], v[136:137]
	v_pk_fma_f32 v[138:139], v[28:29], v[102:103], v[138:139]
	ds_read_b128 v[30:33], v112 offset:1280
	ds_read_b128 v[34:37], v112 offset:1296
	ds_read_b128 v[96:99], v112 offset:17408
	ds_read_b128 v[100:103], v112 offset:17424
	v_add_f32_e32 v140, v136, v137
	v_add_f32_e32 v142, v138, v139
	s_waitcnt lgkmcnt(9)
	v_pk_mul_f32 v[128:129], v[78:79], v[104:105] op_sel_hi:[1,0]
	v_add_f32_dpp v140, v140, v140 row_half_mirror row_mask:0xf bank_mask:0xf
	v_add_f32_dpp v142, v142, v142 row_half_mirror row_mask:0xf bank_mask:0xf
	v_pk_mul_f32 v[130:131], v[80:81], v[104:105] op_sel_hi:[1,0]
	v_pk_mul_f32 v[132:133], v[82:83], v[104:105] op_sel_hi:[1,0]
	v_add_f32_dpp v140, v140, v140 quad_perm:[1,0,3,2] row_mask:0xf bank_mask:0xf
	v_add_f32_dpp v142, v142, v142 quad_perm:[1,0,3,2] row_mask:0xf bank_mask:0xf
	v_pk_mul_f32 v[134:135], v[84:85], v[104:105] op_sel_hi:[1,0]
	ds_read_b128 v[78:81], v112 offset:13568
	ds_read_b128 v[82:85], v112 offset:13584
	ds_read_b32 v104, v108 offset:21120
	s_waitcnt lgkmcnt(10)
	v_pk_fma_f32 v[128:129], v[22:23], v[38:39], v[128:129]
	v_add_f32_dpp v140, v140, v140 quad_perm:[2,3,0,1] row_mask:0xf bank_mask:0xf
	v_add_f32_dpp v142, v142, v142 quad_perm:[2,3,0,1] row_mask:0xf bank_mask:0xf
	v_pk_fma_f32 v[130:131], v[24:25], v[40:41], v[130:131]
	v_pk_fma_f32 v[132:133], v[26:27], v[42:43], v[132:133]
	v_pk_fma_f32 v[134:135], v[28:29], v[44:45], v[134:135]
	ds_read_b128 v[38:41], v112 offset:5376
	ds_read_b128 v[42:45], v112 offset:5392
	s_waitcnt lgkmcnt(10)
	v_pk_fma_f32 v[22:23], v[140:141], v[70:71], v[128:129] op_sel_hi:[0,1,1] neg_lo:[1,0,0] neg_hi:[1,0,0]
	v_pk_fma_f32 v[24:25], v[140:141], v[72:73], v[130:131] op_sel_hi:[0,1,1] neg_lo:[1,0,0] neg_hi:[1,0,0]
	v_pk_fma_f32 v[26:27], v[140:141], v[74:75], v[132:133] op_sel_hi:[0,1,1] neg_lo:[1,0,0] neg_hi:[1,0,0]
	v_pk_fma_f32 v[28:29], v[140:141], v[76:77], v[134:135] op_sel_hi:[0,1,1] neg_lo:[1,0,0] neg_hi:[1,0,0]
	ds_read_b128 v[70:73], v112 offset:9472
	ds_read_b128 v[74:77], v112 offset:9488
	ds_write_b32 v108, v142 offset:22912
	s_waitcnt lgkmcnt(8)
	v_pk_mul_f32 v[136:137], v[22:23], v[30:31]
	v_pk_mul_f32 v[138:139], v[22:23], v[96:97]
	v_pk_fma_f32 v[136:137], v[24:25], v[32:33], v[136:137]
	v_pk_fma_f32 v[138:139], v[24:25], v[98:99], v[138:139]
	v_pk_fma_f32 v[136:137], v[26:27], v[34:35], v[136:137]
	v_pk_fma_f32 v[138:139], v[26:27], v[100:101], v[138:139]
	v_pk_fma_f32 v[136:137], v[28:29], v[36:37], v[136:137]
	v_pk_fma_f32 v[138:139], v[28:29], v[102:103], v[138:139]
	ds_read_b128 v[30:33], v112 offset:1536
	ds_read_b128 v[34:37], v112 offset:1552
	ds_read_b128 v[96:99], v112 offset:17664
	ds_read_b128 v[100:103], v112 offset:17680
	v_add_f32_e32 v140, v136, v137
	v_add_f32_e32 v142, v138, v139
	s_waitcnt lgkmcnt(9)
	v_pk_mul_f32 v[128:129], v[78:79], v[104:105] op_sel_hi:[1,0]
	v_add_f32_dpp v140, v140, v140 row_half_mirror row_mask:0xf bank_mask:0xf
	v_add_f32_dpp v142, v142, v142 row_half_mirror row_mask:0xf bank_mask:0xf
	v_pk_mul_f32 v[130:131], v[80:81], v[104:105] op_sel_hi:[1,0]
	v_pk_mul_f32 v[132:133], v[82:83], v[104:105] op_sel_hi:[1,0]
	v_add_f32_dpp v140, v140, v140 quad_perm:[1,0,3,2] row_mask:0xf bank_mask:0xf
	v_add_f32_dpp v142, v142, v142 quad_perm:[1,0,3,2] row_mask:0xf bank_mask:0xf
	v_pk_mul_f32 v[134:135], v[84:85], v[104:105] op_sel_hi:[1,0]
	ds_read_b128 v[78:81], v112 offset:13824
	ds_read_b128 v[82:85], v112 offset:13840
	ds_read_b32 v104, v108 offset:21248
	s_waitcnt lgkmcnt(10)
	v_pk_fma_f32 v[128:129], v[22:23], v[38:39], v[128:129]
	v_add_f32_dpp v140, v140, v140 quad_perm:[2,3,0,1] row_mask:0xf bank_mask:0xf
	v_add_f32_dpp v142, v142, v142 quad_perm:[2,3,0,1] row_mask:0xf bank_mask:0xf
	v_pk_fma_f32 v[130:131], v[24:25], v[40:41], v[130:131]
	v_pk_fma_f32 v[132:133], v[26:27], v[42:43], v[132:133]
	v_pk_fma_f32 v[134:135], v[28:29], v[44:45], v[134:135]
	ds_read_b128 v[38:41], v112 offset:5632
	ds_read_b128 v[42:45], v112 offset:5648
	s_waitcnt lgkmcnt(10)
	v_pk_fma_f32 v[22:23], v[140:141], v[70:71], v[128:129] op_sel_hi:[0,1,1] neg_lo:[1,0,0] neg_hi:[1,0,0]
	v_pk_fma_f32 v[24:25], v[140:141], v[72:73], v[130:131] op_sel_hi:[0,1,1] neg_lo:[1,0,0] neg_hi:[1,0,0]
	v_pk_fma_f32 v[26:27], v[140:141], v[74:75], v[132:133] op_sel_hi:[0,1,1] neg_lo:[1,0,0] neg_hi:[1,0,0]
	v_pk_fma_f32 v[28:29], v[140:141], v[76:77], v[134:135] op_sel_hi:[0,1,1] neg_lo:[1,0,0] neg_hi:[1,0,0]
	ds_read_b128 v[70:73], v112 offset:9728
	ds_read_b128 v[74:77], v112 offset:9744
	ds_write_b32 v108, v142 offset:23040
	s_waitcnt lgkmcnt(8)
	v_pk_mul_f32 v[136:137], v[22:23], v[30:31]
	v_pk_mul_f32 v[138:139], v[22:23], v[96:97]
	v_pk_fma_f32 v[136:137], v[24:25], v[32:33], v[136:137]
	v_pk_fma_f32 v[138:139], v[24:25], v[98:99], v[138:139]
	v_pk_fma_f32 v[136:137], v[26:27], v[34:35], v[136:137]
	v_pk_fma_f32 v[138:139], v[26:27], v[100:101], v[138:139]
	v_pk_fma_f32 v[136:137], v[28:29], v[36:37], v[136:137]
	v_pk_fma_f32 v[138:139], v[28:29], v[102:103], v[138:139]
	ds_read_b128 v[30:33], v112 offset:1792
	ds_read_b128 v[34:37], v112 offset:1808
	ds_read_b128 v[96:99], v112 offset:17920
	ds_read_b128 v[100:103], v112 offset:17936
	v_add_f32_e32 v140, v136, v137
	v_add_f32_e32 v142, v138, v139
	s_waitcnt lgkmcnt(9)
	v_pk_mul_f32 v[128:129], v[78:79], v[104:105] op_sel_hi:[1,0]
	v_add_f32_dpp v140, v140, v140 row_half_mirror row_mask:0xf bank_mask:0xf
	v_add_f32_dpp v142, v142, v142 row_half_mirror row_mask:0xf bank_mask:0xf
	v_pk_mul_f32 v[130:131], v[80:81], v[104:105] op_sel_hi:[1,0]
	v_pk_mul_f32 v[132:133], v[82:83], v[104:105] op_sel_hi:[1,0]
	v_add_f32_dpp v140, v140, v140 quad_perm:[1,0,3,2] row_mask:0xf bank_mask:0xf
	v_add_f32_dpp v142, v142, v142 quad_perm:[1,0,3,2] row_mask:0xf bank_mask:0xf
	v_pk_mul_f32 v[134:135], v[84:85], v[104:105] op_sel_hi:[1,0]
	ds_read_b128 v[78:81], v112 offset:14080
	ds_read_b128 v[82:85], v112 offset:14096
	ds_read_b32 v104, v108 offset:21376
	s_waitcnt lgkmcnt(10)
	v_pk_fma_f32 v[128:129], v[22:23], v[38:39], v[128:129]
	v_add_f32_dpp v140, v140, v140 quad_perm:[2,3,0,1] row_mask:0xf bank_mask:0xf
	v_add_f32_dpp v142, v142, v142 quad_perm:[2,3,0,1] row_mask:0xf bank_mask:0xf
	v_pk_fma_f32 v[130:131], v[24:25], v[40:41], v[130:131]
	v_pk_fma_f32 v[132:133], v[26:27], v[42:43], v[132:133]
	v_pk_fma_f32 v[134:135], v[28:29], v[44:45], v[134:135]
	ds_read_b128 v[38:41], v112 offset:5888
	ds_read_b128 v[42:45], v112 offset:5904
	s_waitcnt lgkmcnt(10)
	v_pk_fma_f32 v[22:23], v[140:141], v[70:71], v[128:129] op_sel_hi:[0,1,1] neg_lo:[1,0,0] neg_hi:[1,0,0]
	v_pk_fma_f32 v[24:25], v[140:141], v[72:73], v[130:131] op_sel_hi:[0,1,1] neg_lo:[1,0,0] neg_hi:[1,0,0]
	v_pk_fma_f32 v[26:27], v[140:141], v[74:75], v[132:133] op_sel_hi:[0,1,1] neg_lo:[1,0,0] neg_hi:[1,0,0]
	v_pk_fma_f32 v[28:29], v[140:141], v[76:77], v[134:135] op_sel_hi:[0,1,1] neg_lo:[1,0,0] neg_hi:[1,0,0]
	ds_read_b128 v[70:73], v112 offset:9984
	ds_read_b128 v[74:77], v112 offset:10000
	ds_write_b32 v108, v142 offset:23168
	s_waitcnt lgkmcnt(8)
	v_pk_mul_f32 v[136:137], v[22:23], v[30:31]
	v_pk_mul_f32 v[138:139], v[22:23], v[96:97]
	v_pk_fma_f32 v[136:137], v[24:25], v[32:33], v[136:137]
	v_pk_fma_f32 v[138:139], v[24:25], v[98:99], v[138:139]
	v_pk_fma_f32 v[136:137], v[26:27], v[34:35], v[136:137]
	v_pk_fma_f32 v[138:139], v[26:27], v[100:101], v[138:139]
	v_pk_fma_f32 v[136:137], v[28:29], v[36:37], v[136:137]
	v_pk_fma_f32 v[138:139], v[28:29], v[102:103], v[138:139]
	ds_read_b128 v[30:33], v112 offset:2048
	ds_read_b128 v[34:37], v112 offset:2064
	ds_read_b128 v[96:99], v112 offset:18176
	ds_read_b128 v[100:103], v112 offset:18192
	v_add_f32_e32 v140, v136, v137
	v_add_f32_e32 v142, v138, v139
	s_waitcnt lgkmcnt(9)
	v_pk_mul_f32 v[128:129], v[78:79], v[104:105] op_sel_hi:[1,0]
	v_add_f32_dpp v140, v140, v140 row_half_mirror row_mask:0xf bank_mask:0xf
	v_add_f32_dpp v142, v142, v142 row_half_mirror row_mask:0xf bank_mask:0xf
	v_pk_mul_f32 v[130:131], v[80:81], v[104:105] op_sel_hi:[1,0]
	v_pk_mul_f32 v[132:133], v[82:83], v[104:105] op_sel_hi:[1,0]
	v_add_f32_dpp v140, v140, v140 quad_perm:[1,0,3,2] row_mask:0xf bank_mask:0xf
	v_add_f32_dpp v142, v142, v142 quad_perm:[1,0,3,2] row_mask:0xf bank_mask:0xf
	v_pk_mul_f32 v[134:135], v[84:85], v[104:105] op_sel_hi:[1,0]
	ds_read_b128 v[78:81], v112 offset:14336
	ds_read_b128 v[82:85], v112 offset:14352
	ds_read_b32 v104, v108 offset:21504
	s_waitcnt lgkmcnt(10)
	v_pk_fma_f32 v[128:129], v[22:23], v[38:39], v[128:129]
	v_add_f32_dpp v140, v140, v140 quad_perm:[2,3,0,1] row_mask:0xf bank_mask:0xf
	v_add_f32_dpp v142, v142, v142 quad_perm:[2,3,0,1] row_mask:0xf bank_mask:0xf
	v_pk_fma_f32 v[130:131], v[24:25], v[40:41], v[130:131]
	v_pk_fma_f32 v[132:133], v[26:27], v[42:43], v[132:133]
	v_pk_fma_f32 v[134:135], v[28:29], v[44:45], v[134:135]
	ds_read_b128 v[38:41], v112 offset:6144
	ds_read_b128 v[42:45], v112 offset:6160
	s_waitcnt lgkmcnt(10)
	v_pk_fma_f32 v[22:23], v[140:141], v[70:71], v[128:129] op_sel_hi:[0,1,1] neg_lo:[1,0,0] neg_hi:[1,0,0]
	v_pk_fma_f32 v[24:25], v[140:141], v[72:73], v[130:131] op_sel_hi:[0,1,1] neg_lo:[1,0,0] neg_hi:[1,0,0]
	v_pk_fma_f32 v[26:27], v[140:141], v[74:75], v[132:133] op_sel_hi:[0,1,1] neg_lo:[1,0,0] neg_hi:[1,0,0]
	v_pk_fma_f32 v[28:29], v[140:141], v[76:77], v[134:135] op_sel_hi:[0,1,1] neg_lo:[1,0,0] neg_hi:[1,0,0]
	ds_read_b128 v[70:73], v112 offset:10240
	ds_read_b128 v[74:77], v112 offset:10256
	ds_write_b32 v108, v142 offset:23296
	s_waitcnt lgkmcnt(8)
	v_pk_mul_f32 v[136:137], v[22:23], v[30:31]
	v_pk_mul_f32 v[138:139], v[22:23], v[96:97]
	v_pk_fma_f32 v[136:137], v[24:25], v[32:33], v[136:137]
	v_pk_fma_f32 v[138:139], v[24:25], v[98:99], v[138:139]
	v_pk_fma_f32 v[136:137], v[26:27], v[34:35], v[136:137]
	v_pk_fma_f32 v[138:139], v[26:27], v[100:101], v[138:139]
	v_pk_fma_f32 v[136:137], v[28:29], v[36:37], v[136:137]
	v_pk_fma_f32 v[138:139], v[28:29], v[102:103], v[138:139]
	ds_read_b128 v[30:33], v112 offset:2304
	ds_read_b128 v[34:37], v112 offset:2320
	ds_read_b128 v[96:99], v112 offset:18432
	ds_read_b128 v[100:103], v112 offset:18448
	v_add_f32_e32 v140, v136, v137
	v_add_f32_e32 v142, v138, v139
	s_waitcnt lgkmcnt(9)
	v_pk_mul_f32 v[128:129], v[78:79], v[104:105] op_sel_hi:[1,0]
	v_add_f32_dpp v140, v140, v140 row_half_mirror row_mask:0xf bank_mask:0xf
	v_add_f32_dpp v142, v142, v142 row_half_mirror row_mask:0xf bank_mask:0xf
	v_pk_mul_f32 v[130:131], v[80:81], v[104:105] op_sel_hi:[1,0]
	v_pk_mul_f32 v[132:133], v[82:83], v[104:105] op_sel_hi:[1,0]
	v_add_f32_dpp v140, v140, v140 quad_perm:[1,0,3,2] row_mask:0xf bank_mask:0xf
	v_add_f32_dpp v142, v142, v142 quad_perm:[1,0,3,2] row_mask:0xf bank_mask:0xf
	v_pk_mul_f32 v[134:135], v[84:85], v[104:105] op_sel_hi:[1,0]
	ds_read_b128 v[78:81], v112 offset:14592
	ds_read_b128 v[82:85], v112 offset:14608
	ds_read_b32 v104, v108 offset:21632
	s_waitcnt lgkmcnt(10)
	v_pk_fma_f32 v[128:129], v[22:23], v[38:39], v[128:129]
	v_add_f32_dpp v140, v140, v140 quad_perm:[2,3,0,1] row_mask:0xf bank_mask:0xf
	v_add_f32_dpp v142, v142, v142 quad_perm:[2,3,0,1] row_mask:0xf bank_mask:0xf
	v_pk_fma_f32 v[130:131], v[24:25], v[40:41], v[130:131]
	v_pk_fma_f32 v[132:133], v[26:27], v[42:43], v[132:133]
	v_pk_fma_f32 v[134:135], v[28:29], v[44:45], v[134:135]
	ds_read_b128 v[38:41], v112 offset:6400
	ds_read_b128 v[42:45], v112 offset:6416
	s_waitcnt lgkmcnt(10)
	v_pk_fma_f32 v[22:23], v[140:141], v[70:71], v[128:129] op_sel_hi:[0,1,1] neg_lo:[1,0,0] neg_hi:[1,0,0]
	v_pk_fma_f32 v[24:25], v[140:141], v[72:73], v[130:131] op_sel_hi:[0,1,1] neg_lo:[1,0,0] neg_hi:[1,0,0]
	v_pk_fma_f32 v[26:27], v[140:141], v[74:75], v[132:133] op_sel_hi:[0,1,1] neg_lo:[1,0,0] neg_hi:[1,0,0]
	v_pk_fma_f32 v[28:29], v[140:141], v[76:77], v[134:135] op_sel_hi:[0,1,1] neg_lo:[1,0,0] neg_hi:[1,0,0]
	ds_read_b128 v[70:73], v112 offset:10496
	ds_read_b128 v[74:77], v112 offset:10512
	ds_write_b32 v108, v142 offset:23424
	s_waitcnt lgkmcnt(8)
	v_pk_mul_f32 v[136:137], v[22:23], v[30:31]
	v_pk_mul_f32 v[138:139], v[22:23], v[96:97]
	v_pk_fma_f32 v[136:137], v[24:25], v[32:33], v[136:137]
	v_pk_fma_f32 v[138:139], v[24:25], v[98:99], v[138:139]
	v_pk_fma_f32 v[136:137], v[26:27], v[34:35], v[136:137]
	v_pk_fma_f32 v[138:139], v[26:27], v[100:101], v[138:139]
	v_pk_fma_f32 v[136:137], v[28:29], v[36:37], v[136:137]
	v_pk_fma_f32 v[138:139], v[28:29], v[102:103], v[138:139]
	ds_read_b128 v[30:33], v112 offset:2560
	ds_read_b128 v[34:37], v112 offset:2576
	ds_read_b128 v[96:99], v112 offset:18688
	ds_read_b128 v[100:103], v112 offset:18704
	v_add_f32_e32 v140, v136, v137
	v_add_f32_e32 v142, v138, v139
	s_waitcnt lgkmcnt(9)
	v_pk_mul_f32 v[128:129], v[78:79], v[104:105] op_sel_hi:[1,0]
	v_add_f32_dpp v140, v140, v140 row_half_mirror row_mask:0xf bank_mask:0xf
	v_add_f32_dpp v142, v142, v142 row_half_mirror row_mask:0xf bank_mask:0xf
	v_pk_mul_f32 v[130:131], v[80:81], v[104:105] op_sel_hi:[1,0]
	v_pk_mul_f32 v[132:133], v[82:83], v[104:105] op_sel_hi:[1,0]
	v_add_f32_dpp v140, v140, v140 quad_perm:[1,0,3,2] row_mask:0xf bank_mask:0xf
	v_add_f32_dpp v142, v142, v142 quad_perm:[1,0,3,2] row_mask:0xf bank_mask:0xf
	v_pk_mul_f32 v[134:135], v[84:85], v[104:105] op_sel_hi:[1,0]
	ds_read_b128 v[78:81], v112 offset:14848
	ds_read_b128 v[82:85], v112 offset:14864
	ds_read_b32 v104, v108 offset:21760
	s_waitcnt lgkmcnt(10)
	v_pk_fma_f32 v[128:129], v[22:23], v[38:39], v[128:129]
	v_add_f32_dpp v140, v140, v140 quad_perm:[2,3,0,1] row_mask:0xf bank_mask:0xf
	v_add_f32_dpp v142, v142, v142 quad_perm:[2,3,0,1] row_mask:0xf bank_mask:0xf
	v_pk_fma_f32 v[130:131], v[24:25], v[40:41], v[130:131]
	v_pk_fma_f32 v[132:133], v[26:27], v[42:43], v[132:133]
	v_pk_fma_f32 v[134:135], v[28:29], v[44:45], v[134:135]
	ds_read_b128 v[38:41], v112 offset:6656
	ds_read_b128 v[42:45], v112 offset:6672
	s_waitcnt lgkmcnt(10)
	v_pk_fma_f32 v[22:23], v[140:141], v[70:71], v[128:129] op_sel_hi:[0,1,1] neg_lo:[1,0,0] neg_hi:[1,0,0]
	v_pk_fma_f32 v[24:25], v[140:141], v[72:73], v[130:131] op_sel_hi:[0,1,1] neg_lo:[1,0,0] neg_hi:[1,0,0]
	v_pk_fma_f32 v[26:27], v[140:141], v[74:75], v[132:133] op_sel_hi:[0,1,1] neg_lo:[1,0,0] neg_hi:[1,0,0]
	v_pk_fma_f32 v[28:29], v[140:141], v[76:77], v[134:135] op_sel_hi:[0,1,1] neg_lo:[1,0,0] neg_hi:[1,0,0]
	ds_read_b128 v[70:73], v112 offset:10752
	ds_read_b128 v[74:77], v112 offset:10768
	ds_write_b32 v108, v142 offset:23552
	s_waitcnt lgkmcnt(8)
	v_pk_mul_f32 v[136:137], v[22:23], v[30:31]
	v_pk_mul_f32 v[138:139], v[22:23], v[96:97]
	v_pk_fma_f32 v[136:137], v[24:25], v[32:33], v[136:137]
	v_pk_fma_f32 v[138:139], v[24:25], v[98:99], v[138:139]
	v_pk_fma_f32 v[136:137], v[26:27], v[34:35], v[136:137]
	v_pk_fma_f32 v[138:139], v[26:27], v[100:101], v[138:139]
	v_pk_fma_f32 v[136:137], v[28:29], v[36:37], v[136:137]
	v_pk_fma_f32 v[138:139], v[28:29], v[102:103], v[138:139]
	ds_read_b128 v[30:33], v112 offset:2816
	ds_read_b128 v[34:37], v112 offset:2832
	ds_read_b128 v[96:99], v112 offset:18944
	ds_read_b128 v[100:103], v112 offset:18960
	v_add_f32_e32 v140, v136, v137
	v_add_f32_e32 v142, v138, v139
	s_waitcnt lgkmcnt(9)
	v_pk_mul_f32 v[128:129], v[78:79], v[104:105] op_sel_hi:[1,0]
	v_add_f32_dpp v140, v140, v140 row_half_mirror row_mask:0xf bank_mask:0xf
	v_add_f32_dpp v142, v142, v142 row_half_mirror row_mask:0xf bank_mask:0xf
	v_pk_mul_f32 v[130:131], v[80:81], v[104:105] op_sel_hi:[1,0]
	v_pk_mul_f32 v[132:133], v[82:83], v[104:105] op_sel_hi:[1,0]
	v_add_f32_dpp v140, v140, v140 quad_perm:[1,0,3,2] row_mask:0xf bank_mask:0xf
	v_add_f32_dpp v142, v142, v142 quad_perm:[1,0,3,2] row_mask:0xf bank_mask:0xf
	v_pk_mul_f32 v[134:135], v[84:85], v[104:105] op_sel_hi:[1,0]
	ds_read_b128 v[78:81], v112 offset:15104
	ds_read_b128 v[82:85], v112 offset:15120
	ds_read_b32 v104, v108 offset:21888
	s_waitcnt lgkmcnt(10)
	v_pk_fma_f32 v[128:129], v[22:23], v[38:39], v[128:129]
	v_add_f32_dpp v140, v140, v140 quad_perm:[2,3,0,1] row_mask:0xf bank_mask:0xf
	v_add_f32_dpp v142, v142, v142 quad_perm:[2,3,0,1] row_mask:0xf bank_mask:0xf
	v_pk_fma_f32 v[130:131], v[24:25], v[40:41], v[130:131]
	v_pk_fma_f32 v[132:133], v[26:27], v[42:43], v[132:133]
	v_pk_fma_f32 v[134:135], v[28:29], v[44:45], v[134:135]
	ds_read_b128 v[38:41], v112 offset:6912
	ds_read_b128 v[42:45], v112 offset:6928
	s_waitcnt lgkmcnt(10)
	v_pk_fma_f32 v[22:23], v[140:141], v[70:71], v[128:129] op_sel_hi:[0,1,1] neg_lo:[1,0,0] neg_hi:[1,0,0]
	v_pk_fma_f32 v[24:25], v[140:141], v[72:73], v[130:131] op_sel_hi:[0,1,1] neg_lo:[1,0,0] neg_hi:[1,0,0]
	v_pk_fma_f32 v[26:27], v[140:141], v[74:75], v[132:133] op_sel_hi:[0,1,1] neg_lo:[1,0,0] neg_hi:[1,0,0]
	v_pk_fma_f32 v[28:29], v[140:141], v[76:77], v[134:135] op_sel_hi:[0,1,1] neg_lo:[1,0,0] neg_hi:[1,0,0]
	ds_read_b128 v[70:73], v112 offset:11008
	ds_read_b128 v[74:77], v112 offset:11024
	ds_write_b32 v108, v142 offset:23680
	s_waitcnt lgkmcnt(8)
	v_pk_mul_f32 v[136:137], v[22:23], v[30:31]
	v_pk_mul_f32 v[138:139], v[22:23], v[96:97]
	v_pk_fma_f32 v[136:137], v[24:25], v[32:33], v[136:137]
	v_pk_fma_f32 v[138:139], v[24:25], v[98:99], v[138:139]
	v_pk_fma_f32 v[136:137], v[26:27], v[34:35], v[136:137]
	v_pk_fma_f32 v[138:139], v[26:27], v[100:101], v[138:139]
	v_pk_fma_f32 v[136:137], v[28:29], v[36:37], v[136:137]
	v_pk_fma_f32 v[138:139], v[28:29], v[102:103], v[138:139]
	ds_read_b128 v[30:33], v112 offset:3072
	ds_read_b128 v[34:37], v112 offset:3088
	ds_read_b128 v[96:99], v112 offset:19200
	ds_read_b128 v[100:103], v112 offset:19216
	v_add_f32_e32 v140, v136, v137
	v_add_f32_e32 v142, v138, v139
	s_waitcnt lgkmcnt(9)
	v_pk_mul_f32 v[128:129], v[78:79], v[104:105] op_sel_hi:[1,0]
	v_add_f32_dpp v140, v140, v140 row_half_mirror row_mask:0xf bank_mask:0xf
	v_add_f32_dpp v142, v142, v142 row_half_mirror row_mask:0xf bank_mask:0xf
	v_pk_mul_f32 v[130:131], v[80:81], v[104:105] op_sel_hi:[1,0]
	v_pk_mul_f32 v[132:133], v[82:83], v[104:105] op_sel_hi:[1,0]
	v_add_f32_dpp v140, v140, v140 quad_perm:[1,0,3,2] row_mask:0xf bank_mask:0xf
	v_add_f32_dpp v142, v142, v142 quad_perm:[1,0,3,2] row_mask:0xf bank_mask:0xf
	v_pk_mul_f32 v[134:135], v[84:85], v[104:105] op_sel_hi:[1,0]
	ds_read_b128 v[78:81], v112 offset:15360
	ds_read_b128 v[82:85], v112 offset:15376
	ds_read_b32 v104, v108 offset:22016
	s_waitcnt lgkmcnt(10)
	v_pk_fma_f32 v[128:129], v[22:23], v[38:39], v[128:129]
	v_add_f32_dpp v140, v140, v140 quad_perm:[2,3,0,1] row_mask:0xf bank_mask:0xf
	v_add_f32_dpp v142, v142, v142 quad_perm:[2,3,0,1] row_mask:0xf bank_mask:0xf
	v_pk_fma_f32 v[130:131], v[24:25], v[40:41], v[130:131]
	v_pk_fma_f32 v[132:133], v[26:27], v[42:43], v[132:133]
	v_pk_fma_f32 v[134:135], v[28:29], v[44:45], v[134:135]
	ds_read_b128 v[38:41], v112 offset:7168
	ds_read_b128 v[42:45], v112 offset:7184
	s_waitcnt lgkmcnt(10)
	v_pk_fma_f32 v[22:23], v[140:141], v[70:71], v[128:129] op_sel_hi:[0,1,1] neg_lo:[1,0,0] neg_hi:[1,0,0]
	v_pk_fma_f32 v[24:25], v[140:141], v[72:73], v[130:131] op_sel_hi:[0,1,1] neg_lo:[1,0,0] neg_hi:[1,0,0]
	v_pk_fma_f32 v[26:27], v[140:141], v[74:75], v[132:133] op_sel_hi:[0,1,1] neg_lo:[1,0,0] neg_hi:[1,0,0]
	v_pk_fma_f32 v[28:29], v[140:141], v[76:77], v[134:135] op_sel_hi:[0,1,1] neg_lo:[1,0,0] neg_hi:[1,0,0]
	ds_read_b128 v[70:73], v112 offset:11264
	ds_read_b128 v[74:77], v112 offset:11280
	ds_write_b32 v108, v142 offset:23808
	s_waitcnt lgkmcnt(8)
	v_pk_mul_f32 v[136:137], v[22:23], v[30:31]
	v_pk_mul_f32 v[138:139], v[22:23], v[96:97]
	v_pk_fma_f32 v[136:137], v[24:25], v[32:33], v[136:137]
	v_pk_fma_f32 v[138:139], v[24:25], v[98:99], v[138:139]
	v_pk_fma_f32 v[136:137], v[26:27], v[34:35], v[136:137]
	v_pk_fma_f32 v[138:139], v[26:27], v[100:101], v[138:139]
	v_pk_fma_f32 v[136:137], v[28:29], v[36:37], v[136:137]
	v_pk_fma_f32 v[138:139], v[28:29], v[102:103], v[138:139]
	ds_read_b128 v[30:33], v112 offset:3328
	ds_read_b128 v[34:37], v112 offset:3344
	ds_read_b128 v[96:99], v112 offset:19456
	ds_read_b128 v[100:103], v112 offset:19472
	v_add_f32_e32 v140, v136, v137
	v_add_f32_e32 v142, v138, v139
	s_waitcnt lgkmcnt(9)
	v_pk_mul_f32 v[128:129], v[78:79], v[104:105] op_sel_hi:[1,0]
	v_add_f32_dpp v140, v140, v140 row_half_mirror row_mask:0xf bank_mask:0xf
	v_add_f32_dpp v142, v142, v142 row_half_mirror row_mask:0xf bank_mask:0xf
	v_pk_mul_f32 v[130:131], v[80:81], v[104:105] op_sel_hi:[1,0]
	v_pk_mul_f32 v[132:133], v[82:83], v[104:105] op_sel_hi:[1,0]
	v_add_f32_dpp v140, v140, v140 quad_perm:[1,0,3,2] row_mask:0xf bank_mask:0xf
	v_add_f32_dpp v142, v142, v142 quad_perm:[1,0,3,2] row_mask:0xf bank_mask:0xf
	v_pk_mul_f32 v[134:135], v[84:85], v[104:105] op_sel_hi:[1,0]
	ds_read_b128 v[78:81], v112 offset:15616
	ds_read_b128 v[82:85], v112 offset:15632
	ds_read_b32 v104, v108 offset:22144
	s_waitcnt lgkmcnt(10)
	v_pk_fma_f32 v[128:129], v[22:23], v[38:39], v[128:129]
	v_add_f32_dpp v140, v140, v140 quad_perm:[2,3,0,1] row_mask:0xf bank_mask:0xf
	v_add_f32_dpp v142, v142, v142 quad_perm:[2,3,0,1] row_mask:0xf bank_mask:0xf
	v_pk_fma_f32 v[130:131], v[24:25], v[40:41], v[130:131]
	v_pk_fma_f32 v[132:133], v[26:27], v[42:43], v[132:133]
	v_pk_fma_f32 v[134:135], v[28:29], v[44:45], v[134:135]
	ds_read_b128 v[38:41], v112 offset:7424
	ds_read_b128 v[42:45], v112 offset:7440
	s_waitcnt lgkmcnt(10)
	v_pk_fma_f32 v[22:23], v[140:141], v[70:71], v[128:129] op_sel_hi:[0,1,1] neg_lo:[1,0,0] neg_hi:[1,0,0]
	v_pk_fma_f32 v[24:25], v[140:141], v[72:73], v[130:131] op_sel_hi:[0,1,1] neg_lo:[1,0,0] neg_hi:[1,0,0]
	v_pk_fma_f32 v[26:27], v[140:141], v[74:75], v[132:133] op_sel_hi:[0,1,1] neg_lo:[1,0,0] neg_hi:[1,0,0]
	v_pk_fma_f32 v[28:29], v[140:141], v[76:77], v[134:135] op_sel_hi:[0,1,1] neg_lo:[1,0,0] neg_hi:[1,0,0]
	ds_read_b128 v[70:73], v112 offset:11520
	ds_read_b128 v[74:77], v112 offset:11536
	ds_write_b32 v108, v142 offset:23936
	s_waitcnt lgkmcnt(8)
	v_pk_mul_f32 v[136:137], v[22:23], v[30:31]
	v_pk_mul_f32 v[138:139], v[22:23], v[96:97]
	v_pk_fma_f32 v[136:137], v[24:25], v[32:33], v[136:137]
	v_pk_fma_f32 v[138:139], v[24:25], v[98:99], v[138:139]
	v_pk_fma_f32 v[136:137], v[26:27], v[34:35], v[136:137]
	v_pk_fma_f32 v[138:139], v[26:27], v[100:101], v[138:139]
	v_pk_fma_f32 v[136:137], v[28:29], v[36:37], v[136:137]
	v_pk_fma_f32 v[138:139], v[28:29], v[102:103], v[138:139]
	ds_read_b128 v[30:33], v112 offset:3584
	ds_read_b128 v[34:37], v112 offset:3600
	ds_read_b128 v[96:99], v112 offset:19712
	ds_read_b128 v[100:103], v112 offset:19728
	v_add_f32_e32 v140, v136, v137
	v_add_f32_e32 v142, v138, v139
	s_waitcnt lgkmcnt(9)
	v_pk_mul_f32 v[128:129], v[78:79], v[104:105] op_sel_hi:[1,0]
	v_add_f32_dpp v140, v140, v140 row_half_mirror row_mask:0xf bank_mask:0xf
	v_add_f32_dpp v142, v142, v142 row_half_mirror row_mask:0xf bank_mask:0xf
	v_pk_mul_f32 v[130:131], v[80:81], v[104:105] op_sel_hi:[1,0]
	v_pk_mul_f32 v[132:133], v[82:83], v[104:105] op_sel_hi:[1,0]
	v_add_f32_dpp v140, v140, v140 quad_perm:[1,0,3,2] row_mask:0xf bank_mask:0xf
	v_add_f32_dpp v142, v142, v142 quad_perm:[1,0,3,2] row_mask:0xf bank_mask:0xf
	v_pk_mul_f32 v[134:135], v[84:85], v[104:105] op_sel_hi:[1,0]
	ds_read_b128 v[78:81], v112 offset:15872
	ds_read_b128 v[82:85], v112 offset:15888
	ds_read_b32 v104, v108 offset:22272
	s_waitcnt lgkmcnt(10)
	v_pk_fma_f32 v[128:129], v[22:23], v[38:39], v[128:129]
	v_add_f32_dpp v140, v140, v140 quad_perm:[2,3,0,1] row_mask:0xf bank_mask:0xf
	v_add_f32_dpp v142, v142, v142 quad_perm:[2,3,0,1] row_mask:0xf bank_mask:0xf
	v_pk_fma_f32 v[130:131], v[24:25], v[40:41], v[130:131]
	v_pk_fma_f32 v[132:133], v[26:27], v[42:43], v[132:133]
	v_pk_fma_f32 v[134:135], v[28:29], v[44:45], v[134:135]
	ds_read_b128 v[38:41], v112 offset:7680
	ds_read_b128 v[42:45], v112 offset:7696
	s_waitcnt lgkmcnt(10)
	v_pk_fma_f32 v[22:23], v[140:141], v[70:71], v[128:129] op_sel_hi:[0,1,1] neg_lo:[1,0,0] neg_hi:[1,0,0]
	v_pk_fma_f32 v[24:25], v[140:141], v[72:73], v[130:131] op_sel_hi:[0,1,1] neg_lo:[1,0,0] neg_hi:[1,0,0]
	v_pk_fma_f32 v[26:27], v[140:141], v[74:75], v[132:133] op_sel_hi:[0,1,1] neg_lo:[1,0,0] neg_hi:[1,0,0]
	v_pk_fma_f32 v[28:29], v[140:141], v[76:77], v[134:135] op_sel_hi:[0,1,1] neg_lo:[1,0,0] neg_hi:[1,0,0]
	ds_read_b128 v[70:73], v112 offset:11776
	ds_read_b128 v[74:77], v112 offset:11792
	ds_write_b32 v108, v142 offset:24064
	s_waitcnt lgkmcnt(8)
	v_pk_mul_f32 v[136:137], v[22:23], v[30:31]
	v_pk_mul_f32 v[138:139], v[22:23], v[96:97]
	v_pk_fma_f32 v[136:137], v[24:25], v[32:33], v[136:137]
	v_pk_fma_f32 v[138:139], v[24:25], v[98:99], v[138:139]
	v_pk_fma_f32 v[136:137], v[26:27], v[34:35], v[136:137]
	v_pk_fma_f32 v[138:139], v[26:27], v[100:101], v[138:139]
	v_pk_fma_f32 v[136:137], v[28:29], v[36:37], v[136:137]
	v_pk_fma_f32 v[138:139], v[28:29], v[102:103], v[138:139]
	ds_read_b128 v[30:33], v112 offset:3840
	ds_read_b128 v[34:37], v112 offset:3856
	ds_read_b128 v[96:99], v112 offset:19968
	ds_read_b128 v[100:103], v112 offset:19984
	v_add_f32_e32 v140, v136, v137
	v_add_f32_e32 v142, v138, v139
	s_waitcnt lgkmcnt(9)
	v_pk_mul_f32 v[128:129], v[78:79], v[104:105] op_sel_hi:[1,0]
	v_add_f32_dpp v140, v140, v140 row_half_mirror row_mask:0xf bank_mask:0xf
	v_add_f32_dpp v142, v142, v142 row_half_mirror row_mask:0xf bank_mask:0xf
	v_pk_mul_f32 v[130:131], v[80:81], v[104:105] op_sel_hi:[1,0]
	v_pk_mul_f32 v[132:133], v[82:83], v[104:105] op_sel_hi:[1,0]
	v_add_f32_dpp v140, v140, v140 quad_perm:[1,0,3,2] row_mask:0xf bank_mask:0xf
	v_add_f32_dpp v142, v142, v142 quad_perm:[1,0,3,2] row_mask:0xf bank_mask:0xf
	v_pk_mul_f32 v[134:135], v[84:85], v[104:105] op_sel_hi:[1,0]
	ds_read_b128 v[78:81], v112 offset:16128
	ds_read_b128 v[82:85], v112 offset:16144
	ds_read_b32 v104, v108 offset:22400
	s_waitcnt lgkmcnt(10)
	v_pk_fma_f32 v[128:129], v[22:23], v[38:39], v[128:129]
	v_add_f32_dpp v140, v140, v140 quad_perm:[2,3,0,1] row_mask:0xf bank_mask:0xf
	v_add_f32_dpp v142, v142, v142 quad_perm:[2,3,0,1] row_mask:0xf bank_mask:0xf
	v_pk_fma_f32 v[130:131], v[24:25], v[40:41], v[130:131]
	v_pk_fma_f32 v[132:133], v[26:27], v[42:43], v[132:133]
	v_pk_fma_f32 v[134:135], v[28:29], v[44:45], v[134:135]
	ds_read_b128 v[38:41], v112 offset:7936
	ds_read_b128 v[42:45], v112 offset:7952
	s_waitcnt lgkmcnt(10)
	v_pk_fma_f32 v[22:23], v[140:141], v[70:71], v[128:129] op_sel_hi:[0,1,1] neg_lo:[1,0,0] neg_hi:[1,0,0]
	v_pk_fma_f32 v[24:25], v[140:141], v[72:73], v[130:131] op_sel_hi:[0,1,1] neg_lo:[1,0,0] neg_hi:[1,0,0]
	v_pk_fma_f32 v[26:27], v[140:141], v[74:75], v[132:133] op_sel_hi:[0,1,1] neg_lo:[1,0,0] neg_hi:[1,0,0]
	v_pk_fma_f32 v[28:29], v[140:141], v[76:77], v[134:135] op_sel_hi:[0,1,1] neg_lo:[1,0,0] neg_hi:[1,0,0]
	ds_read_b128 v[70:73], v112 offset:12032
	ds_read_b128 v[74:77], v112 offset:12048
	ds_write_b32 v108, v142 offset:24192
	s_waitcnt lgkmcnt(8)
	v_pk_mul_f32 v[136:137], v[22:23], v[30:31]
	v_pk_mul_f32 v[138:139], v[22:23], v[96:97]
	v_pk_fma_f32 v[136:137], v[24:25], v[32:33], v[136:137]
	v_pk_fma_f32 v[138:139], v[24:25], v[98:99], v[138:139]
	v_pk_fma_f32 v[136:137], v[26:27], v[34:35], v[136:137]
	v_pk_fma_f32 v[138:139], v[26:27], v[100:101], v[138:139]
	v_pk_fma_f32 v[136:137], v[28:29], v[36:37], v[136:137]
	v_pk_fma_f32 v[138:139], v[28:29], v[102:103], v[138:139]
	ds_read_b128 v[96:99], v112 offset:20224
	ds_read_b128 v[100:103], v112 offset:20240
	v_add_f32_e32 v140, v136, v137
	v_add_f32_e32 v142, v138, v139
	s_waitcnt lgkmcnt(7)
	v_pk_mul_f32 v[128:129], v[78:79], v[104:105] op_sel_hi:[1,0]
	v_add_f32_dpp v140, v140, v140 row_half_mirror row_mask:0xf bank_mask:0xf
	v_add_f32_dpp v142, v142, v142 row_half_mirror row_mask:0xf bank_mask:0xf
	v_pk_mul_f32 v[130:131], v[80:81], v[104:105] op_sel_hi:[1,0]
	v_pk_mul_f32 v[132:133], v[82:83], v[104:105] op_sel_hi:[1,0]
	v_add_f32_dpp v140, v140, v140 quad_perm:[1,0,3,2] row_mask:0xf bank_mask:0xf
	v_add_f32_dpp v142, v142, v142 quad_perm:[1,0,3,2] row_mask:0xf bank_mask:0xf
	v_pk_mul_f32 v[134:135], v[84:85], v[104:105] op_sel_hi:[1,0]
	s_waitcnt lgkmcnt(5)
	v_pk_fma_f32 v[128:129], v[22:23], v[38:39], v[128:129]
	v_add_f32_dpp v140, v140, v140 quad_perm:[2,3,0,1] row_mask:0xf bank_mask:0xf
	v_add_f32_dpp v142, v142, v142 quad_perm:[2,3,0,1] row_mask:0xf bank_mask:0xf
	v_pk_fma_f32 v[130:131], v[24:25], v[40:41], v[130:131]
	v_pk_fma_f32 v[132:133], v[26:27], v[42:43], v[132:133]
	v_pk_fma_f32 v[134:135], v[28:29], v[44:45], v[134:135]
	s_waitcnt lgkmcnt(3)
	v_pk_fma_f32 v[22:23], v[140:141], v[70:71], v[128:129] op_sel_hi:[0,1,1] neg_lo:[1,0,0] neg_hi:[1,0,0]
	v_pk_fma_f32 v[24:25], v[140:141], v[72:73], v[130:131] op_sel_hi:[0,1,1] neg_lo:[1,0,0] neg_hi:[1,0,0]
	v_pk_fma_f32 v[26:27], v[140:141], v[74:75], v[132:133] op_sel_hi:[0,1,1] neg_lo:[1,0,0] neg_hi:[1,0,0]
	v_pk_fma_f32 v[28:29], v[140:141], v[76:77], v[134:135] op_sel_hi:[0,1,1] neg_lo:[1,0,0] neg_hi:[1,0,0]
	ds_write_b32 v108, v142 offset:24320
	s_waitcnt lgkmcnt(1)
	v_pk_mul_f32 v[138:139], v[22:23], v[96:97]
	v_pk_fma_f32 v[138:139], v[24:25], v[98:99], v[138:139]
	v_pk_fma_f32 v[138:139], v[26:27], v[100:101], v[138:139]
	v_pk_fma_f32 v[138:139], v[28:29], v[102:103], v[138:139]
	v_add_f32_e32 v142, v138, v139
	s_nop 1
	v_add_f32_dpp v142, v142, v142 row_half_mirror row_mask:0xf bank_mask:0xf
	s_nop 1
	v_add_f32_dpp v142, v142, v142 quad_perm:[1,0,3,2] row_mask:0xf bank_mask:0xf
	s_nop 1
	v_add_f32_dpp v142, v142, v142 quad_perm:[2,3,0,1] row_mask:0xf bank_mask:0xf
	ds_write_b32 v108, v142 offset:24448
	s_branch .Lrw0_u2e0
.Lrw0_u2s0:
	ds_read_b128 v[30:33], v112 offset:0
	ds_read_b128 v[34:37], v112 offset:16
	ds_read_b128 v[38:41], v112 offset:4096
	ds_read_b128 v[42:45], v112 offset:4112
	ds_read_b128 v[70:73], v112 offset:8192
	ds_read_b128 v[74:77], v112 offset:8208
	s_waitcnt lgkmcnt(4)
	v_pk_mul_f32 v[136:137], v[22:23], v[30:31]
	v_pk_fma_f32 v[136:137], v[24:25], v[32:33], v[136:137]
	v_pk_fma_f32 v[136:137], v[26:27], v[34:35], v[136:137]
	v_pk_fma_f32 v[136:137], v[28:29], v[36:37], v[136:137]
	ds_read_b128 v[30:33], v112 offset:256
	ds_read_b128 v[34:37], v112 offset:272
	ds_read_b128 v[96:99], v112 offset:16384
	ds_read_b128 v[100:103], v112 offset:16400
	v_add_f32_e32 v140, v136, v137
	s_waitcnt lgkmcnt(6)
	v_pk_mul_f32 v[128:129], v[22:23], v[38:39]
	v_add_f32_dpp v140, v140, v140 row_half_mirror row_mask:0xf bank_mask:0xf
	v_pk_mul_f32 v[130:131], v[24:25], v[40:41]
	v_pk_mul_f32 v[132:133], v[26:27], v[42:43]
	v_pk_mul_f32 v[134:135], v[28:29], v[44:45]
	ds_read_b128 v[38:41], v112 offset:4352
	ds_read_b128 v[42:45], v112 offset:4368
	v_add_f32_dpp v140, v140, v140 quad_perm:[1,0,3,2] row_mask:0xf bank_mask:0xf
	s_nop 1
	v_add_f32_dpp v140, v140, v140 quad_perm:[2,3,0,1] row_mask:0xf bank_mask:0xf
	s_waitcnt lgkmcnt(6)
	v_pk_fma_f32 v[22:23], v[140:141], v[70:71], v[128:129] op_sel_hi:[0,1,1] neg_lo:[1,0,0] neg_hi:[1,0,0]
	v_pk_fma_f32 v[24:25], v[140:141], v[72:73], v[130:131] op_sel_hi:[0,1,1] neg_lo:[1,0,0] neg_hi:[1,0,0]
	v_pk_fma_f32 v[26:27], v[140:141], v[74:75], v[132:133] op_sel_hi:[0,1,1] neg_lo:[1,0,0] neg_hi:[1,0,0]
	v_pk_fma_f32 v[28:29], v[140:141], v[76:77], v[134:135] op_sel_hi:[0,1,1] neg_lo:[1,0,0] neg_hi:[1,0,0]
	ds_read_b128 v[70:73], v112 offset:8448
	ds_read_b128 v[74:77], v112 offset:8464
	s_waitcnt lgkmcnt(4)
	v_pk_mul_f32 v[136:137], v[22:23], v[30:31]
	v_pk_mul_f32 v[138:139], v[22:23], v[96:97]
	v_pk_fma_f32 v[136:137], v[24:25], v[32:33], v[136:137]
	v_pk_fma_f32 v[138:139], v[24:25], v[98:99], v[138:139]
	v_pk_fma_f32 v[136:137], v[26:27], v[34:35], v[136:137]
	v_pk_fma_f32 v[138:139], v[26:27], v[100:101], v[138:139]
	v_pk_fma_f32 v[136:137], v[28:29], v[36:37], v[136:137]
	v_pk_fma_f32 v[138:139], v[28:29], v[102:103], v[138:139]
	ds_read_b128 v[30:33], v112 offset:512
	ds_read_b128 v[34:37], v112 offset:528
	ds_read_b128 v[96:99], v112 offset:16640
	ds_read_b128 v[100:103], v112 offset:16656
	v_add_f32_e32 v140, v136, v137
	v_add_f32_e32 v142, v138, v139
	s_waitcnt lgkmcnt(6)
	v_pk_mul_f32 v[128:129], v[22:23], v[38:39]
	v_add_f32_dpp v140, v140, v140 row_half_mirror row_mask:0xf bank_mask:0xf
	v_add_f32_dpp v142, v142, v142 row_half_mirror row_mask:0xf bank_mask:0xf
	v_pk_mul_f32 v[130:131], v[24:25], v[40:41]
	v_pk_mul_f32 v[132:133], v[26:27], v[42:43]
	v_add_f32_dpp v140, v140, v140 quad_perm:[1,0,3,2] row_mask:0xf bank_mask:0xf
	v_add_f32_dpp v142, v142, v142 quad_perm:[1,0,3,2] row_mask:0xf bank_mask:0xf
	v_pk_mul_f32 v[134:135], v[28:29], v[44:45]
	ds_read_b128 v[38:41], v112 offset:4608
	ds_read_b128 v[42:45], v112 offset:4624
	v_add_f32_dpp v140, v140, v140 quad_perm:[2,3,0,1] row_mask:0xf bank_mask:0xf
	v_add_f32_dpp v142, v142, v142 quad_perm:[2,3,0,1] row_mask:0xf bank_mask:0xf
	s_waitcnt lgkmcnt(6)
	v_pk_fma_f32 v[22:23], v[140:141], v[70:71], v[128:129] op_sel_hi:[0,1,1] neg_lo:[1,0,0] neg_hi:[1,0,0]
	v_pk_fma_f32 v[24:25], v[140:141], v[72:73], v[130:131] op_sel_hi:[0,1,1] neg_lo:[1,0,0] neg_hi:[1,0,0]
	v_pk_fma_f32 v[26:27], v[140:141], v[74:75], v[132:133] op_sel_hi:[0,1,1] neg_lo:[1,0,0] neg_hi:[1,0,0]
	v_pk_fma_f32 v[28:29], v[140:141], v[76:77], v[134:135] op_sel_hi:[0,1,1] neg_lo:[1,0,0] neg_hi:[1,0,0]
	ds_read_b128 v[70:73], v112 offset:8704
	ds_read_b128 v[74:77], v112 offset:8720
	ds_write_b32 v108, v142 offset:22528
	s_waitcnt lgkmcnt(5)
	v_pk_mul_f32 v[136:137], v[22:23], v[30:31]
	v_pk_mul_f32 v[138:139], v[22:23], v[96:97]
	v_pk_fma_f32 v[136:137], v[24:25], v[32:33], v[136:137]
	v_pk_fma_f32 v[138:139], v[24:25], v[98:99], v[138:139]
	v_pk_fma_f32 v[136:137], v[26:27], v[34:35], v[136:137]
	v_pk_fma_f32 v[138:139], v[26:27], v[100:101], v[138:139]
	v_pk_fma_f32 v[136:137], v[28:29], v[36:37], v[136:137]
	v_pk_fma_f32 v[138:139], v[28:29], v[102:103], v[138:139]
	ds_read_b128 v[30:33], v112 offset:768
	ds_read_b128 v[34:37], v112 offset:784
	ds_read_b128 v[96:99], v112 offset:16896
	ds_read_b128 v[100:103], v112 offset:16912
	v_add_f32_e32 v140, v136, v137
	v_add_f32_e32 v142, v138, v139
	s_waitcnt lgkmcnt(7)
	v_pk_mul_f32 v[128:129], v[22:23], v[38:39]
	v_add_f32_dpp v140, v140, v140 row_half_mirror row_mask:0xf bank_mask:0xf
	v_add_f32_dpp v142, v142, v142 row_half_mirror row_mask:0xf bank_mask:0xf
	v_pk_mul_f32 v[130:131], v[24:25], v[40:41]
	v_pk_mul_f32 v[132:133], v[26:27], v[42:43]
	v_add_f32_dpp v140, v140, v140 quad_perm:[1,0,3,2] row_mask:0xf bank_mask:0xf
	v_add_f32_dpp v142, v142, v142 quad_perm:[1,0,3,2] row_mask:0xf bank_mask:0xf
	v_pk_mul_f32 v[134:135], v[28:29], v[44:45]
	ds_read_b128 v[38:41], v112 offset:4864
	ds_read_b128 v[42:45], v112 offset:4880
	v_add_f32_dpp v140, v140, v140 quad_perm:[2,3,0,1] row_mask:0xf bank_mask:0xf
	v_add_f32_dpp v142, v142, v142 quad_perm:[2,3,0,1] row_mask:0xf bank_mask:0xf
	s_waitcnt lgkmcnt(7)
	v_pk_fma_f32 v[22:23], v[140:141], v[70:71], v[128:129] op_sel_hi:[0,1,1] neg_lo:[1,0,0] neg_hi:[1,0,0]
	v_pk_fma_f32 v[24:25], v[140:141], v[72:73], v[130:131] op_sel_hi:[0,1,1] neg_lo:[1,0,0] neg_hi:[1,0,0]
	v_pk_fma_f32 v[26:27], v[140:141], v[74:75], v[132:133] op_sel_hi:[0,1,1] neg_lo:[1,0,0] neg_hi:[1,0,0]
	v_pk_fma_f32 v[28:29], v[140:141], v[76:77], v[134:135] op_sel_hi:[0,1,1] neg_lo:[1,0,0] neg_hi:[1,0,0]
	ds_read_b128 v[70:73], v112 offset:8960
	ds_read_b128 v[74:77], v112 offset:8976
	ds_write_b32 v108, v142 offset:22656
	s_waitcnt lgkmcnt(5)
	v_pk_mul_f32 v[136:137], v[22:23], v[30:31]
	v_pk_mul_f32 v[138:139], v[22:23], v[96:97]
	v_pk_fma_f32 v[136:137], v[24:25], v[32:33], v[136:137]
	v_pk_fma_f32 v[138:139], v[24:25], v[98:99], v[138:139]
	v_pk_fma_f32 v[136:137], v[26:27], v[34:35], v[136:137]
	v_pk_fma_f32 v[138:139], v[26:27], v[100:101], v[138:139]
	v_pk_fma_f32 v[136:137], v[28:29], v[36:37], v[136:137]
	v_pk_fma_f32 v[138:139], v[28:29], v[102:103], v[138:139]
	ds_read_b128 v[30:33], v112 offset:1024
	ds_read_b128 v[34:37], v112 offset:1040
	ds_read_b128 v[96:99], v112 offset:17152
	ds_read_b128 v[100:103], v112 offset:17168
	v_add_f32_e32 v140, v136, v137
	v_add_f32_e32 v142, v138, v139
	s_waitcnt lgkmcnt(7)
	v_pk_mul_f32 v[128:129], v[22:23], v[38:39]
	v_add_f32_dpp v140, v140, v140 row_half_mirror row_mask:0xf bank_mask:0xf
	v_add_f32_dpp v142, v142, v142 row_half_mirror row_mask:0xf bank_mask:0xf
	v_pk_mul_f32 v[130:131], v[24:25], v[40:41]
	v_pk_mul_f32 v[132:133], v[26:27], v[42:43]
	v_add_f32_dpp v140, v140, v140 quad_perm:[1,0,3,2] row_mask:0xf bank_mask:0xf
	v_add_f32_dpp v142, v142, v142 quad_perm:[1,0,3,2] row_mask:0xf bank_mask:0xf
	v_pk_mul_f32 v[134:135], v[28:29], v[44:45]
	ds_read_b128 v[38:41], v112 offset:5120
	ds_read_b128 v[42:45], v112 offset:5136
	v_add_f32_dpp v140, v140, v140 quad_perm:[2,3,0,1] row_mask:0xf bank_mask:0xf
	v_add_f32_dpp v142, v142, v142 quad_perm:[2,3,0,1] row_mask:0xf bank_mask:0xf
	s_waitcnt lgkmcnt(7)
	v_pk_fma_f32 v[22:23], v[140:141], v[70:71], v[128:129] op_sel_hi:[0,1,1] neg_lo:[1,0,0] neg_hi:[1,0,0]
	v_pk_fma_f32 v[24:25], v[140:141], v[72:73], v[130:131] op_sel_hi:[0,1,1] neg_lo:[1,0,0] neg_hi:[1,0,0]
	v_pk_fma_f32 v[26:27], v[140:141], v[74:75], v[132:133] op_sel_hi:[0,1,1] neg_lo:[1,0,0] neg_hi:[1,0,0]
	v_pk_fma_f32 v[28:29], v[140:141], v[76:77], v[134:135] op_sel_hi:[0,1,1] neg_lo:[1,0,0] neg_hi:[1,0,0]
	ds_read_b128 v[70:73], v112 offset:9216
	ds_read_b128 v[74:77], v112 offset:9232
	ds_write_b32 v108, v142 offset:22784
	s_waitcnt lgkmcnt(5)
	v_pk_mul_f32 v[136:137], v[22:23], v[30:31]
	v_pk_mul_f32 v[138:139], v[22:23], v[96:97]
	v_pk_fma_f32 v[136:137], v[24:25], v[32:33], v[136:137]
	v_pk_fma_f32 v[138:139], v[24:25], v[98:99], v[138:139]
	v_pk_fma_f32 v[136:137], v[26:27], v[34:35], v[136:137]
	v_pk_fma_f32 v[138:139], v[26:27], v[100:101], v[138:139]
	v_pk_fma_f32 v[136:137], v[28:29], v[36:37], v[136:137]
	v_pk_fma_f32 v[138:139], v[28:29], v[102:103], v[138:139]
	ds_read_b128 v[30:33], v112 offset:1280
	ds_read_b128 v[34:37], v112 offset:1296
	ds_read_b128 v[96:99], v112 offset:17408
	ds_read_b128 v[100:103], v112 offset:17424
	v_add_f32_e32 v140, v136, v137
	v_add_f32_e32 v142, v138, v139
	s_waitcnt lgkmcnt(7)
	v_pk_mul_f32 v[128:129], v[22:23], v[38:39]
	v_add_f32_dpp v140, v140, v140 row_half_mirror row_mask:0xf bank_mask:0xf
	v_add_f32_dpp v142, v142, v142 row_half_mirror row_mask:0xf bank_mask:0xf
	v_pk_mul_f32 v[130:131], v[24:25], v[40:41]
	v_pk_mul_f32 v[132:133], v[26:27], v[42:43]
	v_add_f32_dpp v140, v140, v140 quad_perm:[1,0,3,2] row_mask:0xf bank_mask:0xf
	v_add_f32_dpp v142, v142, v142 quad_perm:[1,0,3,2] row_mask:0xf bank_mask:0xf
	v_pk_mul_f32 v[134:135], v[28:29], v[44:45]
	ds_read_b128 v[38:41], v112 offset:5376
	ds_read_b128 v[42:45], v112 offset:5392
	v_add_f32_dpp v140, v140, v140 quad_perm:[2,3,0,1] row_mask:0xf bank_mask:0xf
	v_add_f32_dpp v142, v142, v142 quad_perm:[2,3,0,1] row_mask:0xf bank_mask:0xf
	s_waitcnt lgkmcnt(7)
	v_pk_fma_f32 v[22:23], v[140:141], v[70:71], v[128:129] op_sel_hi:[0,1,1] neg_lo:[1,0,0] neg_hi:[1,0,0]
	v_pk_fma_f32 v[24:25], v[140:141], v[72:73], v[130:131] op_sel_hi:[0,1,1] neg_lo:[1,0,0] neg_hi:[1,0,0]
	v_pk_fma_f32 v[26:27], v[140:141], v[74:75], v[132:133] op_sel_hi:[0,1,1] neg_lo:[1,0,0] neg_hi:[1,0,0]
	v_pk_fma_f32 v[28:29], v[140:141], v[76:77], v[134:135] op_sel_hi:[0,1,1] neg_lo:[1,0,0] neg_hi:[1,0,0]
	ds_read_b128 v[70:73], v112 offset:9472
	ds_read_b128 v[74:77], v112 offset:9488
	ds_write_b32 v108, v142 offset:22912
	s_waitcnt lgkmcnt(5)
	v_pk_mul_f32 v[136:137], v[22:23], v[30:31]
	v_pk_mul_f32 v[138:139], v[22:23], v[96:97]
	v_pk_fma_f32 v[136:137], v[24:25], v[32:33], v[136:137]
	v_pk_fma_f32 v[138:139], v[24:25], v[98:99], v[138:139]
	v_pk_fma_f32 v[136:137], v[26:27], v[34:35], v[136:137]
	v_pk_fma_f32 v[138:139], v[26:27], v[100:101], v[138:139]
	v_pk_fma_f32 v[136:137], v[28:29], v[36:37], v[136:137]
	v_pk_fma_f32 v[138:139], v[28:29], v[102:103], v[138:139]
	ds_read_b128 v[30:33], v112 offset:1536
	ds_read_b128 v[34:37], v112 offset:1552
	ds_read_b128 v[96:99], v112 offset:17664
	ds_read_b128 v[100:103], v112 offset:17680
	v_add_f32_e32 v140, v136, v137
	v_add_f32_e32 v142, v138, v139
	s_waitcnt lgkmcnt(7)
	v_pk_mul_f32 v[128:129], v[22:23], v[38:39]
	v_add_f32_dpp v140, v140, v140 row_half_mirror row_mask:0xf bank_mask:0xf
	v_add_f32_dpp v142, v142, v142 row_half_mirror row_mask:0xf bank_mask:0xf
	v_pk_mul_f32 v[130:131], v[24:25], v[40:41]
	v_pk_mul_f32 v[132:133], v[26:27], v[42:43]
	v_add_f32_dpp v140, v140, v140 quad_perm:[1,0,3,2] row_mask:0xf bank_mask:0xf
	v_add_f32_dpp v142, v142, v142 quad_perm:[1,0,3,2] row_mask:0xf bank_mask:0xf
	v_pk_mul_f32 v[134:135], v[28:29], v[44:45]
	ds_read_b128 v[38:41], v112 offset:5632
	ds_read_b128 v[42:45], v112 offset:5648
	v_add_f32_dpp v140, v140, v140 quad_perm:[2,3,0,1] row_mask:0xf bank_mask:0xf
	v_add_f32_dpp v142, v142, v142 quad_perm:[2,3,0,1] row_mask:0xf bank_mask:0xf
	s_waitcnt lgkmcnt(7)
	v_pk_fma_f32 v[22:23], v[140:141], v[70:71], v[128:129] op_sel_hi:[0,1,1] neg_lo:[1,0,0] neg_hi:[1,0,0]
	v_pk_fma_f32 v[24:25], v[140:141], v[72:73], v[130:131] op_sel_hi:[0,1,1] neg_lo:[1,0,0] neg_hi:[1,0,0]
	v_pk_fma_f32 v[26:27], v[140:141], v[74:75], v[132:133] op_sel_hi:[0,1,1] neg_lo:[1,0,0] neg_hi:[1,0,0]
	v_pk_fma_f32 v[28:29], v[140:141], v[76:77], v[134:135] op_sel_hi:[0,1,1] neg_lo:[1,0,0] neg_hi:[1,0,0]
	ds_read_b128 v[70:73], v112 offset:9728
	ds_read_b128 v[74:77], v112 offset:9744
	ds_write_b32 v108, v142 offset:23040
	s_waitcnt lgkmcnt(5)
	v_pk_mul_f32 v[136:137], v[22:23], v[30:31]
	v_pk_mul_f32 v[138:139], v[22:23], v[96:97]
	v_pk_fma_f32 v[136:137], v[24:25], v[32:33], v[136:137]
	v_pk_fma_f32 v[138:139], v[24:25], v[98:99], v[138:139]
	v_pk_fma_f32 v[136:137], v[26:27], v[34:35], v[136:137]
	v_pk_fma_f32 v[138:139], v[26:27], v[100:101], v[138:139]
	v_pk_fma_f32 v[136:137], v[28:29], v[36:37], v[136:137]
	v_pk_fma_f32 v[138:139], v[28:29], v[102:103], v[138:139]
	ds_read_b128 v[30:33], v112 offset:1792
	ds_read_b128 v[34:37], v112 offset:1808
	ds_read_b128 v[96:99], v112 offset:17920
	ds_read_b128 v[100:103], v112 offset:17936
	v_add_f32_e32 v140, v136, v137
	v_add_f32_e32 v142, v138, v139
	s_waitcnt lgkmcnt(7)
	v_pk_mul_f32 v[128:129], v[22:23], v[38:39]
	v_add_f32_dpp v140, v140, v140 row_half_mirror row_mask:0xf bank_mask:0xf
	v_add_f32_dpp v142, v142, v142 row_half_mirror row_mask:0xf bank_mask:0xf
	v_pk_mul_f32 v[130:131], v[24:25], v[40:41]
	v_pk_mul_f32 v[132:133], v[26:27], v[42:43]
	v_add_f32_dpp v140, v140, v140 quad_perm:[1,0,3,2] row_mask:0xf bank_mask:0xf
	v_add_f32_dpp v142, v142, v142 quad_perm:[1,0,3,2] row_mask:0xf bank_mask:0xf
	v_pk_mul_f32 v[134:135], v[28:29], v[44:45]
	ds_read_b128 v[38:41], v112 offset:5888
	ds_read_b128 v[42:45], v112 offset:5904
	v_add_f32_dpp v140, v140, v140 quad_perm:[2,3,0,1] row_mask:0xf bank_mask:0xf
	v_add_f32_dpp v142, v142, v142 quad_perm:[2,3,0,1] row_mask:0xf bank_mask:0xf
	s_waitcnt lgkmcnt(7)
	v_pk_fma_f32 v[22:23], v[140:141], v[70:71], v[128:129] op_sel_hi:[0,1,1] neg_lo:[1,0,0] neg_hi:[1,0,0]
	v_pk_fma_f32 v[24:25], v[140:141], v[72:73], v[130:131] op_sel_hi:[0,1,1] neg_lo:[1,0,0] neg_hi:[1,0,0]
	v_pk_fma_f32 v[26:27], v[140:141], v[74:75], v[132:133] op_sel_hi:[0,1,1] neg_lo:[1,0,0] neg_hi:[1,0,0]
	v_pk_fma_f32 v[28:29], v[140:141], v[76:77], v[134:135] op_sel_hi:[0,1,1] neg_lo:[1,0,0] neg_hi:[1,0,0]
	ds_read_b128 v[70:73], v112 offset:9984
	ds_read_b128 v[74:77], v112 offset:10000
	ds_write_b32 v108, v142 offset:23168
	s_waitcnt lgkmcnt(5)
	v_pk_mul_f32 v[136:137], v[22:23], v[30:31]
	v_pk_mul_f32 v[138:139], v[22:23], v[96:97]
	v_pk_fma_f32 v[136:137], v[24:25], v[32:33], v[136:137]
	v_pk_fma_f32 v[138:139], v[24:25], v[98:99], v[138:139]
	v_pk_fma_f32 v[136:137], v[26:27], v[34:35], v[136:137]
	v_pk_fma_f32 v[138:139], v[26:27], v[100:101], v[138:139]
	v_pk_fma_f32 v[136:137], v[28:29], v[36:37], v[136:137]
	v_pk_fma_f32 v[138:139], v[28:29], v[102:103], v[138:139]
	ds_read_b128 v[30:33], v112 offset:2048
	ds_read_b128 v[34:37], v112 offset:2064
	ds_read_b128 v[96:99], v112 offset:18176
	ds_read_b128 v[100:103], v112 offset:18192
	v_add_f32_e32 v140, v136, v137
	v_add_f32_e32 v142, v138, v139
	s_waitcnt lgkmcnt(7)
	v_pk_mul_f32 v[128:129], v[22:23], v[38:39]
	v_add_f32_dpp v140, v140, v140 row_half_mirror row_mask:0xf bank_mask:0xf
	v_add_f32_dpp v142, v142, v142 row_half_mirror row_mask:0xf bank_mask:0xf
	v_pk_mul_f32 v[130:131], v[24:25], v[40:41]
	v_pk_mul_f32 v[132:133], v[26:27], v[42:43]
	v_add_f32_dpp v140, v140, v140 quad_perm:[1,0,3,2] row_mask:0xf bank_mask:0xf
	v_add_f32_dpp v142, v142, v142 quad_perm:[1,0,3,2] row_mask:0xf bank_mask:0xf
	v_pk_mul_f32 v[134:135], v[28:29], v[44:45]
	ds_read_b128 v[38:41], v112 offset:6144
	ds_read_b128 v[42:45], v112 offset:6160
	v_add_f32_dpp v140, v140, v140 quad_perm:[2,3,0,1] row_mask:0xf bank_mask:0xf
	v_add_f32_dpp v142, v142, v142 quad_perm:[2,3,0,1] row_mask:0xf bank_mask:0xf
	s_waitcnt lgkmcnt(7)
	v_pk_fma_f32 v[22:23], v[140:141], v[70:71], v[128:129] op_sel_hi:[0,1,1] neg_lo:[1,0,0] neg_hi:[1,0,0]
	v_pk_fma_f32 v[24:25], v[140:141], v[72:73], v[130:131] op_sel_hi:[0,1,1] neg_lo:[1,0,0] neg_hi:[1,0,0]
	v_pk_fma_f32 v[26:27], v[140:141], v[74:75], v[132:133] op_sel_hi:[0,1,1] neg_lo:[1,0,0] neg_hi:[1,0,0]
	v_pk_fma_f32 v[28:29], v[140:141], v[76:77], v[134:135] op_sel_hi:[0,1,1] neg_lo:[1,0,0] neg_hi:[1,0,0]
	ds_read_b128 v[70:73], v112 offset:10240
	ds_read_b128 v[74:77], v112 offset:10256
	ds_write_b32 v108, v142 offset:23296
	s_waitcnt lgkmcnt(5)
	v_pk_mul_f32 v[136:137], v[22:23], v[30:31]
	v_pk_mul_f32 v[138:139], v[22:23], v[96:97]
	v_pk_fma_f32 v[136:137], v[24:25], v[32:33], v[136:137]
	v_pk_fma_f32 v[138:139], v[24:25], v[98:99], v[138:139]
	v_pk_fma_f32 v[136:137], v[26:27], v[34:35], v[136:137]
	v_pk_fma_f32 v[138:139], v[26:27], v[100:101], v[138:139]
	v_pk_fma_f32 v[136:137], v[28:29], v[36:37], v[136:137]
	v_pk_fma_f32 v[138:139], v[28:29], v[102:103], v[138:139]
	ds_read_b128 v[30:33], v112 offset:2304
	ds_read_b128 v[34:37], v112 offset:2320
	ds_read_b128 v[96:99], v112 offset:18432
	ds_read_b128 v[100:103], v112 offset:18448
	v_add_f32_e32 v140, v136, v137
	v_add_f32_e32 v142, v138, v139
	s_waitcnt lgkmcnt(7)
	v_pk_mul_f32 v[128:129], v[22:23], v[38:39]
	v_add_f32_dpp v140, v140, v140 row_half_mirror row_mask:0xf bank_mask:0xf
	v_add_f32_dpp v142, v142, v142 row_half_mirror row_mask:0xf bank_mask:0xf
	v_pk_mul_f32 v[130:131], v[24:25], v[40:41]
	v_pk_mul_f32 v[132:133], v[26:27], v[42:43]
	v_add_f32_dpp v140, v140, v140 quad_perm:[1,0,3,2] row_mask:0xf bank_mask:0xf
	v_add_f32_dpp v142, v142, v142 quad_perm:[1,0,3,2] row_mask:0xf bank_mask:0xf
	v_pk_mul_f32 v[134:135], v[28:29], v[44:45]
	ds_read_b128 v[38:41], v112 offset:6400
	ds_read_b128 v[42:45], v112 offset:6416
	v_add_f32_dpp v140, v140, v140 quad_perm:[2,3,0,1] row_mask:0xf bank_mask:0xf
	v_add_f32_dpp v142, v142, v142 quad_perm:[2,3,0,1] row_mask:0xf bank_mask:0xf
	s_waitcnt lgkmcnt(7)
	v_pk_fma_f32 v[22:23], v[140:141], v[70:71], v[128:129] op_sel_hi:[0,1,1] neg_lo:[1,0,0] neg_hi:[1,0,0]
	v_pk_fma_f32 v[24:25], v[140:141], v[72:73], v[130:131] op_sel_hi:[0,1,1] neg_lo:[1,0,0] neg_hi:[1,0,0]
	v_pk_fma_f32 v[26:27], v[140:141], v[74:75], v[132:133] op_sel_hi:[0,1,1] neg_lo:[1,0,0] neg_hi:[1,0,0]
	v_pk_fma_f32 v[28:29], v[140:141], v[76:77], v[134:135] op_sel_hi:[0,1,1] neg_lo:[1,0,0] neg_hi:[1,0,0]
	ds_read_b128 v[70:73], v112 offset:10496
	ds_read_b128 v[74:77], v112 offset:10512
	ds_write_b32 v108, v142 offset:23424
	s_waitcnt lgkmcnt(5)
	v_pk_mul_f32 v[136:137], v[22:23], v[30:31]
	v_pk_mul_f32 v[138:139], v[22:23], v[96:97]
	v_pk_fma_f32 v[136:137], v[24:25], v[32:33], v[136:137]
	v_pk_fma_f32 v[138:139], v[24:25], v[98:99], v[138:139]
	v_pk_fma_f32 v[136:137], v[26:27], v[34:35], v[136:137]
	v_pk_fma_f32 v[138:139], v[26:27], v[100:101], v[138:139]
	v_pk_fma_f32 v[136:137], v[28:29], v[36:37], v[136:137]
	v_pk_fma_f32 v[138:139], v[28:29], v[102:103], v[138:139]
	ds_read_b128 v[30:33], v112 offset:2560
	ds_read_b128 v[34:37], v112 offset:2576
	ds_read_b128 v[96:99], v112 offset:18688
	ds_read_b128 v[100:103], v112 offset:18704
	v_add_f32_e32 v140, v136, v137
	v_add_f32_e32 v142, v138, v139
	s_waitcnt lgkmcnt(7)
	v_pk_mul_f32 v[128:129], v[22:23], v[38:39]
	v_add_f32_dpp v140, v140, v140 row_half_mirror row_mask:0xf bank_mask:0xf
	v_add_f32_dpp v142, v142, v142 row_half_mirror row_mask:0xf bank_mask:0xf
	v_pk_mul_f32 v[130:131], v[24:25], v[40:41]
	v_pk_mul_f32 v[132:133], v[26:27], v[42:43]
	v_add_f32_dpp v140, v140, v140 quad_perm:[1,0,3,2] row_mask:0xf bank_mask:0xf
	v_add_f32_dpp v142, v142, v142 quad_perm:[1,0,3,2] row_mask:0xf bank_mask:0xf
	v_pk_mul_f32 v[134:135], v[28:29], v[44:45]
	ds_read_b128 v[38:41], v112 offset:6656
	ds_read_b128 v[42:45], v112 offset:6672
	v_add_f32_dpp v140, v140, v140 quad_perm:[2,3,0,1] row_mask:0xf bank_mask:0xf
	v_add_f32_dpp v142, v142, v142 quad_perm:[2,3,0,1] row_mask:0xf bank_mask:0xf
	s_waitcnt lgkmcnt(7)
	v_pk_fma_f32 v[22:23], v[140:141], v[70:71], v[128:129] op_sel_hi:[0,1,1] neg_lo:[1,0,0] neg_hi:[1,0,0]
	v_pk_fma_f32 v[24:25], v[140:141], v[72:73], v[130:131] op_sel_hi:[0,1,1] neg_lo:[1,0,0] neg_hi:[1,0,0]
	v_pk_fma_f32 v[26:27], v[140:141], v[74:75], v[132:133] op_sel_hi:[0,1,1] neg_lo:[1,0,0] neg_hi:[1,0,0]
	v_pk_fma_f32 v[28:29], v[140:141], v[76:77], v[134:135] op_sel_hi:[0,1,1] neg_lo:[1,0,0] neg_hi:[1,0,0]
	ds_read_b128 v[70:73], v112 offset:10752
	ds_read_b128 v[74:77], v112 offset:10768
	ds_write_b32 v108, v142 offset:23552
	s_waitcnt lgkmcnt(5)
	v_pk_mul_f32 v[136:137], v[22:23], v[30:31]
	v_pk_mul_f32 v[138:139], v[22:23], v[96:97]
	v_pk_fma_f32 v[136:137], v[24:25], v[32:33], v[136:137]
	v_pk_fma_f32 v[138:139], v[24:25], v[98:99], v[138:139]
	v_pk_fma_f32 v[136:137], v[26:27], v[34:35], v[136:137]
	v_pk_fma_f32 v[138:139], v[26:27], v[100:101], v[138:139]
	v_pk_fma_f32 v[136:137], v[28:29], v[36:37], v[136:137]
	v_pk_fma_f32 v[138:139], v[28:29], v[102:103], v[138:139]
	ds_read_b128 v[30:33], v112 offset:2816
	ds_read_b128 v[34:37], v112 offset:2832
	ds_read_b128 v[96:99], v112 offset:18944
	ds_read_b128 v[100:103], v112 offset:18960
	v_add_f32_e32 v140, v136, v137
	v_add_f32_e32 v142, v138, v139
	s_waitcnt lgkmcnt(7)
	v_pk_mul_f32 v[128:129], v[22:23], v[38:39]
	v_add_f32_dpp v140, v140, v140 row_half_mirror row_mask:0xf bank_mask:0xf
	v_add_f32_dpp v142, v142, v142 row_half_mirror row_mask:0xf bank_mask:0xf
	v_pk_mul_f32 v[130:131], v[24:25], v[40:41]
	v_pk_mul_f32 v[132:133], v[26:27], v[42:43]
	v_add_f32_dpp v140, v140, v140 quad_perm:[1,0,3,2] row_mask:0xf bank_mask:0xf
	v_add_f32_dpp v142, v142, v142 quad_perm:[1,0,3,2] row_mask:0xf bank_mask:0xf
	v_pk_mul_f32 v[134:135], v[28:29], v[44:45]
	ds_read_b128 v[38:41], v112 offset:6912
	ds_read_b128 v[42:45], v112 offset:6928
	v_add_f32_dpp v140, v140, v140 quad_perm:[2,3,0,1] row_mask:0xf bank_mask:0xf
	v_add_f32_dpp v142, v142, v142 quad_perm:[2,3,0,1] row_mask:0xf bank_mask:0xf
	s_waitcnt lgkmcnt(7)
	v_pk_fma_f32 v[22:23], v[140:141], v[70:71], v[128:129] op_sel_hi:[0,1,1] neg_lo:[1,0,0] neg_hi:[1,0,0]
	v_pk_fma_f32 v[24:25], v[140:141], v[72:73], v[130:131] op_sel_hi:[0,1,1] neg_lo:[1,0,0] neg_hi:[1,0,0]
	v_pk_fma_f32 v[26:27], v[140:141], v[74:75], v[132:133] op_sel_hi:[0,1,1] neg_lo:[1,0,0] neg_hi:[1,0,0]
	v_pk_fma_f32 v[28:29], v[140:141], v[76:77], v[134:135] op_sel_hi:[0,1,1] neg_lo:[1,0,0] neg_hi:[1,0,0]
	ds_read_b128 v[70:73], v112 offset:11008
	ds_read_b128 v[74:77], v112 offset:11024
	ds_write_b32 v108, v142 offset:23680
	s_waitcnt lgkmcnt(5)
	v_pk_mul_f32 v[136:137], v[22:23], v[30:31]
	v_pk_mul_f32 v[138:139], v[22:23], v[96:97]
	v_pk_fma_f32 v[136:137], v[24:25], v[32:33], v[136:137]
	v_pk_fma_f32 v[138:139], v[24:25], v[98:99], v[138:139]
	v_pk_fma_f32 v[136:137], v[26:27], v[34:35], v[136:137]
	v_pk_fma_f32 v[138:139], v[26:27], v[100:101], v[138:139]
	v_pk_fma_f32 v[136:137], v[28:29], v[36:37], v[136:137]
	v_pk_fma_f32 v[138:139], v[28:29], v[102:103], v[138:139]
	ds_read_b128 v[30:33], v112 offset:3072
	ds_read_b128 v[34:37], v112 offset:3088
	ds_read_b128 v[96:99], v112 offset:19200
	ds_read_b128 v[100:103], v112 offset:19216
	v_add_f32_e32 v140, v136, v137
	v_add_f32_e32 v142, v138, v139
	s_waitcnt lgkmcnt(7)
	v_pk_mul_f32 v[128:129], v[22:23], v[38:39]
	v_add_f32_dpp v140, v140, v140 row_half_mirror row_mask:0xf bank_mask:0xf
	v_add_f32_dpp v142, v142, v142 row_half_mirror row_mask:0xf bank_mask:0xf
	v_pk_mul_f32 v[130:131], v[24:25], v[40:41]
	v_pk_mul_f32 v[132:133], v[26:27], v[42:43]
	v_add_f32_dpp v140, v140, v140 quad_perm:[1,0,3,2] row_mask:0xf bank_mask:0xf
	v_add_f32_dpp v142, v142, v142 quad_perm:[1,0,3,2] row_mask:0xf bank_mask:0xf
	v_pk_mul_f32 v[134:135], v[28:29], v[44:45]
	ds_read_b128 v[38:41], v112 offset:7168
	ds_read_b128 v[42:45], v112 offset:7184
	v_add_f32_dpp v140, v140, v140 quad_perm:[2,3,0,1] row_mask:0xf bank_mask:0xf
	v_add_f32_dpp v142, v142, v142 quad_perm:[2,3,0,1] row_mask:0xf bank_mask:0xf
	s_waitcnt lgkmcnt(7)
	v_pk_fma_f32 v[22:23], v[140:141], v[70:71], v[128:129] op_sel_hi:[0,1,1] neg_lo:[1,0,0] neg_hi:[1,0,0]
	v_pk_fma_f32 v[24:25], v[140:141], v[72:73], v[130:131] op_sel_hi:[0,1,1] neg_lo:[1,0,0] neg_hi:[1,0,0]
	v_pk_fma_f32 v[26:27], v[140:141], v[74:75], v[132:133] op_sel_hi:[0,1,1] neg_lo:[1,0,0] neg_hi:[1,0,0]
	v_pk_fma_f32 v[28:29], v[140:141], v[76:77], v[134:135] op_sel_hi:[0,1,1] neg_lo:[1,0,0] neg_hi:[1,0,0]
	ds_read_b128 v[70:73], v112 offset:11264
	ds_read_b128 v[74:77], v112 offset:11280
	ds_write_b32 v108, v142 offset:23808
	s_waitcnt lgkmcnt(5)
	v_pk_mul_f32 v[136:137], v[22:23], v[30:31]
	v_pk_mul_f32 v[138:139], v[22:23], v[96:97]
	v_pk_fma_f32 v[136:137], v[24:25], v[32:33], v[136:137]
	v_pk_fma_f32 v[138:139], v[24:25], v[98:99], v[138:139]
	v_pk_fma_f32 v[136:137], v[26:27], v[34:35], v[136:137]
	v_pk_fma_f32 v[138:139], v[26:27], v[100:101], v[138:139]
	v_pk_fma_f32 v[136:137], v[28:29], v[36:37], v[136:137]
	v_pk_fma_f32 v[138:139], v[28:29], v[102:103], v[138:139]
	ds_read_b128 v[30:33], v112 offset:3328
	ds_read_b128 v[34:37], v112 offset:3344
	ds_read_b128 v[96:99], v112 offset:19456
	ds_read_b128 v[100:103], v112 offset:19472
	v_add_f32_e32 v140, v136, v137
	v_add_f32_e32 v142, v138, v139
	s_waitcnt lgkmcnt(7)
	v_pk_mul_f32 v[128:129], v[22:23], v[38:39]
	v_add_f32_dpp v140, v140, v140 row_half_mirror row_mask:0xf bank_mask:0xf
	v_add_f32_dpp v142, v142, v142 row_half_mirror row_mask:0xf bank_mask:0xf
	v_pk_mul_f32 v[130:131], v[24:25], v[40:41]
	v_pk_mul_f32 v[132:133], v[26:27], v[42:43]
	v_add_f32_dpp v140, v140, v140 quad_perm:[1,0,3,2] row_mask:0xf bank_mask:0xf
	v_add_f32_dpp v142, v142, v142 quad_perm:[1,0,3,2] row_mask:0xf bank_mask:0xf
	v_pk_mul_f32 v[134:135], v[28:29], v[44:45]
	ds_read_b128 v[38:41], v112 offset:7424
	ds_read_b128 v[42:45], v112 offset:7440
	v_add_f32_dpp v140, v140, v140 quad_perm:[2,3,0,1] row_mask:0xf bank_mask:0xf
	v_add_f32_dpp v142, v142, v142 quad_perm:[2,3,0,1] row_mask:0xf bank_mask:0xf
	s_waitcnt lgkmcnt(7)
	v_pk_fma_f32 v[22:23], v[140:141], v[70:71], v[128:129] op_sel_hi:[0,1,1] neg_lo:[1,0,0] neg_hi:[1,0,0]
	v_pk_fma_f32 v[24:25], v[140:141], v[72:73], v[130:131] op_sel_hi:[0,1,1] neg_lo:[1,0,0] neg_hi:[1,0,0]
	v_pk_fma_f32 v[26:27], v[140:141], v[74:75], v[132:133] op_sel_hi:[0,1,1] neg_lo:[1,0,0] neg_hi:[1,0,0]
	v_pk_fma_f32 v[28:29], v[140:141], v[76:77], v[134:135] op_sel_hi:[0,1,1] neg_lo:[1,0,0] neg_hi:[1,0,0]
	ds_read_b128 v[70:73], v112 offset:11520
	ds_read_b128 v[74:77], v112 offset:11536
	ds_write_b32 v108, v142 offset:23936
	s_waitcnt lgkmcnt(5)
	v_pk_mul_f32 v[136:137], v[22:23], v[30:31]
	v_pk_mul_f32 v[138:139], v[22:23], v[96:97]
	v_pk_fma_f32 v[136:137], v[24:25], v[32:33], v[136:137]
	v_pk_fma_f32 v[138:139], v[24:25], v[98:99], v[138:139]
	v_pk_fma_f32 v[136:137], v[26:27], v[34:35], v[136:137]
	v_pk_fma_f32 v[138:139], v[26:27], v[100:101], v[138:139]
	v_pk_fma_f32 v[136:137], v[28:29], v[36:37], v[136:137]
	v_pk_fma_f32 v[138:139], v[28:29], v[102:103], v[138:139]
	ds_read_b128 v[30:33], v112 offset:3584
	ds_read_b128 v[34:37], v112 offset:3600
	ds_read_b128 v[96:99], v112 offset:19712
	ds_read_b128 v[100:103], v112 offset:19728
	v_add_f32_e32 v140, v136, v137
	v_add_f32_e32 v142, v138, v139
	s_waitcnt lgkmcnt(7)
	v_pk_mul_f32 v[128:129], v[22:23], v[38:39]
	v_add_f32_dpp v140, v140, v140 row_half_mirror row_mask:0xf bank_mask:0xf
	v_add_f32_dpp v142, v142, v142 row_half_mirror row_mask:0xf bank_mask:0xf
	v_pk_mul_f32 v[130:131], v[24:25], v[40:41]
	v_pk_mul_f32 v[132:133], v[26:27], v[42:43]
	v_add_f32_dpp v140, v140, v140 quad_perm:[1,0,3,2] row_mask:0xf bank_mask:0xf
	v_add_f32_dpp v142, v142, v142 quad_perm:[1,0,3,2] row_mask:0xf bank_mask:0xf
	v_pk_mul_f32 v[134:135], v[28:29], v[44:45]
	ds_read_b128 v[38:41], v112 offset:7680
	ds_read_b128 v[42:45], v112 offset:7696
	v_add_f32_dpp v140, v140, v140 quad_perm:[2,3,0,1] row_mask:0xf bank_mask:0xf
	v_add_f32_dpp v142, v142, v142 quad_perm:[2,3,0,1] row_mask:0xf bank_mask:0xf
	s_waitcnt lgkmcnt(7)
	v_pk_fma_f32 v[22:23], v[140:141], v[70:71], v[128:129] op_sel_hi:[0,1,1] neg_lo:[1,0,0] neg_hi:[1,0,0]
	v_pk_fma_f32 v[24:25], v[140:141], v[72:73], v[130:131] op_sel_hi:[0,1,1] neg_lo:[1,0,0] neg_hi:[1,0,0]
	v_pk_fma_f32 v[26:27], v[140:141], v[74:75], v[132:133] op_sel_hi:[0,1,1] neg_lo:[1,0,0] neg_hi:[1,0,0]
	v_pk_fma_f32 v[28:29], v[140:141], v[76:77], v[134:135] op_sel_hi:[0,1,1] neg_lo:[1,0,0] neg_hi:[1,0,0]
	ds_read_b128 v[70:73], v112 offset:11776
	ds_read_b128 v[74:77], v112 offset:11792
	ds_write_b32 v108, v142 offset:24064
	s_waitcnt lgkmcnt(5)
	v_pk_mul_f32 v[136:137], v[22:23], v[30:31]
	v_pk_mul_f32 v[138:139], v[22:23], v[96:97]
	v_pk_fma_f32 v[136:137], v[24:25], v[32:33], v[136:137]
	v_pk_fma_f32 v[138:139], v[24:25], v[98:99], v[138:139]
	v_pk_fma_f32 v[136:137], v[26:27], v[34:35], v[136:137]
	v_pk_fma_f32 v[138:139], v[26:27], v[100:101], v[138:139]
	v_pk_fma_f32 v[136:137], v[28:29], v[36:37], v[136:137]
	v_pk_fma_f32 v[138:139], v[28:29], v[102:103], v[138:139]
	ds_read_b128 v[30:33], v112 offset:3840
	ds_read_b128 v[34:37], v112 offset:3856
	ds_read_b128 v[96:99], v112 offset:19968
	ds_read_b128 v[100:103], v112 offset:19984
	v_add_f32_e32 v140, v136, v137
	v_add_f32_e32 v142, v138, v139
	s_waitcnt lgkmcnt(7)
	v_pk_mul_f32 v[128:129], v[22:23], v[38:39]
	v_add_f32_dpp v140, v140, v140 row_half_mirror row_mask:0xf bank_mask:0xf
	v_add_f32_dpp v142, v142, v142 row_half_mirror row_mask:0xf bank_mask:0xf
	v_pk_mul_f32 v[130:131], v[24:25], v[40:41]
	v_pk_mul_f32 v[132:133], v[26:27], v[42:43]
	v_add_f32_dpp v140, v140, v140 quad_perm:[1,0,3,2] row_mask:0xf bank_mask:0xf
	v_add_f32_dpp v142, v142, v142 quad_perm:[1,0,3,2] row_mask:0xf bank_mask:0xf
	v_pk_mul_f32 v[134:135], v[28:29], v[44:45]
	ds_read_b128 v[38:41], v112 offset:7936
	ds_read_b128 v[42:45], v112 offset:7952
	v_add_f32_dpp v140, v140, v140 quad_perm:[2,3,0,1] row_mask:0xf bank_mask:0xf
	v_add_f32_dpp v142, v142, v142 quad_perm:[2,3,0,1] row_mask:0xf bank_mask:0xf
	s_waitcnt lgkmcnt(7)
	v_pk_fma_f32 v[22:23], v[140:141], v[70:71], v[128:129] op_sel_hi:[0,1,1] neg_lo:[1,0,0] neg_hi:[1,0,0]
	v_pk_fma_f32 v[24:25], v[140:141], v[72:73], v[130:131] op_sel_hi:[0,1,1] neg_lo:[1,0,0] neg_hi:[1,0,0]
	v_pk_fma_f32 v[26:27], v[140:141], v[74:75], v[132:133] op_sel_hi:[0,1,1] neg_lo:[1,0,0] neg_hi:[1,0,0]
	v_pk_fma_f32 v[28:29], v[140:141], v[76:77], v[134:135] op_sel_hi:[0,1,1] neg_lo:[1,0,0] neg_hi:[1,0,0]
	ds_read_b128 v[70:73], v112 offset:12032
	ds_read_b128 v[74:77], v112 offset:12048
	ds_write_b32 v108, v142 offset:24192
	s_waitcnt lgkmcnt(5)
	v_pk_mul_f32 v[136:137], v[22:23], v[30:31]
	v_pk_mul_f32 v[138:139], v[22:23], v[96:97]
	v_pk_fma_f32 v[136:137], v[24:25], v[32:33], v[136:137]
	v_pk_fma_f32 v[138:139], v[24:25], v[98:99], v[138:139]
	v_pk_fma_f32 v[136:137], v[26:27], v[34:35], v[136:137]
	v_pk_fma_f32 v[138:139], v[26:27], v[100:101], v[138:139]
	v_pk_fma_f32 v[136:137], v[28:29], v[36:37], v[136:137]
	v_pk_fma_f32 v[138:139], v[28:29], v[102:103], v[138:139]
	ds_read_b128 v[96:99], v112 offset:20224
	ds_read_b128 v[100:103], v112 offset:20240
	v_add_f32_e32 v140, v136, v137
	v_add_f32_e32 v142, v138, v139
	s_waitcnt lgkmcnt(5)
	v_pk_mul_f32 v[128:129], v[22:23], v[38:39]
	v_add_f32_dpp v140, v140, v140 row_half_mirror row_mask:0xf bank_mask:0xf
	v_add_f32_dpp v142, v142, v142 row_half_mirror row_mask:0xf bank_mask:0xf
	v_pk_mul_f32 v[130:131], v[24:25], v[40:41]
	v_pk_mul_f32 v[132:133], v[26:27], v[42:43]
	v_add_f32_dpp v140, v140, v140 quad_perm:[1,0,3,2] row_mask:0xf bank_mask:0xf
	v_add_f32_dpp v142, v142, v142 quad_perm:[1,0,3,2] row_mask:0xf bank_mask:0xf
	v_pk_mul_f32 v[134:135], v[28:29], v[44:45]
	v_add_f32_dpp v140, v140, v140 quad_perm:[2,3,0,1] row_mask:0xf bank_mask:0xf
	v_add_f32_dpp v142, v142, v142 quad_perm:[2,3,0,1] row_mask:0xf bank_mask:0xf
	s_waitcnt lgkmcnt(3)
	v_pk_fma_f32 v[22:23], v[140:141], v[70:71], v[128:129] op_sel_hi:[0,1,1] neg_lo:[1,0,0] neg_hi:[1,0,0]
	v_pk_fma_f32 v[24:25], v[140:141], v[72:73], v[130:131] op_sel_hi:[0,1,1] neg_lo:[1,0,0] neg_hi:[1,0,0]
	v_pk_fma_f32 v[26:27], v[140:141], v[74:75], v[132:133] op_sel_hi:[0,1,1] neg_lo:[1,0,0] neg_hi:[1,0,0]
	v_pk_fma_f32 v[28:29], v[140:141], v[76:77], v[134:135] op_sel_hi:[0,1,1] neg_lo:[1,0,0] neg_hi:[1,0,0]
	ds_write_b32 v108, v142 offset:24320
	s_waitcnt lgkmcnt(1)
	v_pk_mul_f32 v[138:139], v[22:23], v[96:97]
	v_pk_fma_f32 v[138:139], v[24:25], v[98:99], v[138:139]
	v_pk_fma_f32 v[138:139], v[26:27], v[100:101], v[138:139]
	v_pk_fma_f32 v[138:139], v[28:29], v[102:103], v[138:139]
	v_add_f32_e32 v142, v138, v139
	s_nop 1
	v_add_f32_dpp v142, v142, v142 row_half_mirror row_mask:0xf bank_mask:0xf
	s_nop 1
	v_add_f32_dpp v142, v142, v142 quad_perm:[1,0,3,2] row_mask:0xf bank_mask:0xf
	s_nop 1
	v_add_f32_dpp v142, v142, v142 quad_perm:[2,3,0,1] row_mask:0xf bank_mask:0xf
	ds_write_b32 v108, v142 offset:24448
.Lrw0_u2e0:
	s_add_u32 s28, s28, 16
	s_mov_b32 s35, 1
	s_waitcnt vmcnt(0)
	ds_write_b128 v110, v[58:61] offset:26624
	ds_write_b128 v110, v[62:65] offset:30720
	ds_write_b128 v110, v[66:69] offset:34816
	s_waitcnt lgkmcnt(0)
	s_barrier
	s_add_u32 s30, s28, 32
	v_add_u32_e32 v87, s30, v15
	v_med3_i32 v87, v87, 0, s29
	v_mad_i64_i32 v[104:105], vcc, v87, v12, v[6:7]
	global_load_dwordx4 v[58:61], v[104:105], off
	v_add_u32_e32 v87, s30, v16
	v_med3_i32 v87, v87, 0, s29
	v_mad_i64_i32 v[104:105], vcc, v87, v13, v[8:9]
	global_load_dwordx4 v[62:65], v[104:105], off
	v_add_u32_e32 v87, s30, v17
	v_med3_i32 v87, v87, 0, s29
	v_mad_i64_i32 v[104:105], vcc, v87, v14, v[10:11]
	global_load_dwordx4 v[66:69], v[104:105], off
	ds_read_b32 v89, v5 offset:22528
	ds_read_b32 v90, v5 offset:22592
	s_sub_u32 s98, s28, 16
	v_add_u32_e32 v87, s98, v127
	v_mad_i64_i32 v[104:105], vcc, v87, v20, v[18:19]
	s_waitcnt lgkmcnt(0)
	v_cvt_pk_bf16_f32 v89, v89, v90
	global_store_short v[104:105], v89, off
	global_store_short_d16_hi v[104:105], v89, off offset:32
	ds_read_b128 v[30:33], v93 offset:46080
	ds_read_b128 v[34:37], v93 offset:46096
	ds_read_b128 v[38:41], v93 offset:46112
	ds_read_b128 v[42:45], v93 offset:46128
	ds_read_b64 v[70:71], v1 offset:27008
	ds_read_b64 v[72:73], v1 offset:26624
	ds_read_b64 v[74:75], v1 offset:27392
	ds_read_b64 v[76:77], v1 offset:27136
	ds_read_b64 v[78:79], v1 offset:26752
	ds_read_b64 v[80:81], v1 offset:27520
	ds_read_b64 v[82:83], v1 offset:27264
	ds_read_b64 v[84:85], v1 offset:26880
	ds_read_b64 v[96:97], v1 offset:27648
	ds_read_b64 v[128:129], v2 offset:33536
	ds_read_b64 v[130:131], v2 offset:33664
	v_add_u32_e32 v87, s28, v127
	v_cmp_ne_u32_e32 vcc, 0, v87
	s_nop 1
	v_cndmask_b32_e64 v98, 0, 0.5, vcc
	v_cmp_ne_u32_e32 vcc, s29, v87
	s_nop 1
	v_cndmask_b32_e64 v100, 0, 0.5, vcc
	s_waitcnt lgkmcnt(8)
	v_lshlrev_b32_e32 v132, 16, v70
	v_and_b32_e32 v133, 0xffff0000, v70
	v_lshlrev_b32_e32 v134, 16, v71
	v_and_b32_e32 v135, 0xffff0000, v71
	v_lshlrev_b32_e32 v136, 16, v72
	v_and_b32_e32 v137, 0xffff0000, v72
	v_lshlrev_b32_e32 v138, 16, v73
	v_and_b32_e32 v139, 0xffff0000, v73
	v_lshlrev_b32_e32 v140, 16, v74
	v_and_b32_e32 v141, 0xffff0000, v74
	v_lshlrev_b32_e32 v142, 16, v75
	v_and_b32_e32 v143, 0xffff0000, v75
	v_pk_mul_f32 v[136:137], v[136:137], v[98:99] op_sel_hi:[1,0]
	v_pk_fma_f32 v[136:137], v[140:141], v[100:101], v[136:137] op_sel_hi:[1,0,1]
	v_pk_add_f32 v[136:137], v[136:137], v[132:133] neg_lo:[0,1] neg_hi:[0,1]
	v_pk_fma_f32 v[144:145], v[30:31], v[136:137], v[132:133]
	v_pk_mul_f32 v[138:139], v[138:139], v[98:99] op_sel_hi:[1,0]
	v_pk_fma_f32 v[138:139], v[142:143], v[100:101], v[138:139] op_sel_hi:[1,0,1]
	v_pk_add_f32 v[138:139], v[138:139], v[134:135] neg_lo:[0,1] neg_hi:[0,1]
	v_pk_fma_f32 v[146:147], v[32:33], v[138:139], v[134:135]
	ds_read_b128 v[30:33], v93 offset:46144
	s_waitcnt lgkmcnt(6)
	v_lshlrev_b32_e32 v132, 16, v76
	v_and_b32_e32 v133, 0xffff0000, v76
	v_lshlrev_b32_e32 v134, 16, v77
	v_and_b32_e32 v135, 0xffff0000, v77
	v_lshlrev_b32_e32 v136, 16, v78
	v_and_b32_e32 v137, 0xffff0000, v78
	v_lshlrev_b32_e32 v138, 16, v79
	v_and_b32_e32 v139, 0xffff0000, v79
	v_lshlrev_b32_e32 v140, 16, v80
	v_and_b32_e32 v141, 0xffff0000, v80
	v_lshlrev_b32_e32 v142, 16, v81
	v_and_b32_e32 v143, 0xffff0000, v81
	v_pk_mul_f32 v[136:137], v[136:137], v[98:99] op_sel_hi:[1,0]
	v_pk_fma_f32 v[136:137], v[140:141], v[100:101], v[136:137] op_sel_hi:[1,0,1]
	v_pk_add_f32 v[136:137], v[136:137], v[132:133] neg_lo:[0,1] neg_hi:[0,1]
	v_pk_fma_f32 v[102:103], v[34:35], v[136:137], v[132:133]
	v_pk_mul_f32 v[138:139], v[138:139], v[98:99] op_sel_hi:[1,0]
	v_pk_fma_f32 v[138:139], v[142:143], v[100:101], v[138:139] op_sel_hi:[1,0,1]
	v_pk_add_f32 v[138:139], v[138:139], v[134:135] neg_lo:[0,1] neg_hi:[0,1]
	v_pk_fma_f32 v[104:105], v[36:37], v[138:139], v[134:135]
	s_waitcnt lgkmcnt(3)
	v_lshlrev_b32_e32 v132, 16, v82
	v_and_b32_e32 v133, 0xffff0000, v82
	v_lshlrev_b32_e32 v134, 16, v83
	v_and_b32_e32 v135, 0xffff0000, v83
	v_lshlrev_b32_e32 v136, 16, v84
	v_and_b32_e32 v137, 0xffff0000, v84
	v_lshlrev_b32_e32 v138, 16, v85
	v_and_b32_e32 v139, 0xffff0000, v85
	v_lshlrev_b32_e32 v140, 16, v96
	v_and_b32_e32 v141, 0xffff0000, v96
	v_lshlrev_b32_e32 v142, 16, v97
	v_and_b32_e32 v143, 0xffff0000, v97
	v_pk_mul_f32 v[136:137], v[136:137], v[98:99] op_sel_hi:[1,0]
	v_pk_fma_f32 v[136:137], v[140:141], v[100:101], v[136:137] op_sel_hi:[1,0,1]
	v_pk_add_f32 v[136:137], v[136:137], v[132:133] neg_lo:[0,1] neg_hi:[0,1]
	v_pk_fma_f32 v[148:149], v[38:39], v[136:137], v[132:133]
	v_pk_mul_f32 v[138:139], v[138:139], v[98:99] op_sel_hi:[1,0]
	v_pk_fma_f32 v[138:139], v[142:143], v[100:101], v[138:139] op_sel_hi:[1,0,1]
	v_pk_add_f32 v[138:139], v[138:139], v[134:135] neg_lo:[0,1] neg_hi:[0,1]
	v_pk_fma_f32 v[150:151], v[40:41], v[138:139], v[134:135]
	s_waitcnt lgkmcnt(0)
	v_lshlrev_b32_e32 v132, 16, v128
	v_and_b32_e32 v133, 0xffff0000, v128
	v_lshlrev_b32_e32 v134, 16, v129
	v_and_b32_e32 v135, 0xffff0000, v129
	v_lshlrev_b32_e32 v136, 16, v130
	v_and_b32_e32 v137, 0xffff0000, v130
	v_lshlrev_b32_e32 v138, 16, v131
	v_and_b32_e32 v139, 0xffff0000, v131
	s_mov_b32 s98, 0xbf60028b
	v_mul_f32_e32 v132, s98, v132
	v_mul_f32_e32 v133, s98, v133
	v_mul_f32_e32 v134, s98, v134
	v_mul_f32_e32 v135, s98, v135
	v_exp_f32_e32 v132, v132
	v_exp_f32_e32 v133, v133
	v_exp_f32_e32 v134, v134
	v_exp_f32_e32 v135, v135
	v_pk_mul_f32 v[140:141], v[102:103], v[42:43]
	v_pk_mul_f32 v[142:143], v[104:105], v[44:45]
	v_pk_mul_f32 v[106:107], v[140:141], v[140:141]
	v_pk_fma_f32 v[106:107], v[142:143], v[142:143], v[106:107]
	v_add_f32_e32 v106, v106, v107
	s_nop 1
	v_add_f32_dpp v106, v106, v106 row_ror:8 row_mask:0xf bank_mask:0xf bound_ctrl:1
	s_nop 1
	v_add_f32_dpp v106, v106, v106 row_ror:4 row_mask:0xf bank_mask:0xf bound_ctrl:1
	s_nop 1
	v_add_f32_dpp v106, v106, v106 row_ror:2 row_mask:0xf bank_mask:0xf bound_ctrl:1
	s_nop 1
	v_add_f32_dpp v106, v106, v106 row_ror:1 row_mask:0xf bank_mask:0xf bound_ctrl:1
	v_add_f32_e32 v106, 0x2b8cbccc, v106
	v_rsq_f32_e32 v106, v106
	v_pk_mul_f32 v[148:149], v[148:149], s[40:41] op_sel_hi:[1,0]
	v_pk_mul_f32 v[150:151], v[150:151], s[40:41] op_sel_hi:[1,0]
	v_pk_mul_f32 v[140:141], v[140:141], v[106:107] op_sel_hi:[1,0]
	v_pk_mul_f32 v[142:143], v[142:143], v[106:107] op_sel_hi:[1,0]
	v_pk_add_f32 v[70:71], v[136:137], -1.0 op_sel_hi:[1,0]
	v_pk_add_f32 v[72:73], v[138:139], -1.0 op_sel_hi:[1,0]
	v_pk_fma_f32 v[70:71], v[30:31], v[70:71], 1.0 op_sel_hi:[1,1,0]
	v_pk_fma_f32 v[72:73], v[32:33], v[72:73], 1.0 op_sel_hi:[1,1,0]
	v_pk_mul_f32 v[70:71], v[102:103], v[70:71]
	v_pk_mul_f32 v[72:73], v[104:105], v[72:73]
	v_pk_mul_f32 v[74:75], v[140:141], v[136:137]
	v_pk_mul_f32 v[76:77], v[142:143], v[138:139]
	ds_write_b128 v3, v[140:143] offset:0
	ds_write_b128 v3, v[132:135] offset:4096
	ds_write_b128 v3, v[74:77] offset:8192
	ds_write_b128 v3, v[70:73] offset:12288
	ds_write_b128 v3, v[144:147] offset:16384
	ds_write_b128 v4, v[148:151]
	s_waitcnt lgkmcnt(0)
	s_barrier
	s_cmp_eq_u32 s18, 2
	s_cbranch_scc1 .Lrw0_u2s1
	ds_read_b128 v[30:33], v112 offset:0
	ds_read_b128 v[34:37], v112 offset:16
	ds_read_b128 v[78:81], v112 offset:12288
	ds_read_b128 v[82:85], v112 offset:12304
	ds_read_b32 v104, v108 offset:20480
	ds_read_b128 v[38:41], v112 offset:4096
	ds_read_b128 v[42:45], v112 offset:4112
	ds_read_b128 v[70:73], v112 offset:8192
	ds_read_b128 v[74:77], v112 offset:8208
	s_waitcnt lgkmcnt(7)
	v_pk_mul_f32 v[136:137], v[22:23], v[30:31]
	v_pk_fma_f32 v[136:137], v[24:25], v[32:33], v[136:137]
	v_pk_fma_f32 v[136:137], v[26:27], v[34:35], v[136:137]
	v_pk_fma_f32 v[136:137], v[28:29], v[36:37], v[136:137]
	ds_read_b128 v[30:33], v112 offset:256
	ds_read_b128 v[34:37], v112 offset:272
	ds_read_b128 v[96:99], v112 offset:16384
	ds_read_b128 v[100:103], v112 offset:16400
	v_add_f32_e32 v140, v136, v137
	s_waitcnt lgkmcnt(8)
	v_pk_mul_f32 v[128:129], v[78:79], v[104:105] op_sel_hi:[1,0]
	v_add_f32_dpp v140, v140, v140 row_half_mirror row_mask:0xf bank_mask:0xf
	v_pk_mul_f32 v[130:131], v[80:81], v[104:105] op_sel_hi:[1,0]
	v_pk_mul_f32 v[132:133], v[82:83], v[104:105] op_sel_hi:[1,0]
	v_pk_mul_f32 v[134:135], v[84:85], v[104:105] op_sel_hi:[1,0]
	ds_read_b128 v[78:81], v112 offset:12544
	ds_read_b128 v[82:85], v112 offset:12560
	ds_read_b32 v104, v108 offset:20608
	v_add_f32_dpp v140, v140, v140 quad_perm:[1,0,3,2] row_mask:0xf bank_mask:0xf
	s_waitcnt lgkmcnt(9)
	v_pk_fma_f32 v[128:129], v[22:23], v[38:39], v[128:129]
	v_pk_fma_f32 v[130:131], v[24:25], v[40:41], v[130:131]
	v_pk_fma_f32 v[132:133], v[26:27], v[42:43], v[132:133]
	v_add_f32_dpp v140, v140, v140 quad_perm:[2,3,0,1] row_mask:0xf bank_mask:0xf
	v_pk_fma_f32 v[134:135], v[28:29], v[44:45], v[134:135]
	ds_read_b128 v[38:41], v112 offset:4352
	ds_read_b128 v[42:45], v112 offset:4368
	s_waitcnt lgkmcnt(9)
	v_pk_fma_f32 v[22:23], v[140:141], v[70:71], v[128:129] op_sel_hi:[0,1,1] neg_lo:[1,0,0] neg_hi:[1,0,0]
	v_pk_fma_f32 v[24:25], v[140:141], v[72:73], v[130:131] op_sel_hi:[0,1,1] neg_lo:[1,0,0] neg_hi:[1,0,0]
	v_pk_fma_f32 v[26:27], v[140:141], v[74:75], v[132:133] op_sel_hi:[0,1,1] neg_lo:[1,0,0] neg_hi:[1,0,0]
	v_pk_fma_f32 v[28:29], v[140:141], v[76:77], v[134:135] op_sel_hi:[0,1,1] neg_lo:[1,0,0] neg_hi:[1,0,0]
	ds_read_b128 v[70:73], v112 offset:8448
	ds_read_b128 v[74:77], v112 offset:8464
	s_waitcnt lgkmcnt(7)
	v_pk_mul_f32 v[136:137], v[22:23], v[30:31]
	v_pk_mul_f32 v[138:139], v[22:23], v[96:97]
	v_pk_fma_f32 v[136:137], v[24:25], v[32:33], v[136:137]
	v_pk_fma_f32 v[138:139], v[24:25], v[98:99], v[138:139]
	v_pk_fma_f32 v[136:137], v[26:27], v[34:35], v[136:137]
	v_pk_fma_f32 v[138:139], v[26:27], v[100:101], v[138:139]
	v_pk_fma_f32 v[136:137], v[28:29], v[36:37], v[136:137]
	v_pk_fma_f32 v[138:139], v[28:29], v[102:103], v[138:139]
	ds_read_b128 v[30:33], v112 offset:512
	ds_read_b128 v[34:37], v112 offset:528
	ds_read_b128 v[96:99], v112 offset:16640
	ds_read_b128 v[100:103], v112 offset:16656
	v_add_f32_e32 v140, v136, v137
	v_add_f32_e32 v142, v138, v139
	s_waitcnt lgkmcnt(8)
	v_pk_mul_f32 v[128:129], v[78:79], v[104:105] op_sel_hi:[1,0]
	v_add_f32_dpp v140, v140, v140 row_half_mirror row_mask:0xf bank_mask:0xf
	v_add_f32_dpp v142, v142, v142 row_half_mirror row_mask:0xf bank_mask:0xf
	v_pk_mul_f32 v[130:131], v[80:81], v[104:105] op_sel_hi:[1,0]
	v_pk_mul_f32 v[132:133], v[82:83], v[104:105] op_sel_hi:[1,0]
	v_add_f32_dpp v140, v140, v140 quad_perm:[1,0,3,2] row_mask:0xf bank_mask:0xf
	v_add_f32_dpp v142, v142, v142 quad_perm:[1,0,3,2] row_mask:0xf bank_mask:0xf
	v_pk_mul_f32 v[134:135], v[84:85], v[104:105] op_sel_hi:[1,0]
	ds_read_b128 v[78:81], v112 offset:12800
	ds_read_b128 v[82:85], v112 offset:12816
	ds_read_b32 v104, v108 offset:20736
	s_waitcnt lgkmcnt(9)
	v_pk_fma_f32 v[128:129], v[22:23], v[38:39], v[128:129]
	v_add_f32_dpp v140, v140, v140 quad_perm:[2,3,0,1] row_mask:0xf bank_mask:0xf
	v_add_f32_dpp v142, v142, v142 quad_perm:[2,3,0,1] row_mask:0xf bank_mask:0xf
	v_pk_fma_f32 v[130:131], v[24:25], v[40:41], v[130:131]
	v_pk_fma_f32 v[132:133], v[26:27], v[42:43], v[132:133]
	v_pk_fma_f32 v[134:135], v[28:29], v[44:45], v[134:135]
	ds_read_b128 v[38:41], v112 offset:4608
	ds_read_b128 v[42:45], v112 offset:4624
	s_waitcnt lgkmcnt(9)
	v_pk_fma_f32 v[22:23], v[140:141], v[70:71], v[128:129] op_sel_hi:[0,1,1] neg_lo:[1,0,0] neg_hi:[1,0,0]
	v_pk_fma_f32 v[24:25], v[140:141], v[72:73], v[130:131] op_sel_hi:[0,1,1] neg_lo:[1,0,0] neg_hi:[1,0,0]
	v_pk_fma_f32 v[26:27], v[140:141], v[74:75], v[132:133] op_sel_hi:[0,1,1] neg_lo:[1,0,0] neg_hi:[1,0,0]
	v_pk_fma_f32 v[28:29], v[140:141], v[76:77], v[134:135] op_sel_hi:[0,1,1] neg_lo:[1,0,0] neg_hi:[1,0,0]
	ds_read_b128 v[70:73], v112 offset:8704
	ds_read_b128 v[74:77], v112 offset:8720
	ds_write_b32 v108, v142 offset:24576
	s_waitcnt lgkmcnt(8)
	v_pk_mul_f32 v[136:137], v[22:23], v[30:31]
	v_pk_mul_f32 v[138:139], v[22:23], v[96:97]
	v_pk_fma_f32 v[136:137], v[24:25], v[32:33], v[136:137]
	v_pk_fma_f32 v[138:139], v[24:25], v[98:99], v[138:139]
	v_pk_fma_f32 v[136:137], v[26:27], v[34:35], v[136:137]
	v_pk_fma_f32 v[138:139], v[26:27], v[100:101], v[138:139]
	v_pk_fma_f32 v[136:137], v[28:29], v[36:37], v[136:137]
	v_pk_fma_f32 v[138:139], v[28:29], v[102:103], v[138:139]
	ds_read_b128 v[30:33], v112 offset:768
	ds_read_b128 v[34:37], v112 offset:784
	ds_read_b128 v[96:99], v112 offset:16896
	ds_read_b128 v[100:103], v112 offset:16912
	v_add_f32_e32 v140, v136, v137
	v_add_f32_e32 v142, v138, v139
	s_waitcnt lgkmcnt(9)
	v_pk_mul_f32 v[128:129], v[78:79], v[104:105] op_sel_hi:[1,0]
	v_add_f32_dpp v140, v140, v140 row_half_mirror row_mask:0xf bank_mask:0xf
	v_add_f32_dpp v142, v142, v142 row_half_mirror row_mask:0xf bank_mask:0xf
	v_pk_mul_f32 v[130:131], v[80:81], v[104:105] op_sel_hi:[1,0]
	v_pk_mul_f32 v[132:133], v[82:83], v[104:105] op_sel_hi:[1,0]
	v_add_f32_dpp v140, v140, v140 quad_perm:[1,0,3,2] row_mask:0xf bank_mask:0xf
	v_add_f32_dpp v142, v142, v142 quad_perm:[1,0,3,2] row_mask:0xf bank_mask:0xf
	v_pk_mul_f32 v[134:135], v[84:85], v[104:105] op_sel_hi:[1,0]
	ds_read_b128 v[78:81], v112 offset:13056
	ds_read_b128 v[82:85], v112 offset:13072
	ds_read_b32 v104, v108 offset:20864
	s_waitcnt lgkmcnt(10)
	v_pk_fma_f32 v[128:129], v[22:23], v[38:39], v[128:129]
	v_add_f32_dpp v140, v140, v140 quad_perm:[2,3,0,1] row_mask:0xf bank_mask:0xf
	v_add_f32_dpp v142, v142, v142 quad_perm:[2,3,0,1] row_mask:0xf bank_mask:0xf
	v_pk_fma_f32 v[130:131], v[24:25], v[40:41], v[130:131]
	v_pk_fma_f32 v[132:133], v[26:27], v[42:43], v[132:133]
	v_pk_fma_f32 v[134:135], v[28:29], v[44:45], v[134:135]
	ds_read_b128 v[38:41], v112 offset:4864
	ds_read_b128 v[42:45], v112 offset:4880
	s_waitcnt lgkmcnt(10)
	v_pk_fma_f32 v[22:23], v[140:141], v[70:71], v[128:129] op_sel_hi:[0,1,1] neg_lo:[1,0,0] neg_hi:[1,0,0]
	v_pk_fma_f32 v[24:25], v[140:141], v[72:73], v[130:131] op_sel_hi:[0,1,1] neg_lo:[1,0,0] neg_hi:[1,0,0]
	v_pk_fma_f32 v[26:27], v[140:141], v[74:75], v[132:133] op_sel_hi:[0,1,1] neg_lo:[1,0,0] neg_hi:[1,0,0]
	v_pk_fma_f32 v[28:29], v[140:141], v[76:77], v[134:135] op_sel_hi:[0,1,1] neg_lo:[1,0,0] neg_hi:[1,0,0]
	ds_read_b128 v[70:73], v112 offset:8960
	ds_read_b128 v[74:77], v112 offset:8976
	ds_write_b32 v108, v142 offset:24704
	s_waitcnt lgkmcnt(8)
	v_pk_mul_f32 v[136:137], v[22:23], v[30:31]
	v_pk_mul_f32 v[138:139], v[22:23], v[96:97]
	v_pk_fma_f32 v[136:137], v[24:25], v[32:33], v[136:137]
	v_pk_fma_f32 v[138:139], v[24:25], v[98:99], v[138:139]
	v_pk_fma_f32 v[136:137], v[26:27], v[34:35], v[136:137]
	v_pk_fma_f32 v[138:139], v[26:27], v[100:101], v[138:139]
	v_pk_fma_f32 v[136:137], v[28:29], v[36:37], v[136:137]
	v_pk_fma_f32 v[138:139], v[28:29], v[102:103], v[138:139]
	ds_read_b128 v[30:33], v112 offset:1024
	ds_read_b128 v[34:37], v112 offset:1040
	ds_read_b128 v[96:99], v112 offset:17152
	ds_read_b128 v[100:103], v112 offset:17168
	v_add_f32_e32 v140, v136, v137
	v_add_f32_e32 v142, v138, v139
	s_waitcnt lgkmcnt(9)
	v_pk_mul_f32 v[128:129], v[78:79], v[104:105] op_sel_hi:[1,0]
	v_add_f32_dpp v140, v140, v140 row_half_mirror row_mask:0xf bank_mask:0xf
	v_add_f32_dpp v142, v142, v142 row_half_mirror row_mask:0xf bank_mask:0xf
	v_pk_mul_f32 v[130:131], v[80:81], v[104:105] op_sel_hi:[1,0]
	v_pk_mul_f32 v[132:133], v[82:83], v[104:105] op_sel_hi:[1,0]
	v_add_f32_dpp v140, v140, v140 quad_perm:[1,0,3,2] row_mask:0xf bank_mask:0xf
	v_add_f32_dpp v142, v142, v142 quad_perm:[1,0,3,2] row_mask:0xf bank_mask:0xf
	v_pk_mul_f32 v[134:135], v[84:85], v[104:105] op_sel_hi:[1,0]
	ds_read_b128 v[78:81], v112 offset:13312
	ds_read_b128 v[82:85], v112 offset:13328
	ds_read_b32 v104, v108 offset:20992
	s_waitcnt lgkmcnt(10)
	v_pk_fma_f32 v[128:129], v[22:23], v[38:39], v[128:129]
	v_add_f32_dpp v140, v140, v140 quad_perm:[2,3,0,1] row_mask:0xf bank_mask:0xf
	v_add_f32_dpp v142, v142, v142 quad_perm:[2,3,0,1] row_mask:0xf bank_mask:0xf
	v_pk_fma_f32 v[130:131], v[24:25], v[40:41], v[130:131]
	v_pk_fma_f32 v[132:133], v[26:27], v[42:43], v[132:133]
	v_pk_fma_f32 v[134:135], v[28:29], v[44:45], v[134:135]
	ds_read_b128 v[38:41], v112 offset:5120
	ds_read_b128 v[42:45], v112 offset:5136
	s_waitcnt lgkmcnt(10)
	v_pk_fma_f32 v[22:23], v[140:141], v[70:71], v[128:129] op_sel_hi:[0,1,1] neg_lo:[1,0,0] neg_hi:[1,0,0]
	v_pk_fma_f32 v[24:25], v[140:141], v[72:73], v[130:131] op_sel_hi:[0,1,1] neg_lo:[1,0,0] neg_hi:[1,0,0]
	v_pk_fma_f32 v[26:27], v[140:141], v[74:75], v[132:133] op_sel_hi:[0,1,1] neg_lo:[1,0,0] neg_hi:[1,0,0]
	v_pk_fma_f32 v[28:29], v[140:141], v[76:77], v[134:135] op_sel_hi:[0,1,1] neg_lo:[1,0,0] neg_hi:[1,0,0]
	ds_read_b128 v[70:73], v112 offset:9216
	ds_read_b128 v[74:77], v112 offset:9232
	ds_write_b32 v108, v142 offset:24832
	s_waitcnt lgkmcnt(8)
	v_pk_mul_f32 v[136:137], v[22:23], v[30:31]
	v_pk_mul_f32 v[138:139], v[22:23], v[96:97]
	v_pk_fma_f32 v[136:137], v[24:25], v[32:33], v[136:137]
	v_pk_fma_f32 v[138:139], v[24:25], v[98:99], v[138:139]
	v_pk_fma_f32 v[136:137], v[26:27], v[34:35], v[136:137]
	v_pk_fma_f32 v[138:139], v[26:27], v[100:101], v[138:139]
	v_pk_fma_f32 v[136:137], v[28:29], v[36:37], v[136:137]
	v_pk_fma_f32 v[138:139], v[28:29], v[102:103], v[138:139]
	ds_read_b128 v[30:33], v112 offset:1280
	ds_read_b128 v[34:37], v112 offset:1296
	ds_read_b128 v[96:99], v112 offset:17408
	ds_read_b128 v[100:103], v112 offset:17424
	v_add_f32_e32 v140, v136, v137
	v_add_f32_e32 v142, v138, v139
	s_waitcnt lgkmcnt(9)
	v_pk_mul_f32 v[128:129], v[78:79], v[104:105] op_sel_hi:[1,0]
	v_add_f32_dpp v140, v140, v140 row_half_mirror row_mask:0xf bank_mask:0xf
	v_add_f32_dpp v142, v142, v142 row_half_mirror row_mask:0xf bank_mask:0xf
	v_pk_mul_f32 v[130:131], v[80:81], v[104:105] op_sel_hi:[1,0]
	v_pk_mul_f32 v[132:133], v[82:83], v[104:105] op_sel_hi:[1,0]
	v_add_f32_dpp v140, v140, v140 quad_perm:[1,0,3,2] row_mask:0xf bank_mask:0xf
	v_add_f32_dpp v142, v142, v142 quad_perm:[1,0,3,2] row_mask:0xf bank_mask:0xf
	v_pk_mul_f32 v[134:135], v[84:85], v[104:105] op_sel_hi:[1,0]
	ds_read_b128 v[78:81], v112 offset:13568
	ds_read_b128 v[82:85], v112 offset:13584
	ds_read_b32 v104, v108 offset:21120
	s_waitcnt lgkmcnt(10)
	v_pk_fma_f32 v[128:129], v[22:23], v[38:39], v[128:129]
	v_add_f32_dpp v140, v140, v140 quad_perm:[2,3,0,1] row_mask:0xf bank_mask:0xf
	v_add_f32_dpp v142, v142, v142 quad_perm:[2,3,0,1] row_mask:0xf bank_mask:0xf
	v_pk_fma_f32 v[130:131], v[24:25], v[40:41], v[130:131]
	v_pk_fma_f32 v[132:133], v[26:27], v[42:43], v[132:133]
	v_pk_fma_f32 v[134:135], v[28:29], v[44:45], v[134:135]
	ds_read_b128 v[38:41], v112 offset:5376
	ds_read_b128 v[42:45], v112 offset:5392
	s_waitcnt lgkmcnt(10)
	v_pk_fma_f32 v[22:23], v[140:141], v[70:71], v[128:129] op_sel_hi:[0,1,1] neg_lo:[1,0,0] neg_hi:[1,0,0]
	v_pk_fma_f32 v[24:25], v[140:141], v[72:73], v[130:131] op_sel_hi:[0,1,1] neg_lo:[1,0,0] neg_hi:[1,0,0]
	v_pk_fma_f32 v[26:27], v[140:141], v[74:75], v[132:133] op_sel_hi:[0,1,1] neg_lo:[1,0,0] neg_hi:[1,0,0]
	v_pk_fma_f32 v[28:29], v[140:141], v[76:77], v[134:135] op_sel_hi:[0,1,1] neg_lo:[1,0,0] neg_hi:[1,0,0]
	ds_read_b128 v[70:73], v112 offset:9472
	ds_read_b128 v[74:77], v112 offset:9488
	ds_write_b32 v108, v142 offset:24960
	s_waitcnt lgkmcnt(8)
	v_pk_mul_f32 v[136:137], v[22:23], v[30:31]
	v_pk_mul_f32 v[138:139], v[22:23], v[96:97]
	v_pk_fma_f32 v[136:137], v[24:25], v[32:33], v[136:137]
	v_pk_fma_f32 v[138:139], v[24:25], v[98:99], v[138:139]
	v_pk_fma_f32 v[136:137], v[26:27], v[34:35], v[136:137]
	v_pk_fma_f32 v[138:139], v[26:27], v[100:101], v[138:139]
	v_pk_fma_f32 v[136:137], v[28:29], v[36:37], v[136:137]
	v_pk_fma_f32 v[138:139], v[28:29], v[102:103], v[138:139]
	ds_read_b128 v[30:33], v112 offset:1536
	ds_read_b128 v[34:37], v112 offset:1552
	ds_read_b128 v[96:99], v112 offset:17664
	ds_read_b128 v[100:103], v112 offset:17680
	v_add_f32_e32 v140, v136, v137
	v_add_f32_e32 v142, v138, v139
	s_waitcnt lgkmcnt(9)
	v_pk_mul_f32 v[128:129], v[78:79], v[104:105] op_sel_hi:[1,0]
	v_add_f32_dpp v140, v140, v140 row_half_mirror row_mask:0xf bank_mask:0xf
	v_add_f32_dpp v142, v142, v142 row_half_mirror row_mask:0xf bank_mask:0xf
	v_pk_mul_f32 v[130:131], v[80:81], v[104:105] op_sel_hi:[1,0]
	v_pk_mul_f32 v[132:133], v[82:83], v[104:105] op_sel_hi:[1,0]
	v_add_f32_dpp v140, v140, v140 quad_perm:[1,0,3,2] row_mask:0xf bank_mask:0xf
	v_add_f32_dpp v142, v142, v142 quad_perm:[1,0,3,2] row_mask:0xf bank_mask:0xf
	v_pk_mul_f32 v[134:135], v[84:85], v[104:105] op_sel_hi:[1,0]
	ds_read_b128 v[78:81], v112 offset:13824
	ds_read_b128 v[82:85], v112 offset:13840
	ds_read_b32 v104, v108 offset:21248
	s_waitcnt lgkmcnt(10)
	v_pk_fma_f32 v[128:129], v[22:23], v[38:39], v[128:129]
	v_add_f32_dpp v140, v140, v140 quad_perm:[2,3,0,1] row_mask:0xf bank_mask:0xf
	v_add_f32_dpp v142, v142, v142 quad_perm:[2,3,0,1] row_mask:0xf bank_mask:0xf
	v_pk_fma_f32 v[130:131], v[24:25], v[40:41], v[130:131]
	v_pk_fma_f32 v[132:133], v[26:27], v[42:43], v[132:133]
	v_pk_fma_f32 v[134:135], v[28:29], v[44:45], v[134:135]
	ds_read_b128 v[38:41], v112 offset:5632
	ds_read_b128 v[42:45], v112 offset:5648
	s_waitcnt lgkmcnt(10)
	v_pk_fma_f32 v[22:23], v[140:141], v[70:71], v[128:129] op_sel_hi:[0,1,1] neg_lo:[1,0,0] neg_hi:[1,0,0]
	v_pk_fma_f32 v[24:25], v[140:141], v[72:73], v[130:131] op_sel_hi:[0,1,1] neg_lo:[1,0,0] neg_hi:[1,0,0]
	v_pk_fma_f32 v[26:27], v[140:141], v[74:75], v[132:133] op_sel_hi:[0,1,1] neg_lo:[1,0,0] neg_hi:[1,0,0]
	v_pk_fma_f32 v[28:29], v[140:141], v[76:77], v[134:135] op_sel_hi:[0,1,1] neg_lo:[1,0,0] neg_hi:[1,0,0]
	ds_read_b128 v[70:73], v112 offset:9728
	ds_read_b128 v[74:77], v112 offset:9744
	ds_write_b32 v108, v142 offset:25088
	s_waitcnt lgkmcnt(8)
	v_pk_mul_f32 v[136:137], v[22:23], v[30:31]
	v_pk_mul_f32 v[138:139], v[22:23], v[96:97]
	v_pk_fma_f32 v[136:137], v[24:25], v[32:33], v[136:137]
	v_pk_fma_f32 v[138:139], v[24:25], v[98:99], v[138:139]
	v_pk_fma_f32 v[136:137], v[26:27], v[34:35], v[136:137]
	v_pk_fma_f32 v[138:139], v[26:27], v[100:101], v[138:139]
	v_pk_fma_f32 v[136:137], v[28:29], v[36:37], v[136:137]
	v_pk_fma_f32 v[138:139], v[28:29], v[102:103], v[138:139]
	ds_read_b128 v[30:33], v112 offset:1792
	ds_read_b128 v[34:37], v112 offset:1808
	ds_read_b128 v[96:99], v112 offset:17920
	ds_read_b128 v[100:103], v112 offset:17936
	v_add_f32_e32 v140, v136, v137
	v_add_f32_e32 v142, v138, v139
	s_waitcnt lgkmcnt(9)
	v_pk_mul_f32 v[128:129], v[78:79], v[104:105] op_sel_hi:[1,0]
	v_add_f32_dpp v140, v140, v140 row_half_mirror row_mask:0xf bank_mask:0xf
	v_add_f32_dpp v142, v142, v142 row_half_mirror row_mask:0xf bank_mask:0xf
	v_pk_mul_f32 v[130:131], v[80:81], v[104:105] op_sel_hi:[1,0]
	v_pk_mul_f32 v[132:133], v[82:83], v[104:105] op_sel_hi:[1,0]
	v_add_f32_dpp v140, v140, v140 quad_perm:[1,0,3,2] row_mask:0xf bank_mask:0xf
	v_add_f32_dpp v142, v142, v142 quad_perm:[1,0,3,2] row_mask:0xf bank_mask:0xf
	v_pk_mul_f32 v[134:135], v[84:85], v[104:105] op_sel_hi:[1,0]
	ds_read_b128 v[78:81], v112 offset:14080
	ds_read_b128 v[82:85], v112 offset:14096
	ds_read_b32 v104, v108 offset:21376
	s_waitcnt lgkmcnt(10)
	v_pk_fma_f32 v[128:129], v[22:23], v[38:39], v[128:129]
	v_add_f32_dpp v140, v140, v140 quad_perm:[2,3,0,1] row_mask:0xf bank_mask:0xf
	v_add_f32_dpp v142, v142, v142 quad_perm:[2,3,0,1] row_mask:0xf bank_mask:0xf
	v_pk_fma_f32 v[130:131], v[24:25], v[40:41], v[130:131]
	v_pk_fma_f32 v[132:133], v[26:27], v[42:43], v[132:133]
	v_pk_fma_f32 v[134:135], v[28:29], v[44:45], v[134:135]
	ds_read_b128 v[38:41], v112 offset:5888
	ds_read_b128 v[42:45], v112 offset:5904
	s_waitcnt lgkmcnt(10)
	v_pk_fma_f32 v[22:23], v[140:141], v[70:71], v[128:129] op_sel_hi:[0,1,1] neg_lo:[1,0,0] neg_hi:[1,0,0]
	v_pk_fma_f32 v[24:25], v[140:141], v[72:73], v[130:131] op_sel_hi:[0,1,1] neg_lo:[1,0,0] neg_hi:[1,0,0]
	v_pk_fma_f32 v[26:27], v[140:141], v[74:75], v[132:133] op_sel_hi:[0,1,1] neg_lo:[1,0,0] neg_hi:[1,0,0]
	v_pk_fma_f32 v[28:29], v[140:141], v[76:77], v[134:135] op_sel_hi:[0,1,1] neg_lo:[1,0,0] neg_hi:[1,0,0]
	ds_read_b128 v[70:73], v112 offset:9984
	ds_read_b128 v[74:77], v112 offset:10000
	ds_write_b32 v108, v142 offset:25216
	s_waitcnt lgkmcnt(8)
	v_pk_mul_f32 v[136:137], v[22:23], v[30:31]
	v_pk_mul_f32 v[138:139], v[22:23], v[96:97]
	v_pk_fma_f32 v[136:137], v[24:25], v[32:33], v[136:137]
	v_pk_fma_f32 v[138:139], v[24:25], v[98:99], v[138:139]
	v_pk_fma_f32 v[136:137], v[26:27], v[34:35], v[136:137]
	v_pk_fma_f32 v[138:139], v[26:27], v[100:101], v[138:139]
	v_pk_fma_f32 v[136:137], v[28:29], v[36:37], v[136:137]
	v_pk_fma_f32 v[138:139], v[28:29], v[102:103], v[138:139]
	ds_read_b128 v[30:33], v112 offset:2048
	ds_read_b128 v[34:37], v112 offset:2064
	ds_read_b128 v[96:99], v112 offset:18176
	ds_read_b128 v[100:103], v112 offset:18192
	v_add_f32_e32 v140, v136, v137
	v_add_f32_e32 v142, v138, v139
	s_waitcnt lgkmcnt(9)
	v_pk_mul_f32 v[128:129], v[78:79], v[104:105] op_sel_hi:[1,0]
	v_add_f32_dpp v140, v140, v140 row_half_mirror row_mask:0xf bank_mask:0xf
	v_add_f32_dpp v142, v142, v142 row_half_mirror row_mask:0xf bank_mask:0xf
	v_pk_mul_f32 v[130:131], v[80:81], v[104:105] op_sel_hi:[1,0]
	v_pk_mul_f32 v[132:133], v[82:83], v[104:105] op_sel_hi:[1,0]
	v_add_f32_dpp v140, v140, v140 quad_perm:[1,0,3,2] row_mask:0xf bank_mask:0xf
	v_add_f32_dpp v142, v142, v142 quad_perm:[1,0,3,2] row_mask:0xf bank_mask:0xf
	v_pk_mul_f32 v[134:135], v[84:85], v[104:105] op_sel_hi:[1,0]
	ds_read_b128 v[78:81], v112 offset:14336
	ds_read_b128 v[82:85], v112 offset:14352
	ds_read_b32 v104, v108 offset:21504
	s_waitcnt lgkmcnt(10)
	v_pk_fma_f32 v[128:129], v[22:23], v[38:39], v[128:129]
	v_add_f32_dpp v140, v140, v140 quad_perm:[2,3,0,1] row_mask:0xf bank_mask:0xf
	v_add_f32_dpp v142, v142, v142 quad_perm:[2,3,0,1] row_mask:0xf bank_mask:0xf
	v_pk_fma_f32 v[130:131], v[24:25], v[40:41], v[130:131]
	v_pk_fma_f32 v[132:133], v[26:27], v[42:43], v[132:133]
	v_pk_fma_f32 v[134:135], v[28:29], v[44:45], v[134:135]
	ds_read_b128 v[38:41], v112 offset:6144
	ds_read_b128 v[42:45], v112 offset:6160
	s_waitcnt lgkmcnt(10)
	v_pk_fma_f32 v[22:23], v[140:141], v[70:71], v[128:129] op_sel_hi:[0,1,1] neg_lo:[1,0,0] neg_hi:[1,0,0]
	v_pk_fma_f32 v[24:25], v[140:141], v[72:73], v[130:131] op_sel_hi:[0,1,1] neg_lo:[1,0,0] neg_hi:[1,0,0]
	v_pk_fma_f32 v[26:27], v[140:141], v[74:75], v[132:133] op_sel_hi:[0,1,1] neg_lo:[1,0,0] neg_hi:[1,0,0]
	v_pk_fma_f32 v[28:29], v[140:141], v[76:77], v[134:135] op_sel_hi:[0,1,1] neg_lo:[1,0,0] neg_hi:[1,0,0]
	ds_read_b128 v[70:73], v112 offset:10240
	ds_read_b128 v[74:77], v112 offset:10256
	ds_write_b32 v108, v142 offset:25344
	s_waitcnt lgkmcnt(8)
	v_pk_mul_f32 v[136:137], v[22:23], v[30:31]
	v_pk_mul_f32 v[138:139], v[22:23], v[96:97]
	v_pk_fma_f32 v[136:137], v[24:25], v[32:33], v[136:137]
	v_pk_fma_f32 v[138:139], v[24:25], v[98:99], v[138:139]
	v_pk_fma_f32 v[136:137], v[26:27], v[34:35], v[136:137]
	v_pk_fma_f32 v[138:139], v[26:27], v[100:101], v[138:139]
	v_pk_fma_f32 v[136:137], v[28:29], v[36:37], v[136:137]
	v_pk_fma_f32 v[138:139], v[28:29], v[102:103], v[138:139]
	ds_read_b128 v[30:33], v112 offset:2304
	ds_read_b128 v[34:37], v112 offset:2320
	ds_read_b128 v[96:99], v112 offset:18432
	ds_read_b128 v[100:103], v112 offset:18448
	v_add_f32_e32 v140, v136, v137
	v_add_f32_e32 v142, v138, v139
	s_waitcnt lgkmcnt(9)
	v_pk_mul_f32 v[128:129], v[78:79], v[104:105] op_sel_hi:[1,0]
	v_add_f32_dpp v140, v140, v140 row_half_mirror row_mask:0xf bank_mask:0xf
	v_add_f32_dpp v142, v142, v142 row_half_mirror row_mask:0xf bank_mask:0xf
	v_pk_mul_f32 v[130:131], v[80:81], v[104:105] op_sel_hi:[1,0]
	v_pk_mul_f32 v[132:133], v[82:83], v[104:105] op_sel_hi:[1,0]
	v_add_f32_dpp v140, v140, v140 quad_perm:[1,0,3,2] row_mask:0xf bank_mask:0xf
	v_add_f32_dpp v142, v142, v142 quad_perm:[1,0,3,2] row_mask:0xf bank_mask:0xf
	v_pk_mul_f32 v[134:135], v[84:85], v[104:105] op_sel_hi:[1,0]
	ds_read_b128 v[78:81], v112 offset:14592
	ds_read_b128 v[82:85], v112 offset:14608
	ds_read_b32 v104, v108 offset:21632
	s_waitcnt lgkmcnt(10)
	v_pk_fma_f32 v[128:129], v[22:23], v[38:39], v[128:129]
	v_add_f32_dpp v140, v140, v140 quad_perm:[2,3,0,1] row_mask:0xf bank_mask:0xf
	v_add_f32_dpp v142, v142, v142 quad_perm:[2,3,0,1] row_mask:0xf bank_mask:0xf
	v_pk_fma_f32 v[130:131], v[24:25], v[40:41], v[130:131]
	v_pk_fma_f32 v[132:133], v[26:27], v[42:43], v[132:133]
	v_pk_fma_f32 v[134:135], v[28:29], v[44:45], v[134:135]
	ds_read_b128 v[38:41], v112 offset:6400
	ds_read_b128 v[42:45], v112 offset:6416
	s_waitcnt lgkmcnt(10)
	v_pk_fma_f32 v[22:23], v[140:141], v[70:71], v[128:129] op_sel_hi:[0,1,1] neg_lo:[1,0,0] neg_hi:[1,0,0]
	v_pk_fma_f32 v[24:25], v[140:141], v[72:73], v[130:131] op_sel_hi:[0,1,1] neg_lo:[1,0,0] neg_hi:[1,0,0]
	v_pk_fma_f32 v[26:27], v[140:141], v[74:75], v[132:133] op_sel_hi:[0,1,1] neg_lo:[1,0,0] neg_hi:[1,0,0]
	v_pk_fma_f32 v[28:29], v[140:141], v[76:77], v[134:135] op_sel_hi:[0,1,1] neg_lo:[1,0,0] neg_hi:[1,0,0]
	ds_read_b128 v[70:73], v112 offset:10496
	ds_read_b128 v[74:77], v112 offset:10512
	ds_write_b32 v108, v142 offset:25472
	s_waitcnt lgkmcnt(8)
	v_pk_mul_f32 v[136:137], v[22:23], v[30:31]
	v_pk_mul_f32 v[138:139], v[22:23], v[96:97]
	v_pk_fma_f32 v[136:137], v[24:25], v[32:33], v[136:137]
	v_pk_fma_f32 v[138:139], v[24:25], v[98:99], v[138:139]
	v_pk_fma_f32 v[136:137], v[26:27], v[34:35], v[136:137]
	v_pk_fma_f32 v[138:139], v[26:27], v[100:101], v[138:139]
	v_pk_fma_f32 v[136:137], v[28:29], v[36:37], v[136:137]
	v_pk_fma_f32 v[138:139], v[28:29], v[102:103], v[138:139]
	ds_read_b128 v[30:33], v112 offset:2560
	ds_read_b128 v[34:37], v112 offset:2576
	ds_read_b128 v[96:99], v112 offset:18688
	ds_read_b128 v[100:103], v112 offset:18704
	v_add_f32_e32 v140, v136, v137
	v_add_f32_e32 v142, v138, v139
	s_waitcnt lgkmcnt(9)
	v_pk_mul_f32 v[128:129], v[78:79], v[104:105] op_sel_hi:[1,0]
	v_add_f32_dpp v140, v140, v140 row_half_mirror row_mask:0xf bank_mask:0xf
	v_add_f32_dpp v142, v142, v142 row_half_mirror row_mask:0xf bank_mask:0xf
	v_pk_mul_f32 v[130:131], v[80:81], v[104:105] op_sel_hi:[1,0]
	v_pk_mul_f32 v[132:133], v[82:83], v[104:105] op_sel_hi:[1,0]
	v_add_f32_dpp v140, v140, v140 quad_perm:[1,0,3,2] row_mask:0xf bank_mask:0xf
	v_add_f32_dpp v142, v142, v142 quad_perm:[1,0,3,2] row_mask:0xf bank_mask:0xf
	v_pk_mul_f32 v[134:135], v[84:85], v[104:105] op_sel_hi:[1,0]
	ds_read_b128 v[78:81], v112 offset:14848
	ds_read_b128 v[82:85], v112 offset:14864
	ds_read_b32 v104, v108 offset:21760
	s_waitcnt lgkmcnt(10)
	v_pk_fma_f32 v[128:129], v[22:23], v[38:39], v[128:129]
	v_add_f32_dpp v140, v140, v140 quad_perm:[2,3,0,1] row_mask:0xf bank_mask:0xf
	v_add_f32_dpp v142, v142, v142 quad_perm:[2,3,0,1] row_mask:0xf bank_mask:0xf
	v_pk_fma_f32 v[130:131], v[24:25], v[40:41], v[130:131]
	v_pk_fma_f32 v[132:133], v[26:27], v[42:43], v[132:133]
	v_pk_fma_f32 v[134:135], v[28:29], v[44:45], v[134:135]
	ds_read_b128 v[38:41], v112 offset:6656
	ds_read_b128 v[42:45], v112 offset:6672
	s_waitcnt lgkmcnt(10)
	v_pk_fma_f32 v[22:23], v[140:141], v[70:71], v[128:129] op_sel_hi:[0,1,1] neg_lo:[1,0,0] neg_hi:[1,0,0]
	v_pk_fma_f32 v[24:25], v[140:141], v[72:73], v[130:131] op_sel_hi:[0,1,1] neg_lo:[1,0,0] neg_hi:[1,0,0]
	v_pk_fma_f32 v[26:27], v[140:141], v[74:75], v[132:133] op_sel_hi:[0,1,1] neg_lo:[1,0,0] neg_hi:[1,0,0]
	v_pk_fma_f32 v[28:29], v[140:141], v[76:77], v[134:135] op_sel_hi:[0,1,1] neg_lo:[1,0,0] neg_hi:[1,0,0]
	ds_read_b128 v[70:73], v112 offset:10752
	ds_read_b128 v[74:77], v112 offset:10768
	ds_write_b32 v108, v142 offset:25600
	s_waitcnt lgkmcnt(8)
	v_pk_mul_f32 v[136:137], v[22:23], v[30:31]
	v_pk_mul_f32 v[138:139], v[22:23], v[96:97]
	v_pk_fma_f32 v[136:137], v[24:25], v[32:33], v[136:137]
	v_pk_fma_f32 v[138:139], v[24:25], v[98:99], v[138:139]
	v_pk_fma_f32 v[136:137], v[26:27], v[34:35], v[136:137]
	v_pk_fma_f32 v[138:139], v[26:27], v[100:101], v[138:139]
	v_pk_fma_f32 v[136:137], v[28:29], v[36:37], v[136:137]
	v_pk_fma_f32 v[138:139], v[28:29], v[102:103], v[138:139]
	ds_read_b128 v[30:33], v112 offset:2816
	ds_read_b128 v[34:37], v112 offset:2832
	ds_read_b128 v[96:99], v112 offset:18944
	ds_read_b128 v[100:103], v112 offset:18960
	v_add_f32_e32 v140, v136, v137
	v_add_f32_e32 v142, v138, v139
	s_waitcnt lgkmcnt(9)
	v_pk_mul_f32 v[128:129], v[78:79], v[104:105] op_sel_hi:[1,0]
	v_add_f32_dpp v140, v140, v140 row_half_mirror row_mask:0xf bank_mask:0xf
	v_add_f32_dpp v142, v142, v142 row_half_mirror row_mask:0xf bank_mask:0xf
	v_pk_mul_f32 v[130:131], v[80:81], v[104:105] op_sel_hi:[1,0]
	v_pk_mul_f32 v[132:133], v[82:83], v[104:105] op_sel_hi:[1,0]
	v_add_f32_dpp v140, v140, v140 quad_perm:[1,0,3,2] row_mask:0xf bank_mask:0xf
	v_add_f32_dpp v142, v142, v142 quad_perm:[1,0,3,2] row_mask:0xf bank_mask:0xf
	v_pk_mul_f32 v[134:135], v[84:85], v[104:105] op_sel_hi:[1,0]
	ds_read_b128 v[78:81], v112 offset:15104
	ds_read_b128 v[82:85], v112 offset:15120
	ds_read_b32 v104, v108 offset:21888
	s_waitcnt lgkmcnt(10)
	v_pk_fma_f32 v[128:129], v[22:23], v[38:39], v[128:129]
	v_add_f32_dpp v140, v140, v140 quad_perm:[2,3,0,1] row_mask:0xf bank_mask:0xf
	v_add_f32_dpp v142, v142, v142 quad_perm:[2,3,0,1] row_mask:0xf bank_mask:0xf
	v_pk_fma_f32 v[130:131], v[24:25], v[40:41], v[130:131]
	v_pk_fma_f32 v[132:133], v[26:27], v[42:43], v[132:133]
	v_pk_fma_f32 v[134:135], v[28:29], v[44:45], v[134:135]
	ds_read_b128 v[38:41], v112 offset:6912
	ds_read_b128 v[42:45], v112 offset:6928
	s_waitcnt lgkmcnt(10)
	v_pk_fma_f32 v[22:23], v[140:141], v[70:71], v[128:129] op_sel_hi:[0,1,1] neg_lo:[1,0,0] neg_hi:[1,0,0]
	v_pk_fma_f32 v[24:25], v[140:141], v[72:73], v[130:131] op_sel_hi:[0,1,1] neg_lo:[1,0,0] neg_hi:[1,0,0]
	v_pk_fma_f32 v[26:27], v[140:141], v[74:75], v[132:133] op_sel_hi:[0,1,1] neg_lo:[1,0,0] neg_hi:[1,0,0]
	v_pk_fma_f32 v[28:29], v[140:141], v[76:77], v[134:135] op_sel_hi:[0,1,1] neg_lo:[1,0,0] neg_hi:[1,0,0]
	ds_read_b128 v[70:73], v112 offset:11008
	ds_read_b128 v[74:77], v112 offset:11024
	ds_write_b32 v108, v142 offset:25728
	s_waitcnt lgkmcnt(8)
	v_pk_mul_f32 v[136:137], v[22:23], v[30:31]
	v_pk_mul_f32 v[138:139], v[22:23], v[96:97]
	v_pk_fma_f32 v[136:137], v[24:25], v[32:33], v[136:137]
	v_pk_fma_f32 v[138:139], v[24:25], v[98:99], v[138:139]
	v_pk_fma_f32 v[136:137], v[26:27], v[34:35], v[136:137]
	v_pk_fma_f32 v[138:139], v[26:27], v[100:101], v[138:139]
	v_pk_fma_f32 v[136:137], v[28:29], v[36:37], v[136:137]
	v_pk_fma_f32 v[138:139], v[28:29], v[102:103], v[138:139]
	ds_read_b128 v[30:33], v112 offset:3072
	ds_read_b128 v[34:37], v112 offset:3088
	ds_read_b128 v[96:99], v112 offset:19200
	ds_read_b128 v[100:103], v112 offset:19216
	v_add_f32_e32 v140, v136, v137
	v_add_f32_e32 v142, v138, v139
	s_waitcnt lgkmcnt(9)
	v_pk_mul_f32 v[128:129], v[78:79], v[104:105] op_sel_hi:[1,0]
	v_add_f32_dpp v140, v140, v140 row_half_mirror row_mask:0xf bank_mask:0xf
	v_add_f32_dpp v142, v142, v142 row_half_mirror row_mask:0xf bank_mask:0xf
	v_pk_mul_f32 v[130:131], v[80:81], v[104:105] op_sel_hi:[1,0]
	v_pk_mul_f32 v[132:133], v[82:83], v[104:105] op_sel_hi:[1,0]
	v_add_f32_dpp v140, v140, v140 quad_perm:[1,0,3,2] row_mask:0xf bank_mask:0xf
	v_add_f32_dpp v142, v142, v142 quad_perm:[1,0,3,2] row_mask:0xf bank_mask:0xf
	v_pk_mul_f32 v[134:135], v[84:85], v[104:105] op_sel_hi:[1,0]
	ds_read_b128 v[78:81], v112 offset:15360
	ds_read_b128 v[82:85], v112 offset:15376
	ds_read_b32 v104, v108 offset:22016
	s_waitcnt lgkmcnt(10)
	v_pk_fma_f32 v[128:129], v[22:23], v[38:39], v[128:129]
	v_add_f32_dpp v140, v140, v140 quad_perm:[2,3,0,1] row_mask:0xf bank_mask:0xf
	v_add_f32_dpp v142, v142, v142 quad_perm:[2,3,0,1] row_mask:0xf bank_mask:0xf
	v_pk_fma_f32 v[130:131], v[24:25], v[40:41], v[130:131]
	v_pk_fma_f32 v[132:133], v[26:27], v[42:43], v[132:133]
	v_pk_fma_f32 v[134:135], v[28:29], v[44:45], v[134:135]
	ds_read_b128 v[38:41], v112 offset:7168
	ds_read_b128 v[42:45], v112 offset:7184
	s_waitcnt lgkmcnt(10)
	v_pk_fma_f32 v[22:23], v[140:141], v[70:71], v[128:129] op_sel_hi:[0,1,1] neg_lo:[1,0,0] neg_hi:[1,0,0]
	v_pk_fma_f32 v[24:25], v[140:141], v[72:73], v[130:131] op_sel_hi:[0,1,1] neg_lo:[1,0,0] neg_hi:[1,0,0]
	v_pk_fma_f32 v[26:27], v[140:141], v[74:75], v[132:133] op_sel_hi:[0,1,1] neg_lo:[1,0,0] neg_hi:[1,0,0]
	v_pk_fma_f32 v[28:29], v[140:141], v[76:77], v[134:135] op_sel_hi:[0,1,1] neg_lo:[1,0,0] neg_hi:[1,0,0]
	ds_read_b128 v[70:73], v112 offset:11264
	ds_read_b128 v[74:77], v112 offset:11280
	ds_write_b32 v108, v142 offset:25856
	s_waitcnt lgkmcnt(8)
	v_pk_mul_f32 v[136:137], v[22:23], v[30:31]
	v_pk_mul_f32 v[138:139], v[22:23], v[96:97]
	v_pk_fma_f32 v[136:137], v[24:25], v[32:33], v[136:137]
	v_pk_fma_f32 v[138:139], v[24:25], v[98:99], v[138:139]
	v_pk_fma_f32 v[136:137], v[26:27], v[34:35], v[136:137]
	v_pk_fma_f32 v[138:139], v[26:27], v[100:101], v[138:139]
	v_pk_fma_f32 v[136:137], v[28:29], v[36:37], v[136:137]
	v_pk_fma_f32 v[138:139], v[28:29], v[102:103], v[138:139]
	ds_read_b128 v[30:33], v112 offset:3328
	ds_read_b128 v[34:37], v112 offset:3344
	ds_read_b128 v[96:99], v112 offset:19456
	ds_read_b128 v[100:103], v112 offset:19472
	v_add_f32_e32 v140, v136, v137
	v_add_f32_e32 v142, v138, v139
	s_waitcnt lgkmcnt(9)
	v_pk_mul_f32 v[128:129], v[78:79], v[104:105] op_sel_hi:[1,0]
	v_add_f32_dpp v140, v140, v140 row_half_mirror row_mask:0xf bank_mask:0xf
	v_add_f32_dpp v142, v142, v142 row_half_mirror row_mask:0xf bank_mask:0xf
	v_pk_mul_f32 v[130:131], v[80:81], v[104:105] op_sel_hi:[1,0]
	v_pk_mul_f32 v[132:133], v[82:83], v[104:105] op_sel_hi:[1,0]
	v_add_f32_dpp v140, v140, v140 quad_perm:[1,0,3,2] row_mask:0xf bank_mask:0xf
	v_add_f32_dpp v142, v142, v142 quad_perm:[1,0,3,2] row_mask:0xf bank_mask:0xf
	v_pk_mul_f32 v[134:135], v[84:85], v[104:105] op_sel_hi:[1,0]
	ds_read_b128 v[78:81], v112 offset:15616
	ds_read_b128 v[82:85], v112 offset:15632
	ds_read_b32 v104, v108 offset:22144
	s_waitcnt lgkmcnt(10)
	v_pk_fma_f32 v[128:129], v[22:23], v[38:39], v[128:129]
	v_add_f32_dpp v140, v140, v140 quad_perm:[2,3,0,1] row_mask:0xf bank_mask:0xf
	v_add_f32_dpp v142, v142, v142 quad_perm:[2,3,0,1] row_mask:0xf bank_mask:0xf
	v_pk_fma_f32 v[130:131], v[24:25], v[40:41], v[130:131]
	v_pk_fma_f32 v[132:133], v[26:27], v[42:43], v[132:133]
	v_pk_fma_f32 v[134:135], v[28:29], v[44:45], v[134:135]
	ds_read_b128 v[38:41], v112 offset:7424
	ds_read_b128 v[42:45], v112 offset:7440
	s_waitcnt lgkmcnt(10)
	v_pk_fma_f32 v[22:23], v[140:141], v[70:71], v[128:129] op_sel_hi:[0,1,1] neg_lo:[1,0,0] neg_hi:[1,0,0]
	v_pk_fma_f32 v[24:25], v[140:141], v[72:73], v[130:131] op_sel_hi:[0,1,1] neg_lo:[1,0,0] neg_hi:[1,0,0]
	v_pk_fma_f32 v[26:27], v[140:141], v[74:75], v[132:133] op_sel_hi:[0,1,1] neg_lo:[1,0,0] neg_hi:[1,0,0]
	v_pk_fma_f32 v[28:29], v[140:141], v[76:77], v[134:135] op_sel_hi:[0,1,1] neg_lo:[1,0,0] neg_hi:[1,0,0]
	ds_read_b128 v[70:73], v112 offset:11520
	ds_read_b128 v[74:77], v112 offset:11536
	ds_write_b32 v108, v142 offset:25984
	s_waitcnt lgkmcnt(8)
	v_pk_mul_f32 v[136:137], v[22:23], v[30:31]
	v_pk_mul_f32 v[138:139], v[22:23], v[96:97]
	v_pk_fma_f32 v[136:137], v[24:25], v[32:33], v[136:137]
	v_pk_fma_f32 v[138:139], v[24:25], v[98:99], v[138:139]
	v_pk_fma_f32 v[136:137], v[26:27], v[34:35], v[136:137]
	v_pk_fma_f32 v[138:139], v[26:27], v[100:101], v[138:139]
	v_pk_fma_f32 v[136:137], v[28:29], v[36:37], v[136:137]
	v_pk_fma_f32 v[138:139], v[28:29], v[102:103], v[138:139]
	ds_read_b128 v[30:33], v112 offset:3584
	ds_read_b128 v[34:37], v112 offset:3600
	ds_read_b128 v[96:99], v112 offset:19712
	ds_read_b128 v[100:103], v112 offset:19728
	v_add_f32_e32 v140, v136, v137
	v_add_f32_e32 v142, v138, v139
	s_waitcnt lgkmcnt(9)
	v_pk_mul_f32 v[128:129], v[78:79], v[104:105] op_sel_hi:[1,0]
	v_add_f32_dpp v140, v140, v140 row_half_mirror row_mask:0xf bank_mask:0xf
	v_add_f32_dpp v142, v142, v142 row_half_mirror row_mask:0xf bank_mask:0xf
	v_pk_mul_f32 v[130:131], v[80:81], v[104:105] op_sel_hi:[1,0]
	v_pk_mul_f32 v[132:133], v[82:83], v[104:105] op_sel_hi:[1,0]
	v_add_f32_dpp v140, v140, v140 quad_perm:[1,0,3,2] row_mask:0xf bank_mask:0xf
	v_add_f32_dpp v142, v142, v142 quad_perm:[1,0,3,2] row_mask:0xf bank_mask:0xf
	v_pk_mul_f32 v[134:135], v[84:85], v[104:105] op_sel_hi:[1,0]
	ds_read_b128 v[78:81], v112 offset:15872
	ds_read_b128 v[82:85], v112 offset:15888
	ds_read_b32 v104, v108 offset:22272
	s_waitcnt lgkmcnt(10)
	v_pk_fma_f32 v[128:129], v[22:23], v[38:39], v[128:129]
	v_add_f32_dpp v140, v140, v140 quad_perm:[2,3,0,1] row_mask:0xf bank_mask:0xf
	v_add_f32_dpp v142, v142, v142 quad_perm:[2,3,0,1] row_mask:0xf bank_mask:0xf
	v_pk_fma_f32 v[130:131], v[24:25], v[40:41], v[130:131]
	v_pk_fma_f32 v[132:133], v[26:27], v[42:43], v[132:133]
	v_pk_fma_f32 v[134:135], v[28:29], v[44:45], v[134:135]
	ds_read_b128 v[38:41], v112 offset:7680
	ds_read_b128 v[42:45], v112 offset:7696
	s_waitcnt lgkmcnt(10)
	v_pk_fma_f32 v[22:23], v[140:141], v[70:71], v[128:129] op_sel_hi:[0,1,1] neg_lo:[1,0,0] neg_hi:[1,0,0]
	v_pk_fma_f32 v[24:25], v[140:141], v[72:73], v[130:131] op_sel_hi:[0,1,1] neg_lo:[1,0,0] neg_hi:[1,0,0]
	v_pk_fma_f32 v[26:27], v[140:141], v[74:75], v[132:133] op_sel_hi:[0,1,1] neg_lo:[1,0,0] neg_hi:[1,0,0]
	v_pk_fma_f32 v[28:29], v[140:141], v[76:77], v[134:135] op_sel_hi:[0,1,1] neg_lo:[1,0,0] neg_hi:[1,0,0]
	ds_read_b128 v[70:73], v112 offset:11776
	ds_read_b128 v[74:77], v112 offset:11792
	ds_write_b32 v108, v142 offset:26112
	s_waitcnt lgkmcnt(8)
	v_pk_mul_f32 v[136:137], v[22:23], v[30:31]
	v_pk_mul_f32 v[138:139], v[22:23], v[96:97]
	v_pk_fma_f32 v[136:137], v[24:25], v[32:33], v[136:137]
	v_pk_fma_f32 v[138:139], v[24:25], v[98:99], v[138:139]
	v_pk_fma_f32 v[136:137], v[26:27], v[34:35], v[136:137]
	v_pk_fma_f32 v[138:139], v[26:27], v[100:101], v[138:139]
	v_pk_fma_f32 v[136:137], v[28:29], v[36:37], v[136:137]
	v_pk_fma_f32 v[138:139], v[28:29], v[102:103], v[138:139]
	ds_read_b128 v[30:33], v112 offset:3840
	ds_read_b128 v[34:37], v112 offset:3856
	ds_read_b128 v[96:99], v112 offset:19968
	ds_read_b128 v[100:103], v112 offset:19984
	v_add_f32_e32 v140, v136, v137
	v_add_f32_e32 v142, v138, v139
	s_waitcnt lgkmcnt(9)
	v_pk_mul_f32 v[128:129], v[78:79], v[104:105] op_sel_hi:[1,0]
	v_add_f32_dpp v140, v140, v140 row_half_mirror row_mask:0xf bank_mask:0xf
	v_add_f32_dpp v142, v142, v142 row_half_mirror row_mask:0xf bank_mask:0xf
	v_pk_mul_f32 v[130:131], v[80:81], v[104:105] op_sel_hi:[1,0]
	v_pk_mul_f32 v[132:133], v[82:83], v[104:105] op_sel_hi:[1,0]
	v_add_f32_dpp v140, v140, v140 quad_perm:[1,0,3,2] row_mask:0xf bank_mask:0xf
	v_add_f32_dpp v142, v142, v142 quad_perm:[1,0,3,2] row_mask:0xf bank_mask:0xf
	v_pk_mul_f32 v[134:135], v[84:85], v[104:105] op_sel_hi:[1,0]
	ds_read_b128 v[78:81], v112 offset:16128
	ds_read_b128 v[82:85], v112 offset:16144
	ds_read_b32 v104, v108 offset:22400
	s_waitcnt lgkmcnt(10)
	v_pk_fma_f32 v[128:129], v[22:23], v[38:39], v[128:129]
	v_add_f32_dpp v140, v140, v140 quad_perm:[2,3,0,1] row_mask:0xf bank_mask:0xf
	v_add_f32_dpp v142, v142, v142 quad_perm:[2,3,0,1] row_mask:0xf bank_mask:0xf
	v_pk_fma_f32 v[130:131], v[24:25], v[40:41], v[130:131]
	v_pk_fma_f32 v[132:133], v[26:27], v[42:43], v[132:133]
	v_pk_fma_f32 v[134:135], v[28:29], v[44:45], v[134:135]
	ds_read_b128 v[38:41], v112 offset:7936
	ds_read_b128 v[42:45], v112 offset:7952
	s_waitcnt lgkmcnt(10)
	v_pk_fma_f32 v[22:23], v[140:141], v[70:71], v[128:129] op_sel_hi:[0,1,1] neg_lo:[1,0,0] neg_hi:[1,0,0]
	v_pk_fma_f32 v[24:25], v[140:141], v[72:73], v[130:131] op_sel_hi:[0,1,1] neg_lo:[1,0,0] neg_hi:[1,0,0]
	v_pk_fma_f32 v[26:27], v[140:141], v[74:75], v[132:133] op_sel_hi:[0,1,1] neg_lo:[1,0,0] neg_hi:[1,0,0]
	v_pk_fma_f32 v[28:29], v[140:141], v[76:77], v[134:135] op_sel_hi:[0,1,1] neg_lo:[1,0,0] neg_hi:[1,0,0]
	ds_read_b128 v[70:73], v112 offset:12032
	ds_read_b128 v[74:77], v112 offset:12048
	ds_write_b32 v108, v142 offset:26240
	s_waitcnt lgkmcnt(8)
	v_pk_mul_f32 v[136:137], v[22:23], v[30:31]
	v_pk_mul_f32 v[138:139], v[22:23], v[96:97]
	v_pk_fma_f32 v[136:137], v[24:25], v[32:33], v[136:137]
	v_pk_fma_f32 v[138:139], v[24:25], v[98:99], v[138:139]
	v_pk_fma_f32 v[136:137], v[26:27], v[34:35], v[136:137]
	v_pk_fma_f32 v[138:139], v[26:27], v[100:101], v[138:139]
	v_pk_fma_f32 v[136:137], v[28:29], v[36:37], v[136:137]
	v_pk_fma_f32 v[138:139], v[28:29], v[102:103], v[138:139]
	ds_read_b128 v[96:99], v112 offset:20224
	ds_read_b128 v[100:103], v112 offset:20240
	v_add_f32_e32 v140, v136, v137
	v_add_f32_e32 v142, v138, v139
	s_waitcnt lgkmcnt(7)
	v_pk_mul_f32 v[128:129], v[78:79], v[104:105] op_sel_hi:[1,0]
	v_add_f32_dpp v140, v140, v140 row_half_mirror row_mask:0xf bank_mask:0xf
	v_add_f32_dpp v142, v142, v142 row_half_mirror row_mask:0xf bank_mask:0xf
	v_pk_mul_f32 v[130:131], v[80:81], v[104:105] op_sel_hi:[1,0]
	v_pk_mul_f32 v[132:133], v[82:83], v[104:105] op_sel_hi:[1,0]
	v_add_f32_dpp v140, v140, v140 quad_perm:[1,0,3,2] row_mask:0xf bank_mask:0xf
	v_add_f32_dpp v142, v142, v142 quad_perm:[1,0,3,2] row_mask:0xf bank_mask:0xf
	v_pk_mul_f32 v[134:135], v[84:85], v[104:105] op_sel_hi:[1,0]
	s_waitcnt lgkmcnt(5)
	v_pk_fma_f32 v[128:129], v[22:23], v[38:39], v[128:129]
	v_add_f32_dpp v140, v140, v140 quad_perm:[2,3,0,1] row_mask:0xf bank_mask:0xf
	v_add_f32_dpp v142, v142, v142 quad_perm:[2,3,0,1] row_mask:0xf bank_mask:0xf
	v_pk_fma_f32 v[130:131], v[24:25], v[40:41], v[130:131]
	v_pk_fma_f32 v[132:133], v[26:27], v[42:43], v[132:133]
	v_pk_fma_f32 v[134:135], v[28:29], v[44:45], v[134:135]
	s_waitcnt lgkmcnt(3)
	v_pk_fma_f32 v[22:23], v[140:141], v[70:71], v[128:129] op_sel_hi:[0,1,1] neg_lo:[1,0,0] neg_hi:[1,0,0]
	v_pk_fma_f32 v[24:25], v[140:141], v[72:73], v[130:131] op_sel_hi:[0,1,1] neg_lo:[1,0,0] neg_hi:[1,0,0]
	v_pk_fma_f32 v[26:27], v[140:141], v[74:75], v[132:133] op_sel_hi:[0,1,1] neg_lo:[1,0,0] neg_hi:[1,0,0]
	v_pk_fma_f32 v[28:29], v[140:141], v[76:77], v[134:135] op_sel_hi:[0,1,1] neg_lo:[1,0,0] neg_hi:[1,0,0]
	ds_write_b32 v108, v142 offset:26368
	s_waitcnt lgkmcnt(1)
	v_pk_mul_f32 v[138:139], v[22:23], v[96:97]
	v_pk_fma_f32 v[138:139], v[24:25], v[98:99], v[138:139]
	v_pk_fma_f32 v[138:139], v[26:27], v[100:101], v[138:139]
	v_pk_fma_f32 v[138:139], v[28:29], v[102:103], v[138:139]
	v_add_f32_e32 v142, v138, v139
	s_nop 1
	v_add_f32_dpp v142, v142, v142 row_half_mirror row_mask:0xf bank_mask:0xf
	s_nop 1
	v_add_f32_dpp v142, v142, v142 quad_perm:[1,0,3,2] row_mask:0xf bank_mask:0xf
	s_nop 1
	v_add_f32_dpp v142, v142, v142 quad_perm:[2,3,0,1] row_mask:0xf bank_mask:0xf
	ds_write_b32 v108, v142 offset:26496
	s_branch .Lrw0_u2e1
.Lrw0_u2s1:
	ds_read_b128 v[30:33], v112 offset:0
	ds_read_b128 v[34:37], v112 offset:16
	ds_read_b128 v[38:41], v112 offset:4096
	ds_read_b128 v[42:45], v112 offset:4112
	ds_read_b128 v[70:73], v112 offset:8192
	ds_read_b128 v[74:77], v112 offset:8208
	s_waitcnt lgkmcnt(4)
	v_pk_mul_f32 v[136:137], v[22:23], v[30:31]
	v_pk_fma_f32 v[136:137], v[24:25], v[32:33], v[136:137]
	v_pk_fma_f32 v[136:137], v[26:27], v[34:35], v[136:137]
	v_pk_fma_f32 v[136:137], v[28:29], v[36:37], v[136:137]
	ds_read_b128 v[30:33], v112 offset:256
	ds_read_b128 v[34:37], v112 offset:272
	ds_read_b128 v[96:99], v112 offset:16384
	ds_read_b128 v[100:103], v112 offset:16400
	v_add_f32_e32 v140, v136, v137
	s_waitcnt lgkmcnt(6)
	v_pk_mul_f32 v[128:129], v[22:23], v[38:39]
	v_add_f32_dpp v140, v140, v140 row_half_mirror row_mask:0xf bank_mask:0xf
	v_pk_mul_f32 v[130:131], v[24:25], v[40:41]
	v_pk_mul_f32 v[132:133], v[26:27], v[42:43]
	v_pk_mul_f32 v[134:135], v[28:29], v[44:45]
	ds_read_b128 v[38:41], v112 offset:4352
	ds_read_b128 v[42:45], v112 offset:4368
	v_add_f32_dpp v140, v140, v140 quad_perm:[1,0,3,2] row_mask:0xf bank_mask:0xf
	s_nop 1
	v_add_f32_dpp v140, v140, v140 quad_perm:[2,3,0,1] row_mask:0xf bank_mask:0xf
	s_waitcnt lgkmcnt(6)
	v_pk_fma_f32 v[22:23], v[140:141], v[70:71], v[128:129] op_sel_hi:[0,1,1] neg_lo:[1,0,0] neg_hi:[1,0,0]
	v_pk_fma_f32 v[24:25], v[140:141], v[72:73], v[130:131] op_sel_hi:[0,1,1] neg_lo:[1,0,0] neg_hi:[1,0,0]
	v_pk_fma_f32 v[26:27], v[140:141], v[74:75], v[132:133] op_sel_hi:[0,1,1] neg_lo:[1,0,0] neg_hi:[1,0,0]
	v_pk_fma_f32 v[28:29], v[140:141], v[76:77], v[134:135] op_sel_hi:[0,1,1] neg_lo:[1,0,0] neg_hi:[1,0,0]
	ds_read_b128 v[70:73], v112 offset:8448
	ds_read_b128 v[74:77], v112 offset:8464
	s_waitcnt lgkmcnt(4)
	v_pk_mul_f32 v[136:137], v[22:23], v[30:31]
	v_pk_mul_f32 v[138:139], v[22:23], v[96:97]
	v_pk_fma_f32 v[136:137], v[24:25], v[32:33], v[136:137]
	v_pk_fma_f32 v[138:139], v[24:25], v[98:99], v[138:139]
	v_pk_fma_f32 v[136:137], v[26:27], v[34:35], v[136:137]
	v_pk_fma_f32 v[138:139], v[26:27], v[100:101], v[138:139]
	v_pk_fma_f32 v[136:137], v[28:29], v[36:37], v[136:137]
	v_pk_fma_f32 v[138:139], v[28:29], v[102:103], v[138:139]
	ds_read_b128 v[30:33], v112 offset:512
	ds_read_b128 v[34:37], v112 offset:528
	ds_read_b128 v[96:99], v112 offset:16640
	ds_read_b128 v[100:103], v112 offset:16656
	v_add_f32_e32 v140, v136, v137
	v_add_f32_e32 v142, v138, v139
	s_waitcnt lgkmcnt(6)
	v_pk_mul_f32 v[128:129], v[22:23], v[38:39]
	v_add_f32_dpp v140, v140, v140 row_half_mirror row_mask:0xf bank_mask:0xf
	v_add_f32_dpp v142, v142, v142 row_half_mirror row_mask:0xf bank_mask:0xf
	v_pk_mul_f32 v[130:131], v[24:25], v[40:41]
	v_pk_mul_f32 v[132:133], v[26:27], v[42:43]
	v_add_f32_dpp v140, v140, v140 quad_perm:[1,0,3,2] row_mask:0xf bank_mask:0xf
	v_add_f32_dpp v142, v142, v142 quad_perm:[1,0,3,2] row_mask:0xf bank_mask:0xf
	v_pk_mul_f32 v[134:135], v[28:29], v[44:45]
	ds_read_b128 v[38:41], v112 offset:4608
	ds_read_b128 v[42:45], v112 offset:4624
	v_add_f32_dpp v140, v140, v140 quad_perm:[2,3,0,1] row_mask:0xf bank_mask:0xf
	v_add_f32_dpp v142, v142, v142 quad_perm:[2,3,0,1] row_mask:0xf bank_mask:0xf
	s_waitcnt lgkmcnt(6)
	v_pk_fma_f32 v[22:23], v[140:141], v[70:71], v[128:129] op_sel_hi:[0,1,1] neg_lo:[1,0,0] neg_hi:[1,0,0]
	v_pk_fma_f32 v[24:25], v[140:141], v[72:73], v[130:131] op_sel_hi:[0,1,1] neg_lo:[1,0,0] neg_hi:[1,0,0]
	v_pk_fma_f32 v[26:27], v[140:141], v[74:75], v[132:133] op_sel_hi:[0,1,1] neg_lo:[1,0,0] neg_hi:[1,0,0]
	v_pk_fma_f32 v[28:29], v[140:141], v[76:77], v[134:135] op_sel_hi:[0,1,1] neg_lo:[1,0,0] neg_hi:[1,0,0]
	ds_read_b128 v[70:73], v112 offset:8704
	ds_read_b128 v[74:77], v112 offset:8720
	ds_write_b32 v108, v142 offset:24576
	s_waitcnt lgkmcnt(5)
	v_pk_mul_f32 v[136:137], v[22:23], v[30:31]
	v_pk_mul_f32 v[138:139], v[22:23], v[96:97]
	v_pk_fma_f32 v[136:137], v[24:25], v[32:33], v[136:137]
	v_pk_fma_f32 v[138:139], v[24:25], v[98:99], v[138:139]
	v_pk_fma_f32 v[136:137], v[26:27], v[34:35], v[136:137]
	v_pk_fma_f32 v[138:139], v[26:27], v[100:101], v[138:139]
	v_pk_fma_f32 v[136:137], v[28:29], v[36:37], v[136:137]
	v_pk_fma_f32 v[138:139], v[28:29], v[102:103], v[138:139]
	ds_read_b128 v[30:33], v112 offset:768
	ds_read_b128 v[34:37], v112 offset:784
	ds_read_b128 v[96:99], v112 offset:16896
	ds_read_b128 v[100:103], v112 offset:16912
	v_add_f32_e32 v140, v136, v137
	v_add_f32_e32 v142, v138, v139
	s_waitcnt lgkmcnt(7)
	v_pk_mul_f32 v[128:129], v[22:23], v[38:39]
	v_add_f32_dpp v140, v140, v140 row_half_mirror row_mask:0xf bank_mask:0xf
	v_add_f32_dpp v142, v142, v142 row_half_mirror row_mask:0xf bank_mask:0xf
	v_pk_mul_f32 v[130:131], v[24:25], v[40:41]
	v_pk_mul_f32 v[132:133], v[26:27], v[42:43]
	v_add_f32_dpp v140, v140, v140 quad_perm:[1,0,3,2] row_mask:0xf bank_mask:0xf
	v_add_f32_dpp v142, v142, v142 quad_perm:[1,0,3,2] row_mask:0xf bank_mask:0xf
	v_pk_mul_f32 v[134:135], v[28:29], v[44:45]
	ds_read_b128 v[38:41], v112 offset:4864
	ds_read_b128 v[42:45], v112 offset:4880
	v_add_f32_dpp v140, v140, v140 quad_perm:[2,3,0,1] row_mask:0xf bank_mask:0xf
	v_add_f32_dpp v142, v142, v142 quad_perm:[2,3,0,1] row_mask:0xf bank_mask:0xf
	s_waitcnt lgkmcnt(7)
	v_pk_fma_f32 v[22:23], v[140:141], v[70:71], v[128:129] op_sel_hi:[0,1,1] neg_lo:[1,0,0] neg_hi:[1,0,0]
	v_pk_fma_f32 v[24:25], v[140:141], v[72:73], v[130:131] op_sel_hi:[0,1,1] neg_lo:[1,0,0] neg_hi:[1,0,0]
	v_pk_fma_f32 v[26:27], v[140:141], v[74:75], v[132:133] op_sel_hi:[0,1,1] neg_lo:[1,0,0] neg_hi:[1,0,0]
	v_pk_fma_f32 v[28:29], v[140:141], v[76:77], v[134:135] op_sel_hi:[0,1,1] neg_lo:[1,0,0] neg_hi:[1,0,0]
	ds_read_b128 v[70:73], v112 offset:8960
	ds_read_b128 v[74:77], v112 offset:8976
	ds_write_b32 v108, v142 offset:24704
	s_waitcnt lgkmcnt(5)
	v_pk_mul_f32 v[136:137], v[22:23], v[30:31]
	v_pk_mul_f32 v[138:139], v[22:23], v[96:97]
	v_pk_fma_f32 v[136:137], v[24:25], v[32:33], v[136:137]
	v_pk_fma_f32 v[138:139], v[24:25], v[98:99], v[138:139]
	v_pk_fma_f32 v[136:137], v[26:27], v[34:35], v[136:137]
	v_pk_fma_f32 v[138:139], v[26:27], v[100:101], v[138:139]
	v_pk_fma_f32 v[136:137], v[28:29], v[36:37], v[136:137]
	v_pk_fma_f32 v[138:139], v[28:29], v[102:103], v[138:139]
	ds_read_b128 v[30:33], v112 offset:1024
	ds_read_b128 v[34:37], v112 offset:1040
	ds_read_b128 v[96:99], v112 offset:17152
	ds_read_b128 v[100:103], v112 offset:17168
	v_add_f32_e32 v140, v136, v137
	v_add_f32_e32 v142, v138, v139
	s_waitcnt lgkmcnt(7)
	v_pk_mul_f32 v[128:129], v[22:23], v[38:39]
	v_add_f32_dpp v140, v140, v140 row_half_mirror row_mask:0xf bank_mask:0xf
	v_add_f32_dpp v142, v142, v142 row_half_mirror row_mask:0xf bank_mask:0xf
	v_pk_mul_f32 v[130:131], v[24:25], v[40:41]
	v_pk_mul_f32 v[132:133], v[26:27], v[42:43]
	v_add_f32_dpp v140, v140, v140 quad_perm:[1,0,3,2] row_mask:0xf bank_mask:0xf
	v_add_f32_dpp v142, v142, v142 quad_perm:[1,0,3,2] row_mask:0xf bank_mask:0xf
	v_pk_mul_f32 v[134:135], v[28:29], v[44:45]
	ds_read_b128 v[38:41], v112 offset:5120
	ds_read_b128 v[42:45], v112 offset:5136
	v_add_f32_dpp v140, v140, v140 quad_perm:[2,3,0,1] row_mask:0xf bank_mask:0xf
	v_add_f32_dpp v142, v142, v142 quad_perm:[2,3,0,1] row_mask:0xf bank_mask:0xf
	s_waitcnt lgkmcnt(7)
	v_pk_fma_f32 v[22:23], v[140:141], v[70:71], v[128:129] op_sel_hi:[0,1,1] neg_lo:[1,0,0] neg_hi:[1,0,0]
	v_pk_fma_f32 v[24:25], v[140:141], v[72:73], v[130:131] op_sel_hi:[0,1,1] neg_lo:[1,0,0] neg_hi:[1,0,0]
	v_pk_fma_f32 v[26:27], v[140:141], v[74:75], v[132:133] op_sel_hi:[0,1,1] neg_lo:[1,0,0] neg_hi:[1,0,0]
	v_pk_fma_f32 v[28:29], v[140:141], v[76:77], v[134:135] op_sel_hi:[0,1,1] neg_lo:[1,0,0] neg_hi:[1,0,0]
	ds_read_b128 v[70:73], v112 offset:9216
	ds_read_b128 v[74:77], v112 offset:9232
	ds_write_b32 v108, v142 offset:24832
	s_waitcnt lgkmcnt(5)
	v_pk_mul_f32 v[136:137], v[22:23], v[30:31]
	v_pk_mul_f32 v[138:139], v[22:23], v[96:97]
	v_pk_fma_f32 v[136:137], v[24:25], v[32:33], v[136:137]
	v_pk_fma_f32 v[138:139], v[24:25], v[98:99], v[138:139]
	v_pk_fma_f32 v[136:137], v[26:27], v[34:35], v[136:137]
	v_pk_fma_f32 v[138:139], v[26:27], v[100:101], v[138:139]
	v_pk_fma_f32 v[136:137], v[28:29], v[36:37], v[136:137]
	v_pk_fma_f32 v[138:139], v[28:29], v[102:103], v[138:139]
	ds_read_b128 v[30:33], v112 offset:1280
	ds_read_b128 v[34:37], v112 offset:1296
	ds_read_b128 v[96:99], v112 offset:17408
	ds_read_b128 v[100:103], v112 offset:17424
	v_add_f32_e32 v140, v136, v137
	v_add_f32_e32 v142, v138, v139
	s_waitcnt lgkmcnt(7)
	v_pk_mul_f32 v[128:129], v[22:23], v[38:39]
	v_add_f32_dpp v140, v140, v140 row_half_mirror row_mask:0xf bank_mask:0xf
	v_add_f32_dpp v142, v142, v142 row_half_mirror row_mask:0xf bank_mask:0xf
	v_pk_mul_f32 v[130:131], v[24:25], v[40:41]
	v_pk_mul_f32 v[132:133], v[26:27], v[42:43]
	v_add_f32_dpp v140, v140, v140 quad_perm:[1,0,3,2] row_mask:0xf bank_mask:0xf
	v_add_f32_dpp v142, v142, v142 quad_perm:[1,0,3,2] row_mask:0xf bank_mask:0xf
	v_pk_mul_f32 v[134:135], v[28:29], v[44:45]
	ds_read_b128 v[38:41], v112 offset:5376
	ds_read_b128 v[42:45], v112 offset:5392
	v_add_f32_dpp v140, v140, v140 quad_perm:[2,3,0,1] row_mask:0xf bank_mask:0xf
	v_add_f32_dpp v142, v142, v142 quad_perm:[2,3,0,1] row_mask:0xf bank_mask:0xf
	s_waitcnt lgkmcnt(7)
	v_pk_fma_f32 v[22:23], v[140:141], v[70:71], v[128:129] op_sel_hi:[0,1,1] neg_lo:[1,0,0] neg_hi:[1,0,0]
	v_pk_fma_f32 v[24:25], v[140:141], v[72:73], v[130:131] op_sel_hi:[0,1,1] neg_lo:[1,0,0] neg_hi:[1,0,0]
	v_pk_fma_f32 v[26:27], v[140:141], v[74:75], v[132:133] op_sel_hi:[0,1,1] neg_lo:[1,0,0] neg_hi:[1,0,0]
	v_pk_fma_f32 v[28:29], v[140:141], v[76:77], v[134:135] op_sel_hi:[0,1,1] neg_lo:[1,0,0] neg_hi:[1,0,0]
	ds_read_b128 v[70:73], v112 offset:9472
	ds_read_b128 v[74:77], v112 offset:9488
	ds_write_b32 v108, v142 offset:24960
	s_waitcnt lgkmcnt(5)
	v_pk_mul_f32 v[136:137], v[22:23], v[30:31]
	v_pk_mul_f32 v[138:139], v[22:23], v[96:97]
	v_pk_fma_f32 v[136:137], v[24:25], v[32:33], v[136:137]
	v_pk_fma_f32 v[138:139], v[24:25], v[98:99], v[138:139]
	v_pk_fma_f32 v[136:137], v[26:27], v[34:35], v[136:137]
	v_pk_fma_f32 v[138:139], v[26:27], v[100:101], v[138:139]
	v_pk_fma_f32 v[136:137], v[28:29], v[36:37], v[136:137]
	v_pk_fma_f32 v[138:139], v[28:29], v[102:103], v[138:139]
	ds_read_b128 v[30:33], v112 offset:1536
	ds_read_b128 v[34:37], v112 offset:1552
	ds_read_b128 v[96:99], v112 offset:17664
	ds_read_b128 v[100:103], v112 offset:17680
	v_add_f32_e32 v140, v136, v137
	v_add_f32_e32 v142, v138, v139
	s_waitcnt lgkmcnt(7)
	v_pk_mul_f32 v[128:129], v[22:23], v[38:39]
	v_add_f32_dpp v140, v140, v140 row_half_mirror row_mask:0xf bank_mask:0xf
	v_add_f32_dpp v142, v142, v142 row_half_mirror row_mask:0xf bank_mask:0xf
	v_pk_mul_f32 v[130:131], v[24:25], v[40:41]
	v_pk_mul_f32 v[132:133], v[26:27], v[42:43]
	v_add_f32_dpp v140, v140, v140 quad_perm:[1,0,3,2] row_mask:0xf bank_mask:0xf
	v_add_f32_dpp v142, v142, v142 quad_perm:[1,0,3,2] row_mask:0xf bank_mask:0xf
	v_pk_mul_f32 v[134:135], v[28:29], v[44:45]
	ds_read_b128 v[38:41], v112 offset:5632
	ds_read_b128 v[42:45], v112 offset:5648
	v_add_f32_dpp v140, v140, v140 quad_perm:[2,3,0,1] row_mask:0xf bank_mask:0xf
	v_add_f32_dpp v142, v142, v142 quad_perm:[2,3,0,1] row_mask:0xf bank_mask:0xf
	s_waitcnt lgkmcnt(7)
	v_pk_fma_f32 v[22:23], v[140:141], v[70:71], v[128:129] op_sel_hi:[0,1,1] neg_lo:[1,0,0] neg_hi:[1,0,0]
	v_pk_fma_f32 v[24:25], v[140:141], v[72:73], v[130:131] op_sel_hi:[0,1,1] neg_lo:[1,0,0] neg_hi:[1,0,0]
	v_pk_fma_f32 v[26:27], v[140:141], v[74:75], v[132:133] op_sel_hi:[0,1,1] neg_lo:[1,0,0] neg_hi:[1,0,0]
	v_pk_fma_f32 v[28:29], v[140:141], v[76:77], v[134:135] op_sel_hi:[0,1,1] neg_lo:[1,0,0] neg_hi:[1,0,0]
	ds_read_b128 v[70:73], v112 offset:9728
	ds_read_b128 v[74:77], v112 offset:9744
	ds_write_b32 v108, v142 offset:25088
	s_waitcnt lgkmcnt(5)
	v_pk_mul_f32 v[136:137], v[22:23], v[30:31]
	v_pk_mul_f32 v[138:139], v[22:23], v[96:97]
	v_pk_fma_f32 v[136:137], v[24:25], v[32:33], v[136:137]
	v_pk_fma_f32 v[138:139], v[24:25], v[98:99], v[138:139]
	v_pk_fma_f32 v[136:137], v[26:27], v[34:35], v[136:137]
	v_pk_fma_f32 v[138:139], v[26:27], v[100:101], v[138:139]
	v_pk_fma_f32 v[136:137], v[28:29], v[36:37], v[136:137]
	v_pk_fma_f32 v[138:139], v[28:29], v[102:103], v[138:139]
	ds_read_b128 v[30:33], v112 offset:1792
	ds_read_b128 v[34:37], v112 offset:1808
	ds_read_b128 v[96:99], v112 offset:17920
	ds_read_b128 v[100:103], v112 offset:17936
	v_add_f32_e32 v140, v136, v137
	v_add_f32_e32 v142, v138, v139
	s_waitcnt lgkmcnt(7)
	v_pk_mul_f32 v[128:129], v[22:23], v[38:39]
	v_add_f32_dpp v140, v140, v140 row_half_mirror row_mask:0xf bank_mask:0xf
	v_add_f32_dpp v142, v142, v142 row_half_mirror row_mask:0xf bank_mask:0xf
	v_pk_mul_f32 v[130:131], v[24:25], v[40:41]
	v_pk_mul_f32 v[132:133], v[26:27], v[42:43]
	v_add_f32_dpp v140, v140, v140 quad_perm:[1,0,3,2] row_mask:0xf bank_mask:0xf
	v_add_f32_dpp v142, v142, v142 quad_perm:[1,0,3,2] row_mask:0xf bank_mask:0xf
	v_pk_mul_f32 v[134:135], v[28:29], v[44:45]
	ds_read_b128 v[38:41], v112 offset:5888
	ds_read_b128 v[42:45], v112 offset:5904
	v_add_f32_dpp v140, v140, v140 quad_perm:[2,3,0,1] row_mask:0xf bank_mask:0xf
	v_add_f32_dpp v142, v142, v142 quad_perm:[2,3,0,1] row_mask:0xf bank_mask:0xf
	s_waitcnt lgkmcnt(7)
	v_pk_fma_f32 v[22:23], v[140:141], v[70:71], v[128:129] op_sel_hi:[0,1,1] neg_lo:[1,0,0] neg_hi:[1,0,0]
	v_pk_fma_f32 v[24:25], v[140:141], v[72:73], v[130:131] op_sel_hi:[0,1,1] neg_lo:[1,0,0] neg_hi:[1,0,0]
	v_pk_fma_f32 v[26:27], v[140:141], v[74:75], v[132:133] op_sel_hi:[0,1,1] neg_lo:[1,0,0] neg_hi:[1,0,0]
	v_pk_fma_f32 v[28:29], v[140:141], v[76:77], v[134:135] op_sel_hi:[0,1,1] neg_lo:[1,0,0] neg_hi:[1,0,0]
	ds_read_b128 v[70:73], v112 offset:9984
	ds_read_b128 v[74:77], v112 offset:10000
	ds_write_b32 v108, v142 offset:25216
	s_waitcnt lgkmcnt(5)
	v_pk_mul_f32 v[136:137], v[22:23], v[30:31]
	v_pk_mul_f32 v[138:139], v[22:23], v[96:97]
	v_pk_fma_f32 v[136:137], v[24:25], v[32:33], v[136:137]
	v_pk_fma_f32 v[138:139], v[24:25], v[98:99], v[138:139]
	v_pk_fma_f32 v[136:137], v[26:27], v[34:35], v[136:137]
	v_pk_fma_f32 v[138:139], v[26:27], v[100:101], v[138:139]
	v_pk_fma_f32 v[136:137], v[28:29], v[36:37], v[136:137]
	v_pk_fma_f32 v[138:139], v[28:29], v[102:103], v[138:139]
	ds_read_b128 v[30:33], v112 offset:2048
	ds_read_b128 v[34:37], v112 offset:2064
	ds_read_b128 v[96:99], v112 offset:18176
	ds_read_b128 v[100:103], v112 offset:18192
	v_add_f32_e32 v140, v136, v137
	v_add_f32_e32 v142, v138, v139
	s_waitcnt lgkmcnt(7)
	v_pk_mul_f32 v[128:129], v[22:23], v[38:39]
	v_add_f32_dpp v140, v140, v140 row_half_mirror row_mask:0xf bank_mask:0xf
	v_add_f32_dpp v142, v142, v142 row_half_mirror row_mask:0xf bank_mask:0xf
	v_pk_mul_f32 v[130:131], v[24:25], v[40:41]
	v_pk_mul_f32 v[132:133], v[26:27], v[42:43]
	v_add_f32_dpp v140, v140, v140 quad_perm:[1,0,3,2] row_mask:0xf bank_mask:0xf
	v_add_f32_dpp v142, v142, v142 quad_perm:[1,0,3,2] row_mask:0xf bank_mask:0xf
	v_pk_mul_f32 v[134:135], v[28:29], v[44:45]
	ds_read_b128 v[38:41], v112 offset:6144
	ds_read_b128 v[42:45], v112 offset:6160
	v_add_f32_dpp v140, v140, v140 quad_perm:[2,3,0,1] row_mask:0xf bank_mask:0xf
	v_add_f32_dpp v142, v142, v142 quad_perm:[2,3,0,1] row_mask:0xf bank_mask:0xf
	s_waitcnt lgkmcnt(7)
	v_pk_fma_f32 v[22:23], v[140:141], v[70:71], v[128:129] op_sel_hi:[0,1,1] neg_lo:[1,0,0] neg_hi:[1,0,0]
	v_pk_fma_f32 v[24:25], v[140:141], v[72:73], v[130:131] op_sel_hi:[0,1,1] neg_lo:[1,0,0] neg_hi:[1,0,0]
	v_pk_fma_f32 v[26:27], v[140:141], v[74:75], v[132:133] op_sel_hi:[0,1,1] neg_lo:[1,0,0] neg_hi:[1,0,0]
	v_pk_fma_f32 v[28:29], v[140:141], v[76:77], v[134:135] op_sel_hi:[0,1,1] neg_lo:[1,0,0] neg_hi:[1,0,0]
	ds_read_b128 v[70:73], v112 offset:10240
	ds_read_b128 v[74:77], v112 offset:10256
	ds_write_b32 v108, v142 offset:25344
	s_waitcnt lgkmcnt(5)
	v_pk_mul_f32 v[136:137], v[22:23], v[30:31]
	v_pk_mul_f32 v[138:139], v[22:23], v[96:97]
	v_pk_fma_f32 v[136:137], v[24:25], v[32:33], v[136:137]
	v_pk_fma_f32 v[138:139], v[24:25], v[98:99], v[138:139]
	v_pk_fma_f32 v[136:137], v[26:27], v[34:35], v[136:137]
	v_pk_fma_f32 v[138:139], v[26:27], v[100:101], v[138:139]
	v_pk_fma_f32 v[136:137], v[28:29], v[36:37], v[136:137]
	v_pk_fma_f32 v[138:139], v[28:29], v[102:103], v[138:139]
	ds_read_b128 v[30:33], v112 offset:2304
	ds_read_b128 v[34:37], v112 offset:2320
	ds_read_b128 v[96:99], v112 offset:18432
	ds_read_b128 v[100:103], v112 offset:18448
	v_add_f32_e32 v140, v136, v137
	v_add_f32_e32 v142, v138, v139
	s_waitcnt lgkmcnt(7)
	v_pk_mul_f32 v[128:129], v[22:23], v[38:39]
	v_add_f32_dpp v140, v140, v140 row_half_mirror row_mask:0xf bank_mask:0xf
	v_add_f32_dpp v142, v142, v142 row_half_mirror row_mask:0xf bank_mask:0xf
	v_pk_mul_f32 v[130:131], v[24:25], v[40:41]
	v_pk_mul_f32 v[132:133], v[26:27], v[42:43]
	v_add_f32_dpp v140, v140, v140 quad_perm:[1,0,3,2] row_mask:0xf bank_mask:0xf
	v_add_f32_dpp v142, v142, v142 quad_perm:[1,0,3,2] row_mask:0xf bank_mask:0xf
	v_pk_mul_f32 v[134:135], v[28:29], v[44:45]
	ds_read_b128 v[38:41], v112 offset:6400
	ds_read_b128 v[42:45], v112 offset:6416
	v_add_f32_dpp v140, v140, v140 quad_perm:[2,3,0,1] row_mask:0xf bank_mask:0xf
	v_add_f32_dpp v142, v142, v142 quad_perm:[2,3,0,1] row_mask:0xf bank_mask:0xf
	s_waitcnt lgkmcnt(7)
	v_pk_fma_f32 v[22:23], v[140:141], v[70:71], v[128:129] op_sel_hi:[0,1,1] neg_lo:[1,0,0] neg_hi:[1,0,0]
	v_pk_fma_f32 v[24:25], v[140:141], v[72:73], v[130:131] op_sel_hi:[0,1,1] neg_lo:[1,0,0] neg_hi:[1,0,0]
	v_pk_fma_f32 v[26:27], v[140:141], v[74:75], v[132:133] op_sel_hi:[0,1,1] neg_lo:[1,0,0] neg_hi:[1,0,0]
	v_pk_fma_f32 v[28:29], v[140:141], v[76:77], v[134:135] op_sel_hi:[0,1,1] neg_lo:[1,0,0] neg_hi:[1,0,0]
	ds_read_b128 v[70:73], v112 offset:10496
	ds_read_b128 v[74:77], v112 offset:10512
	ds_write_b32 v108, v142 offset:25472
	s_waitcnt lgkmcnt(5)
	v_pk_mul_f32 v[136:137], v[22:23], v[30:31]
	v_pk_mul_f32 v[138:139], v[22:23], v[96:97]
	v_pk_fma_f32 v[136:137], v[24:25], v[32:33], v[136:137]
	v_pk_fma_f32 v[138:139], v[24:25], v[98:99], v[138:139]
	v_pk_fma_f32 v[136:137], v[26:27], v[34:35], v[136:137]
	v_pk_fma_f32 v[138:139], v[26:27], v[100:101], v[138:139]
	v_pk_fma_f32 v[136:137], v[28:29], v[36:37], v[136:137]
	v_pk_fma_f32 v[138:139], v[28:29], v[102:103], v[138:139]
	ds_read_b128 v[30:33], v112 offset:2560
	ds_read_b128 v[34:37], v112 offset:2576
	ds_read_b128 v[96:99], v112 offset:18688
	ds_read_b128 v[100:103], v112 offset:18704
	v_add_f32_e32 v140, v136, v137
	v_add_f32_e32 v142, v138, v139
	s_waitcnt lgkmcnt(7)
	v_pk_mul_f32 v[128:129], v[22:23], v[38:39]
	v_add_f32_dpp v140, v140, v140 row_half_mirror row_mask:0xf bank_mask:0xf
	v_add_f32_dpp v142, v142, v142 row_half_mirror row_mask:0xf bank_mask:0xf
	v_pk_mul_f32 v[130:131], v[24:25], v[40:41]
	v_pk_mul_f32 v[132:133], v[26:27], v[42:43]
	v_add_f32_dpp v140, v140, v140 quad_perm:[1,0,3,2] row_mask:0xf bank_mask:0xf
	v_add_f32_dpp v142, v142, v142 quad_perm:[1,0,3,2] row_mask:0xf bank_mask:0xf
	v_pk_mul_f32 v[134:135], v[28:29], v[44:45]
	ds_read_b128 v[38:41], v112 offset:6656
	ds_read_b128 v[42:45], v112 offset:6672
	v_add_f32_dpp v140, v140, v140 quad_perm:[2,3,0,1] row_mask:0xf bank_mask:0xf
	v_add_f32_dpp v142, v142, v142 quad_perm:[2,3,0,1] row_mask:0xf bank_mask:0xf
	s_waitcnt lgkmcnt(7)
	v_pk_fma_f32 v[22:23], v[140:141], v[70:71], v[128:129] op_sel_hi:[0,1,1] neg_lo:[1,0,0] neg_hi:[1,0,0]
	v_pk_fma_f32 v[24:25], v[140:141], v[72:73], v[130:131] op_sel_hi:[0,1,1] neg_lo:[1,0,0] neg_hi:[1,0,0]
	v_pk_fma_f32 v[26:27], v[140:141], v[74:75], v[132:133] op_sel_hi:[0,1,1] neg_lo:[1,0,0] neg_hi:[1,0,0]
	v_pk_fma_f32 v[28:29], v[140:141], v[76:77], v[134:135] op_sel_hi:[0,1,1] neg_lo:[1,0,0] neg_hi:[1,0,0]
	ds_read_b128 v[70:73], v112 offset:10752
	ds_read_b128 v[74:77], v112 offset:10768
	ds_write_b32 v108, v142 offset:25600
	s_waitcnt lgkmcnt(5)
	v_pk_mul_f32 v[136:137], v[22:23], v[30:31]
	v_pk_mul_f32 v[138:139], v[22:23], v[96:97]
	v_pk_fma_f32 v[136:137], v[24:25], v[32:33], v[136:137]
	v_pk_fma_f32 v[138:139], v[24:25], v[98:99], v[138:139]
	v_pk_fma_f32 v[136:137], v[26:27], v[34:35], v[136:137]
	v_pk_fma_f32 v[138:139], v[26:27], v[100:101], v[138:139]
	v_pk_fma_f32 v[136:137], v[28:29], v[36:37], v[136:137]
	v_pk_fma_f32 v[138:139], v[28:29], v[102:103], v[138:139]
	ds_read_b128 v[30:33], v112 offset:2816
	ds_read_b128 v[34:37], v112 offset:2832
	ds_read_b128 v[96:99], v112 offset:18944
	ds_read_b128 v[100:103], v112 offset:18960
	v_add_f32_e32 v140, v136, v137
	v_add_f32_e32 v142, v138, v139
	s_waitcnt lgkmcnt(7)
	v_pk_mul_f32 v[128:129], v[22:23], v[38:39]
	v_add_f32_dpp v140, v140, v140 row_half_mirror row_mask:0xf bank_mask:0xf
	v_add_f32_dpp v142, v142, v142 row_half_mirror row_mask:0xf bank_mask:0xf
	v_pk_mul_f32 v[130:131], v[24:25], v[40:41]
	v_pk_mul_f32 v[132:133], v[26:27], v[42:43]
	v_add_f32_dpp v140, v140, v140 quad_perm:[1,0,3,2] row_mask:0xf bank_mask:0xf
	v_add_f32_dpp v142, v142, v142 quad_perm:[1,0,3,2] row_mask:0xf bank_mask:0xf
	v_pk_mul_f32 v[134:135], v[28:29], v[44:45]
	ds_read_b128 v[38:41], v112 offset:6912
	ds_read_b128 v[42:45], v112 offset:6928
	v_add_f32_dpp v140, v140, v140 quad_perm:[2,3,0,1] row_mask:0xf bank_mask:0xf
	v_add_f32_dpp v142, v142, v142 quad_perm:[2,3,0,1] row_mask:0xf bank_mask:0xf
	s_waitcnt lgkmcnt(7)
	v_pk_fma_f32 v[22:23], v[140:141], v[70:71], v[128:129] op_sel_hi:[0,1,1] neg_lo:[1,0,0] neg_hi:[1,0,0]
	v_pk_fma_f32 v[24:25], v[140:141], v[72:73], v[130:131] op_sel_hi:[0,1,1] neg_lo:[1,0,0] neg_hi:[1,0,0]
	v_pk_fma_f32 v[26:27], v[140:141], v[74:75], v[132:133] op_sel_hi:[0,1,1] neg_lo:[1,0,0] neg_hi:[1,0,0]
	v_pk_fma_f32 v[28:29], v[140:141], v[76:77], v[134:135] op_sel_hi:[0,1,1] neg_lo:[1,0,0] neg_hi:[1,0,0]
	ds_read_b128 v[70:73], v112 offset:11008
	ds_read_b128 v[74:77], v112 offset:11024
	ds_write_b32 v108, v142 offset:25728
	s_waitcnt lgkmcnt(5)
	v_pk_mul_f32 v[136:137], v[22:23], v[30:31]
	v_pk_mul_f32 v[138:139], v[22:23], v[96:97]
	v_pk_fma_f32 v[136:137], v[24:25], v[32:33], v[136:137]
	v_pk_fma_f32 v[138:139], v[24:25], v[98:99], v[138:139]
	v_pk_fma_f32 v[136:137], v[26:27], v[34:35], v[136:137]
	v_pk_fma_f32 v[138:139], v[26:27], v[100:101], v[138:139]
	v_pk_fma_f32 v[136:137], v[28:29], v[36:37], v[136:137]
	v_pk_fma_f32 v[138:139], v[28:29], v[102:103], v[138:139]
	ds_read_b128 v[30:33], v112 offset:3072
	ds_read_b128 v[34:37], v112 offset:3088
	ds_read_b128 v[96:99], v112 offset:19200
	ds_read_b128 v[100:103], v112 offset:19216
	v_add_f32_e32 v140, v136, v137
	v_add_f32_e32 v142, v138, v139
	s_waitcnt lgkmcnt(7)
	v_pk_mul_f32 v[128:129], v[22:23], v[38:39]
	v_add_f32_dpp v140, v140, v140 row_half_mirror row_mask:0xf bank_mask:0xf
	v_add_f32_dpp v142, v142, v142 row_half_mirror row_mask:0xf bank_mask:0xf
	v_pk_mul_f32 v[130:131], v[24:25], v[40:41]
	v_pk_mul_f32 v[132:133], v[26:27], v[42:43]
	v_add_f32_dpp v140, v140, v140 quad_perm:[1,0,3,2] row_mask:0xf bank_mask:0xf
	v_add_f32_dpp v142, v142, v142 quad_perm:[1,0,3,2] row_mask:0xf bank_mask:0xf
	v_pk_mul_f32 v[134:135], v[28:29], v[44:45]
	ds_read_b128 v[38:41], v112 offset:7168
	ds_read_b128 v[42:45], v112 offset:7184
	v_add_f32_dpp v140, v140, v140 quad_perm:[2,3,0,1] row_mask:0xf bank_mask:0xf
	v_add_f32_dpp v142, v142, v142 quad_perm:[2,3,0,1] row_mask:0xf bank_mask:0xf
	s_waitcnt lgkmcnt(7)
	v_pk_fma_f32 v[22:23], v[140:141], v[70:71], v[128:129] op_sel_hi:[0,1,1] neg_lo:[1,0,0] neg_hi:[1,0,0]
	v_pk_fma_f32 v[24:25], v[140:141], v[72:73], v[130:131] op_sel_hi:[0,1,1] neg_lo:[1,0,0] neg_hi:[1,0,0]
	v_pk_fma_f32 v[26:27], v[140:141], v[74:75], v[132:133] op_sel_hi:[0,1,1] neg_lo:[1,0,0] neg_hi:[1,0,0]
	v_pk_fma_f32 v[28:29], v[140:141], v[76:77], v[134:135] op_sel_hi:[0,1,1] neg_lo:[1,0,0] neg_hi:[1,0,0]
	ds_read_b128 v[70:73], v112 offset:11264
	ds_read_b128 v[74:77], v112 offset:11280
	ds_write_b32 v108, v142 offset:25856
	s_waitcnt lgkmcnt(5)
	v_pk_mul_f32 v[136:137], v[22:23], v[30:31]
	v_pk_mul_f32 v[138:139], v[22:23], v[96:97]
	v_pk_fma_f32 v[136:137], v[24:25], v[32:33], v[136:137]
	v_pk_fma_f32 v[138:139], v[24:25], v[98:99], v[138:139]
	v_pk_fma_f32 v[136:137], v[26:27], v[34:35], v[136:137]
	v_pk_fma_f32 v[138:139], v[26:27], v[100:101], v[138:139]
	v_pk_fma_f32 v[136:137], v[28:29], v[36:37], v[136:137]
	v_pk_fma_f32 v[138:139], v[28:29], v[102:103], v[138:139]
	ds_read_b128 v[30:33], v112 offset:3328
	ds_read_b128 v[34:37], v112 offset:3344
	ds_read_b128 v[96:99], v112 offset:19456
	ds_read_b128 v[100:103], v112 offset:19472
	v_add_f32_e32 v140, v136, v137
	v_add_f32_e32 v142, v138, v139
	s_waitcnt lgkmcnt(7)
	v_pk_mul_f32 v[128:129], v[22:23], v[38:39]
	v_add_f32_dpp v140, v140, v140 row_half_mirror row_mask:0xf bank_mask:0xf
	v_add_f32_dpp v142, v142, v142 row_half_mirror row_mask:0xf bank_mask:0xf
	v_pk_mul_f32 v[130:131], v[24:25], v[40:41]
	v_pk_mul_f32 v[132:133], v[26:27], v[42:43]
	v_add_f32_dpp v140, v140, v140 quad_perm:[1,0,3,2] row_mask:0xf bank_mask:0xf
	v_add_f32_dpp v142, v142, v142 quad_perm:[1,0,3,2] row_mask:0xf bank_mask:0xf
	v_pk_mul_f32 v[134:135], v[28:29], v[44:45]
	ds_read_b128 v[38:41], v112 offset:7424
	ds_read_b128 v[42:45], v112 offset:7440
	v_add_f32_dpp v140, v140, v140 quad_perm:[2,3,0,1] row_mask:0xf bank_mask:0xf
	v_add_f32_dpp v142, v142, v142 quad_perm:[2,3,0,1] row_mask:0xf bank_mask:0xf
	s_waitcnt lgkmcnt(7)
	v_pk_fma_f32 v[22:23], v[140:141], v[70:71], v[128:129] op_sel_hi:[0,1,1] neg_lo:[1,0,0] neg_hi:[1,0,0]
	v_pk_fma_f32 v[24:25], v[140:141], v[72:73], v[130:131] op_sel_hi:[0,1,1] neg_lo:[1,0,0] neg_hi:[1,0,0]
	v_pk_fma_f32 v[26:27], v[140:141], v[74:75], v[132:133] op_sel_hi:[0,1,1] neg_lo:[1,0,0] neg_hi:[1,0,0]
	v_pk_fma_f32 v[28:29], v[140:141], v[76:77], v[134:135] op_sel_hi:[0,1,1] neg_lo:[1,0,0] neg_hi:[1,0,0]
	ds_read_b128 v[70:73], v112 offset:11520
	ds_read_b128 v[74:77], v112 offset:11536
	ds_write_b32 v108, v142 offset:25984
	s_waitcnt lgkmcnt(5)
	v_pk_mul_f32 v[136:137], v[22:23], v[30:31]
	v_pk_mul_f32 v[138:139], v[22:23], v[96:97]
	v_pk_fma_f32 v[136:137], v[24:25], v[32:33], v[136:137]
	v_pk_fma_f32 v[138:139], v[24:25], v[98:99], v[138:139]
	v_pk_fma_f32 v[136:137], v[26:27], v[34:35], v[136:137]
	v_pk_fma_f32 v[138:139], v[26:27], v[100:101], v[138:139]
	v_pk_fma_f32 v[136:137], v[28:29], v[36:37], v[136:137]
	v_pk_fma_f32 v[138:139], v[28:29], v[102:103], v[138:139]
	ds_read_b128 v[30:33], v112 offset:3584
	ds_read_b128 v[34:37], v112 offset:3600
	ds_read_b128 v[96:99], v112 offset:19712
	ds_read_b128 v[100:103], v112 offset:19728
	v_add_f32_e32 v140, v136, v137
	v_add_f32_e32 v142, v138, v139
	s_waitcnt lgkmcnt(7)
	v_pk_mul_f32 v[128:129], v[22:23], v[38:39]
	v_add_f32_dpp v140, v140, v140 row_half_mirror row_mask:0xf bank_mask:0xf
	v_add_f32_dpp v142, v142, v142 row_half_mirror row_mask:0xf bank_mask:0xf
	v_pk_mul_f32 v[130:131], v[24:25], v[40:41]
	v_pk_mul_f32 v[132:133], v[26:27], v[42:43]
	v_add_f32_dpp v140, v140, v140 quad_perm:[1,0,3,2] row_mask:0xf bank_mask:0xf
	v_add_f32_dpp v142, v142, v142 quad_perm:[1,0,3,2] row_mask:0xf bank_mask:0xf
	v_pk_mul_f32 v[134:135], v[28:29], v[44:45]
	ds_read_b128 v[38:41], v112 offset:7680
	ds_read_b128 v[42:45], v112 offset:7696
	v_add_f32_dpp v140, v140, v140 quad_perm:[2,3,0,1] row_mask:0xf bank_mask:0xf
	v_add_f32_dpp v142, v142, v142 quad_perm:[2,3,0,1] row_mask:0xf bank_mask:0xf
	s_waitcnt lgkmcnt(7)
	v_pk_fma_f32 v[22:23], v[140:141], v[70:71], v[128:129] op_sel_hi:[0,1,1] neg_lo:[1,0,0] neg_hi:[1,0,0]
	v_pk_fma_f32 v[24:25], v[140:141], v[72:73], v[130:131] op_sel_hi:[0,1,1] neg_lo:[1,0,0] neg_hi:[1,0,0]
	v_pk_fma_f32 v[26:27], v[140:141], v[74:75], v[132:133] op_sel_hi:[0,1,1] neg_lo:[1,0,0] neg_hi:[1,0,0]
	v_pk_fma_f32 v[28:29], v[140:141], v[76:77], v[134:135] op_sel_hi:[0,1,1] neg_lo:[1,0,0] neg_hi:[1,0,0]
	ds_read_b128 v[70:73], v112 offset:11776
	ds_read_b128 v[74:77], v112 offset:11792
	ds_write_b32 v108, v142 offset:26112
	s_waitcnt lgkmcnt(5)
	v_pk_mul_f32 v[136:137], v[22:23], v[30:31]
	v_pk_mul_f32 v[138:139], v[22:23], v[96:97]
	v_pk_fma_f32 v[136:137], v[24:25], v[32:33], v[136:137]
	v_pk_fma_f32 v[138:139], v[24:25], v[98:99], v[138:139]
	v_pk_fma_f32 v[136:137], v[26:27], v[34:35], v[136:137]
	v_pk_fma_f32 v[138:139], v[26:27], v[100:101], v[138:139]
	v_pk_fma_f32 v[136:137], v[28:29], v[36:37], v[136:137]
	v_pk_fma_f32 v[138:139], v[28:29], v[102:103], v[138:139]
	ds_read_b128 v[30:33], v112 offset:3840
	ds_read_b128 v[34:37], v112 offset:3856
	ds_read_b128 v[96:99], v112 offset:19968
	ds_read_b128 v[100:103], v112 offset:19984
	v_add_f32_e32 v140, v136, v137
	v_add_f32_e32 v142, v138, v139
	s_waitcnt lgkmcnt(7)
	v_pk_mul_f32 v[128:129], v[22:23], v[38:39]
	v_add_f32_dpp v140, v140, v140 row_half_mirror row_mask:0xf bank_mask:0xf
	v_add_f32_dpp v142, v142, v142 row_half_mirror row_mask:0xf bank_mask:0xf
	v_pk_mul_f32 v[130:131], v[24:25], v[40:41]
	v_pk_mul_f32 v[132:133], v[26:27], v[42:43]
	v_add_f32_dpp v140, v140, v140 quad_perm:[1,0,3,2] row_mask:0xf bank_mask:0xf
	v_add_f32_dpp v142, v142, v142 quad_perm:[1,0,3,2] row_mask:0xf bank_mask:0xf
	v_pk_mul_f32 v[134:135], v[28:29], v[44:45]
	ds_read_b128 v[38:41], v112 offset:7936
	ds_read_b128 v[42:45], v112 offset:7952
	v_add_f32_dpp v140, v140, v140 quad_perm:[2,3,0,1] row_mask:0xf bank_mask:0xf
	v_add_f32_dpp v142, v142, v142 quad_perm:[2,3,0,1] row_mask:0xf bank_mask:0xf
	s_waitcnt lgkmcnt(7)
	v_pk_fma_f32 v[22:23], v[140:141], v[70:71], v[128:129] op_sel_hi:[0,1,1] neg_lo:[1,0,0] neg_hi:[1,0,0]
	v_pk_fma_f32 v[24:25], v[140:141], v[72:73], v[130:131] op_sel_hi:[0,1,1] neg_lo:[1,0,0] neg_hi:[1,0,0]
	v_pk_fma_f32 v[26:27], v[140:141], v[74:75], v[132:133] op_sel_hi:[0,1,1] neg_lo:[1,0,0] neg_hi:[1,0,0]
	v_pk_fma_f32 v[28:29], v[140:141], v[76:77], v[134:135] op_sel_hi:[0,1,1] neg_lo:[1,0,0] neg_hi:[1,0,0]
	ds_read_b128 v[70:73], v112 offset:12032
	ds_read_b128 v[74:77], v112 offset:12048
	ds_write_b32 v108, v142 offset:26240
	s_waitcnt lgkmcnt(5)
	v_pk_mul_f32 v[136:137], v[22:23], v[30:31]
	v_pk_mul_f32 v[138:139], v[22:23], v[96:97]
	v_pk_fma_f32 v[136:137], v[24:25], v[32:33], v[136:137]
	v_pk_fma_f32 v[138:139], v[24:25], v[98:99], v[138:139]
	v_pk_fma_f32 v[136:137], v[26:27], v[34:35], v[136:137]
	v_pk_fma_f32 v[138:139], v[26:27], v[100:101], v[138:139]
	v_pk_fma_f32 v[136:137], v[28:29], v[36:37], v[136:137]
	v_pk_fma_f32 v[138:139], v[28:29], v[102:103], v[138:139]
	ds_read_b128 v[96:99], v112 offset:20224
	ds_read_b128 v[100:103], v112 offset:20240
	v_add_f32_e32 v140, v136, v137
	v_add_f32_e32 v142, v138, v139
	s_waitcnt lgkmcnt(5)
	v_pk_mul_f32 v[128:129], v[22:23], v[38:39]
	v_add_f32_dpp v140, v140, v140 row_half_mirror row_mask:0xf bank_mask:0xf
	v_add_f32_dpp v142, v142, v142 row_half_mirror row_mask:0xf bank_mask:0xf
	v_pk_mul_f32 v[130:131], v[24:25], v[40:41]
	v_pk_mul_f32 v[132:133], v[26:27], v[42:43]
	v_add_f32_dpp v140, v140, v140 quad_perm:[1,0,3,2] row_mask:0xf bank_mask:0xf
	v_add_f32_dpp v142, v142, v142 quad_perm:[1,0,3,2] row_mask:0xf bank_mask:0xf
	v_pk_mul_f32 v[134:135], v[28:29], v[44:45]
	v_add_f32_dpp v140, v140, v140 quad_perm:[2,3,0,1] row_mask:0xf bank_mask:0xf
	v_add_f32_dpp v142, v142, v142 quad_perm:[2,3,0,1] row_mask:0xf bank_mask:0xf
	s_waitcnt lgkmcnt(3)
	v_pk_fma_f32 v[22:23], v[140:141], v[70:71], v[128:129] op_sel_hi:[0,1,1] neg_lo:[1,0,0] neg_hi:[1,0,0]
	v_pk_fma_f32 v[24:25], v[140:141], v[72:73], v[130:131] op_sel_hi:[0,1,1] neg_lo:[1,0,0] neg_hi:[1,0,0]
	v_pk_fma_f32 v[26:27], v[140:141], v[74:75], v[132:133] op_sel_hi:[0,1,1] neg_lo:[1,0,0] neg_hi:[1,0,0]
	v_pk_fma_f32 v[28:29], v[140:141], v[76:77], v[134:135] op_sel_hi:[0,1,1] neg_lo:[1,0,0] neg_hi:[1,0,0]
	ds_write_b32 v108, v142 offset:26368
	s_waitcnt lgkmcnt(1)
	v_pk_mul_f32 v[138:139], v[22:23], v[96:97]
	v_pk_fma_f32 v[138:139], v[24:25], v[98:99], v[138:139]
	v_pk_fma_f32 v[138:139], v[26:27], v[100:101], v[138:139]
	v_pk_fma_f32 v[138:139], v[28:29], v[102:103], v[138:139]
	v_add_f32_e32 v142, v138, v139
	s_nop 1
	v_add_f32_dpp v142, v142, v142 row_half_mirror row_mask:0xf bank_mask:0xf
	s_nop 1
	v_add_f32_dpp v142, v142, v142 quad_perm:[1,0,3,2] row_mask:0xf bank_mask:0xf
	s_nop 1
	v_add_f32_dpp v142, v142, v142 quad_perm:[2,3,0,1] row_mask:0xf bank_mask:0xf
	ds_write_b32 v108, v142 offset:26496
.Lrw0_u2e1:
	s_add_u32 s28, s28, 16
	s_cmp_lt_u32 s28, s25
	s_cbranch_scc1 .Lrw0_loop
	s_waitcnt lgkmcnt(0)
	s_barrier
	ds_read_b32 v89, v5 offset:24576
	ds_read_b32 v90, v5 offset:24640
	s_sub_u32 s98, s28, 16
	v_add_u32_e32 v87, s98, v127
	v_mad_i64_i32 v[104:105], vcc, v87, v20, v[18:19]
	s_waitcnt lgkmcnt(0)
	v_cvt_pk_bf16_f32 v89, v89, v90
	global_store_short v[104:105], v89, off
	global_store_short_d16_hi v[104:105], v89, off offset:32
	v_lshrrev_b32_e32 v87, 2, v108
	v_lshl_add_u32 v87, s17, 4, v87
	v_lshl_add_u32 v89, v87, 8, v112
	s_cmp_eq_u32 s18, 3
	s_cbranch_scc0 .Lrw0_f_not3
	s_load_dwordx2 s[36:37], s[14:15], 0x120
	s_waitcnt lgkmcnt(0)
	s_lshl_b32 s98, s42, 14
	s_add_u32 s36, s36, s98
	s_addc_u32 s37, s37, 0
	s_add_u32 s36, s36, 0x5e00000
	s_addc_u32 s37, s37, 0
	global_store_dwordx4 v89, v[22:25], s[36:37]
	global_store_dwordx4 v89, v[26:29], s[36:37] offset:16
	s_branch .Lrw0_f_done
